# MFMA issue order inside each K-half regrouped so 4 consecutive MFMAs share src0 (w_in, w_out, down, up loops; GLU unchanged)
# baseline (speedup 1.0000x reference)
; #define PG8_STAGE(bufoff, gbase, voff) do { _Pragma("unroll") for (int _i = 0; _i < 2; ++_i) \
;         __builtin_amdgcn_global_load_lds((const unsigned*)((const char*)(gbase) + (voff)[_i]), (PG8_LAS unsigned*)(lds + (bufoff) + ldsw + _i * 8192), 16, 0, 0); } while (0)
; #define PG8_LDA(dst, b, h) do { _Pragma("unroll") for (int m = 0; m < 4; ++m) _Pragma("unroll") for (int k = 0; k < 2; ++k) dst[m][k] = *(const PG8_LAS bf16x8*)(lds + PG8_SA(b, h) + aoff + m * 2048 + k * 1024); } while (0)
; #define PG8_LDB(dst, b, h) do { _Pragma("unroll") for (int n = 0; n < 2; ++n) _Pragma("unroll") for (int k = 0; k < 2; ++k) dst[n][k] = *(const PG8_LAS bf16x8*)(lds + PG8_SB(b, h) + boff + n * 2048 + k * 1024); } while (0)
; #define PG8_MMA(ai, bj, At, Bt) do { __builtin_amdgcn_s_setprio(1); _Pragma("unroll") for (int m = 0; m < 4; ++m) _Pragma("unroll") for (int n = 0; n < 2; ++n) _Pragma("unroll") for (int k = 0; k < 2; ++k) \
;         acc[ai][bj][m][n] = __builtin_amdgcn_mfma_f32_16x16x32_bf16(Bt[n][k], At[m][k], acc[ai][bj][m][n], 0, 0, 0); __builtin_amdgcn_s_setprio(0); } while (0)
; #define PG8_BAR __builtin_amdgcn_s_barrier()
; template <class Epi, class Sched, bool ALIGN_EPI = false, bool SP2 = false>
; __device__ __forceinline__ void gemm_phase(PG8_LAS unsigned char* lds, const Gemm g, const Sched& S, const Epi& E) {
;     ...
;         const bool has_next = S.next(ui + 1, nxt);
;         const char* nA = has_next ? (const char*)g.A + (size_t)nxt.pm * tstep : cA; const char* nB = has_next ? (const char*)g.Bt + (size_t)nxt.pn * tstep : cB;
;         for (int t = 0; t < nt; t += 2) {
;             const bool last = (t == nt - 2);
;             const char* a1 = cA + (size_t)(t + 1) * kstep;
;             const char* a2 = last ? nA : cA + (size_t)(t + 2) * kstep; const char* b2 = last ? nB : cB + (size_t)(t + 2) * kstep;
;             const char* a3 = a2 + kstep; const char* b3 = b2 + kstep;
;             if (last && has_next) S.a_ready(nxt);
;             if constexpr (SP2) {
;             PG8_LDB(B0, 0, 0); PG8_LDB(B1, 0, 1); PG8_SCHED; PG8_LDA(At, 0, 0); PG8_STAGE(PG8_SA(1, 1), a1 + hstep, voffA);
;             PG8_WAIT_V(8); PG8_WAIT_L(0); PG8_BAR; PG8_MMA(0, 0, At, B0); PG8_MMA(0, 1, At, B1); PG8_BAR; PG8_SCHED;
;             PG8_LDA(At, 0, 1); PG8_STAGE(PG8_SB(0, 0), b2, voffB); PG8_STAGE(PG8_SB(0, 1), b2 + hstepB, voffB); PG8_STAGE(PG8_SA(0, 0), a2, voffA);
.LBB0_169:
	s_add_u32 s93, s46, 0x100
	s_addc_u32 s94, s47, 0
	s_ashr_i32 s69, s68, 31
	s_lshl_b64 s[4:5], s[68:69], 20
	s_add_u32 s76, s52, s4
	s_addc_u32 s77, s53, s5
	s_and_b64 s[4:5], s[38:39], exec
	s_cselect_b32 s4, s77, s71
	s_cselect_b32 s5, s76, s70
	s_ashr_i32 s63, s62, 31
	s_lshl_b64 s[6:7], s[62:63], 20
	v_readlane_b32 s8, v249, 19
	v_readlane_b32 s9, v249, 20
	s_add_u32 s72, s8, s6
	s_addc_u32 s73, s9, s7
	s_and_b64 s[6:7], s[38:39], exec
	s_cselect_b32 s6, s73, s47
	s_cselect_b32 s7, s72, s46
	s_add_u32 s8, s70, 0x80080
	s_addc_u32 s9, s71, 0
	v_lshl_add_u64 v[144:145], s[8:9], 0, v[140:141]
	v_lshl_add_u64 v[146:147], s[8:9], 0, v[142:143]
	s_mov_b32 s8, -2
	s_mov_b64 s[46:47], 0
	v_add_u32_e32 v186, 0x10000, v139
	v_add_u32_e32 v187, 0x14000, v139
	v_add_u32_e32 v198, 0x18000, v139
	v_add_u32_e32 v199, 0x1c000, v139
	s_add_u32 s9, s70, s46
	s_addc_u32 s10, s71, s47
	s_add_u32 s9, s9, 0x100
	s_addc_u32 s10, s10, 0
	s_add_u32 s100, s9, 0x7ff80
	s_addc_u32 s101, s10, 0
	s_add_u32 s11, s93, s46
	s_addc_u32 s12, s94, s47
	s_add_i32 s13, 0, 0x10000
	s_cmpk_eq_i32 s46, 0xf00
	s_cselect_b32 s85, s4, s10
	s_cselect_b32 s84, s5, s9
	s_cselect_b32 s81, s6, s12
	s_cselect_b32 s80, s7, s11
	s_add_i32 s9, 0, 0x14000
	ds_read_b128 v[148:151], v186
	ds_read_b128 v[152:155], v186 offset:1024
	ds_read_b128 v[156:159], v186 offset:2048
	ds_read_b128 v[160:163], v186 offset:3072
	ds_read_b128 v[166:169], v187
	ds_read_b128 v[170:173], v187 offset:1024
	ds_read_b128 v[174:177], v187 offset:2048
	ds_read_b128 v[178:181], v187 offset:3072
	s_add_i32 m0, s1, 0xc000
	ds_read_b128 v[182:185], v165
	ds_read_b128 v[206:209], v165 offset:1024
	ds_read_b128 v[210:213], v165 offset:2048
	ds_read_b128 v[214:217], v165 offset:3072
	ds_read_b128 v[218:221], v165 offset:4096
	ds_read_b128 v[236:239], v165 offset:5120
	ds_read_b128 v[240:243], v165 offset:6144
	ds_read_b128 v[244:247], v165 offset:7168
	global_load_lds_dwordx4 v140, s[100:101]
	s_add_i32 m0, s1, 0xe000
	s_nop 0
	global_load_lds_dwordx4 v142, s[100:101]
	s_waitcnt vmcnt(8)
	s_waitcnt lgkmcnt(0)
	s_barrier
	v_mfma_f32_16x16x32_bf16 v[126:129], v[148:151], v[182:185], 0
	v_mfma_f32_16x16x32_bf16 v[118:121], v[148:151], v[210:213], 0
	v_mfma_f32_16x16x32_bf16 v[110:113], v[148:151], v[218:221], 0
	v_mfma_f32_16x16x32_bf16 v[102:105], v[148:151], v[240:243], 0
	v_mfma_f32_16x16x32_bf16 v[122:125], v[156:159], v[182:185], 0
	v_mfma_f32_16x16x32_bf16 v[114:117], v[156:159], v[210:213], 0
	v_mfma_f32_16x16x32_bf16 v[106:109], v[156:159], v[218:221], 0
	v_mfma_f32_16x16x32_bf16 v[98:101], v[156:159], v[240:243], 0
	v_mfma_f32_16x16x32_bf16 v[126:129], v[152:155], v[206:209], v[126:129]
	v_mfma_f32_16x16x32_bf16 v[118:121], v[152:155], v[214:217], v[118:121]
	v_mfma_f32_16x16x32_bf16 v[110:113], v[152:155], v[236:239], v[110:113]
	v_mfma_f32_16x16x32_bf16 v[102:105], v[152:155], v[244:247], v[102:105]
	v_mfma_f32_16x16x32_bf16 v[122:125], v[160:163], v[206:209], v[122:125]
	v_mfma_f32_16x16x32_bf16 v[114:117], v[160:163], v[214:217], v[114:117]
	v_mfma_f32_16x16x32_bf16 v[106:109], v[160:163], v[236:239], v[106:109]
	v_mfma_f32_16x16x32_bf16 v[98:101], v[160:163], v[244:247], v[98:101]
	v_mfma_f32_16x16x32_bf16 v[94:97], v[166:169], v[182:185], 0
	v_mfma_f32_16x16x32_bf16 v[86:89], v[166:169], v[210:213], 0
	v_mfma_f32_16x16x32_bf16 v[78:81], v[166:169], v[218:221], 0
	v_mfma_f32_16x16x32_bf16 v[70:73], v[166:169], v[240:243], 0
	v_mfma_f32_16x16x32_bf16 v[90:93], v[174:177], v[182:185], 0
	v_mfma_f32_16x16x32_bf16 v[82:85], v[174:177], v[210:213], 0
	v_mfma_f32_16x16x32_bf16 v[74:77], v[174:177], v[218:221], 0
	v_mfma_f32_16x16x32_bf16 v[66:69], v[174:177], v[240:243], 0
	v_mfma_f32_16x16x32_bf16 v[94:97], v[170:173], v[206:209], v[94:97]
	v_mfma_f32_16x16x32_bf16 v[86:89], v[170:173], v[214:217], v[86:89]
	v_mfma_f32_16x16x32_bf16 v[78:81], v[170:173], v[236:239], v[78:81]
	v_mfma_f32_16x16x32_bf16 v[70:73], v[170:173], v[244:247], v[70:73]
	v_mfma_f32_16x16x32_bf16 v[90:93], v[178:181], v[206:209], v[90:93]
	v_mfma_f32_16x16x32_bf16 v[82:85], v[178:181], v[214:217], v[82:85]
	v_mfma_f32_16x16x32_bf16 v[74:77], v[178:181], v[236:239], v[74:77]
	v_mfma_f32_16x16x32_bf16 v[66:69], v[178:181], v[244:247], v[66:69]
	s_barrier
	s_add_i32 s10, s13, s0
	s_mov_b32 m0, s10
	ds_read_b128 v[182:185], v165 offset:16384
	ds_read_b128 v[206:209], v165 offset:17408
	ds_read_b128 v[210:213], v165 offset:18432
	ds_read_b128 v[214:217], v165 offset:19456
	ds_read_b128 v[218:221], v165 offset:20480
	ds_read_b128 v[236:239], v165 offset:21504
	ds_read_b128 v[240:243], v165 offset:22528
	ds_read_b128 v[244:247], v165 offset:23552
	global_load_lds_dwordx4 v132, s[80:81]
	s_add_i32 m0, s10, 0x2000
	s_add_u32 s10, s80, 0x20000
	s_addc_u32 s11, s81, 0
	s_add_i32 s9, s9, s0
	global_load_lds_dwordx4 v136, s[80:81]
	s_mov_b32 m0, s9
	s_nop 0
	global_load_lds_dwordx4 v132, s[10:11]
	s_add_i32 m0, s9, 0x2000
	s_nop 0
	global_load_lds_dwordx4 v136, s[10:11]
	s_mov_b32 m0, s1
	s_nop 0
	global_load_lds_dwordx4 v130, s[84:85]
	s_mov_b32 m0, s25
	s_nop 0
	global_load_lds_dwordx4 v134, s[84:85]
	s_waitcnt vmcnt(8)
	s_waitcnt lgkmcnt(0)
	s_barrier
; #define PG8_STAGE(bufoff, gbase, voff) do { _Pragma("unroll") for (int _i = 0; _i < 2; ++_i) \
;         __builtin_amdgcn_global_load_lds((const unsigned*)((const char*)(gbase) + (voff)[_i]), (PG8_LAS unsigned*)(lds + (bufoff) + ldsw + _i * 8192), 16, 0, 0); } while (0)
; #define PG8_LDA(dst, b, h) do { _Pragma("unroll") for (int m = 0; m < 4; ++m) _Pragma("unroll") for (int k = 0; k < 2; ++k) dst[m][k] = *(const PG8_LAS bf16x8*)(lds + PG8_SA(b, h) + aoff + m * 2048 + k * 1024); } while (0)
; #define PG8_LDB(dst, b, h) do { _Pragma("unroll") for (int n = 0; n < 2; ++n) _Pragma("unroll") for (int k = 0; k < 2; ++k) dst[n][k] = *(const PG8_LAS bf16x8*)(lds + PG8_SB(b, h) + boff + n * 2048 + k * 1024); } while (0)
; #define PG8_MMA(ai, bj, At, Bt) do { __builtin_amdgcn_s_setprio(1); _Pragma("unroll") for (int m = 0; m < 4; ++m) _Pragma("unroll") for (int n = 0; n < 2; ++n) _Pragma("unroll") for (int k = 0; k < 2; ++k) \
;         acc[ai][bj][m][n] = __builtin_amdgcn_mfma_f32_16x16x32_bf16(Bt[n][k], At[m][k], acc[ai][bj][m][n], 0, 0, 0); __builtin_amdgcn_s_setprio(0); } while (0)
; #define PG8_WAIT_V(n) asm volatile("s_waitcnt vmcnt(" #n ")" ::: "memory")
; #define PG8_WAIT_L(n) asm volatile("s_waitcnt lgkmcnt(" #n ")" ::: "memory")
; #define PG8_BAR __builtin_amdgcn_s_barrier()
; #define PG8_SCHED __builtin_amdgcn_sched_barrier(0)
; template <class Epi, class Sched, bool ALIGN_EPI = false, bool SP2 = false>
; __device__ __forceinline__ void gemm_phase(PG8_LAS unsigned char* lds, const Gemm g, const Sched& S, const Epi& E) {
;     ...
;             PG8_WAIT_V(8); PG8_WAIT_L(0); PG8_BAR; PG8_MMA(1, 0, At, B0); PG8_MMA(1, 1, At, B1); PG8_BAR; PG8_SCHED;
;             PG8_LDB(B0, 1, 0); PG8_LDB(B1, 1, 1); PG8_SCHED; PG8_LDA(At, 1, 0); PG8_STAGE(PG8_SA(0, 1), a2 + hstep, voffA);
;             PG8_WAIT_V(8); PG8_WAIT_L(0); PG8_BAR; PG8_MMA(0, 0, At, B0); PG8_MMA(0, 1, At, B1); PG8_BAR; PG8_SCHED;
	v_mfma_f32_16x16x32_bf16 v[62:65], v[148:151], v[182:185], 0
	v_mfma_f32_16x16x32_bf16 v[54:57], v[148:151], v[210:213], 0
	v_mfma_f32_16x16x32_bf16 v[46:49], v[148:151], v[218:221], 0
	v_mfma_f32_16x16x32_bf16 v[38:41], v[148:151], v[240:243], 0
	v_mfma_f32_16x16x32_bf16 v[58:61], v[156:159], v[182:185], 0
	v_mfma_f32_16x16x32_bf16 v[50:53], v[156:159], v[210:213], 0
	v_mfma_f32_16x16x32_bf16 v[42:45], v[156:159], v[218:221], 0
	v_mfma_f32_16x16x32_bf16 v[34:37], v[156:159], v[240:243], 0
	v_mfma_f32_16x16x32_bf16 v[62:65], v[152:155], v[206:209], v[62:65]
	v_mfma_f32_16x16x32_bf16 v[54:57], v[152:155], v[214:217], v[54:57]
	v_mfma_f32_16x16x32_bf16 v[46:49], v[152:155], v[236:239], v[46:49]
	v_mfma_f32_16x16x32_bf16 v[38:41], v[152:155], v[244:247], v[38:41]
	v_mfma_f32_16x16x32_bf16 v[58:61], v[160:163], v[206:209], v[58:61]
	v_mfma_f32_16x16x32_bf16 v[50:53], v[160:163], v[214:217], v[50:53]
	v_mfma_f32_16x16x32_bf16 v[42:45], v[160:163], v[236:239], v[42:45]
	v_mfma_f32_16x16x32_bf16 v[34:37], v[160:163], v[244:247], v[34:37]
	v_mfma_f32_16x16x32_bf16 v[30:33], v[166:169], v[182:185], 0
	v_mfma_f32_16x16x32_bf16 v[22:25], v[166:169], v[210:213], 0
	v_mfma_f32_16x16x32_bf16 v[14:17], v[166:169], v[218:221], 0
	v_mfma_f32_16x16x32_bf16 v[6:9], v[166:169], v[240:243], 0
	v_mfma_f32_16x16x32_bf16 v[26:29], v[174:177], v[182:185], 0
	v_mfma_f32_16x16x32_bf16 v[18:21], v[174:177], v[210:213], 0
	v_mfma_f32_16x16x32_bf16 v[10:13], v[174:177], v[218:221], 0
	v_mfma_f32_16x16x32_bf16 v[2:5], v[174:177], v[240:243], 0
	v_mfma_f32_16x16x32_bf16 v[30:33], v[170:173], v[206:209], v[30:33]
	v_mfma_f32_16x16x32_bf16 v[22:25], v[170:173], v[214:217], v[22:25]
	v_mfma_f32_16x16x32_bf16 v[14:17], v[170:173], v[236:239], v[14:17]
	v_mfma_f32_16x16x32_bf16 v[6:9], v[170:173], v[244:247], v[6:9]
	v_mfma_f32_16x16x32_bf16 v[26:29], v[178:181], v[206:209], v[26:29]
	v_mfma_f32_16x16x32_bf16 v[18:21], v[178:181], v[214:217], v[18:21]
	v_mfma_f32_16x16x32_bf16 v[10:13], v[178:181], v[236:239], v[10:13]
	v_mfma_f32_16x16x32_bf16 v[2:5], v[178:181], v[244:247], v[2:5]
	s_barrier
	s_add_i32 s9, 0, 0x18000
	s_add_i32 s12, 0, 0x1c000
	ds_read_b128 v[148:151], v198
	ds_read_b128 v[152:155], v198 offset:1024
	ds_read_b128 v[156:159], v198 offset:2048
	ds_read_b128 v[160:163], v198 offset:3072
	ds_read_b128 v[166:169], v199
	ds_read_b128 v[170:173], v199 offset:1024
	ds_read_b128 v[174:177], v199 offset:2048
	ds_read_b128 v[178:181], v199 offset:3072
	s_add_u32 s10, s84, 0x80000
	s_addc_u32 s11, s85, 0
	s_mov_b32 m0, s42
	ds_read_b128 v[182:185], v165 offset:32768
	ds_read_b128 v[206:209], v165 offset:33792
	ds_read_b128 v[210:213], v165 offset:34816
	ds_read_b128 v[214:217], v165 offset:35840
	ds_read_b128 v[218:221], v165 offset:36864
	ds_read_b128 v[236:239], v165 offset:37888
	ds_read_b128 v[240:243], v165 offset:38912
	ds_read_b128 v[244:247], v165 offset:39936
	global_load_lds_dwordx4 v130, s[10:11]
	s_mov_b32 m0, s51
	s_nop 0
	global_load_lds_dwordx4 v134, s[10:11]
	s_waitcnt vmcnt(8)
	s_waitcnt lgkmcnt(0)
	s_barrier
	v_mfma_f32_16x16x32_bf16 v[126:129], v[148:151], v[182:185], v[126:129]
	v_mfma_f32_16x16x32_bf16 v[118:121], v[148:151], v[210:213], v[118:121]
	v_mfma_f32_16x16x32_bf16 v[110:113], v[148:151], v[218:221], v[110:113]
	v_mfma_f32_16x16x32_bf16 v[102:105], v[148:151], v[240:243], v[102:105]
	v_mfma_f32_16x16x32_bf16 v[122:125], v[156:159], v[182:185], v[122:125]
	v_mfma_f32_16x16x32_bf16 v[114:117], v[156:159], v[210:213], v[114:117]
	v_mfma_f32_16x16x32_bf16 v[106:109], v[156:159], v[218:221], v[106:109]
	v_mfma_f32_16x16x32_bf16 v[98:101], v[156:159], v[240:243], v[98:101]
	v_mfma_f32_16x16x32_bf16 v[126:129], v[152:155], v[206:209], v[126:129]
	v_mfma_f32_16x16x32_bf16 v[118:121], v[152:155], v[214:217], v[118:121]
	v_mfma_f32_16x16x32_bf16 v[110:113], v[152:155], v[236:239], v[110:113]
	v_mfma_f32_16x16x32_bf16 v[102:105], v[152:155], v[244:247], v[102:105]
	v_mfma_f32_16x16x32_bf16 v[122:125], v[160:163], v[206:209], v[122:125]
	v_mfma_f32_16x16x32_bf16 v[114:117], v[160:163], v[214:217], v[114:117]
	v_mfma_f32_16x16x32_bf16 v[106:109], v[160:163], v[236:239], v[106:109]
	v_mfma_f32_16x16x32_bf16 v[98:101], v[160:163], v[244:247], v[98:101]
	v_mfma_f32_16x16x32_bf16 v[94:97], v[166:169], v[182:185], v[94:97]
	v_mfma_f32_16x16x32_bf16 v[86:89], v[166:169], v[210:213], v[86:89]
	v_mfma_f32_16x16x32_bf16 v[78:81], v[166:169], v[218:221], v[78:81]
	v_mfma_f32_16x16x32_bf16 v[70:73], v[166:169], v[240:243], v[70:73]
	v_mfma_f32_16x16x32_bf16 v[90:93], v[174:177], v[182:185], v[90:93]
	v_mfma_f32_16x16x32_bf16 v[82:85], v[174:177], v[210:213], v[82:85]
	v_mfma_f32_16x16x32_bf16 v[74:77], v[174:177], v[218:221], v[74:77]
	v_mfma_f32_16x16x32_bf16 v[66:69], v[174:177], v[240:243], v[66:69]
	v_mfma_f32_16x16x32_bf16 v[94:97], v[170:173], v[206:209], v[94:97]
	v_mfma_f32_16x16x32_bf16 v[86:89], v[170:173], v[214:217], v[86:89]
	v_mfma_f32_16x16x32_bf16 v[78:81], v[170:173], v[236:239], v[78:81]
	v_mfma_f32_16x16x32_bf16 v[70:73], v[170:173], v[244:247], v[70:73]
	v_mfma_f32_16x16x32_bf16 v[90:93], v[178:181], v[206:209], v[90:93]
	v_mfma_f32_16x16x32_bf16 v[82:85], v[178:181], v[214:217], v[82:85]
	v_mfma_f32_16x16x32_bf16 v[74:77], v[178:181], v[236:239], v[74:77]
	v_mfma_f32_16x16x32_bf16 v[66:69], v[178:181], v[244:247], v[66:69]
	s_barrier
; #define PG8_STAGE(bufoff, gbase, voff) do { _Pragma("unroll") for (int _i = 0; _i < 2; ++_i) \
;         __builtin_amdgcn_global_load_lds((const unsigned*)((const char*)(gbase) + (voff)[_i]), (PG8_LAS unsigned*)(lds + (bufoff) + ldsw + _i * 8192), 16, 0, 0); } while (0)
; #define PG8_LDA(dst, b, h) do { _Pragma("unroll") for (int m = 0; m < 4; ++m) _Pragma("unroll") for (int k = 0; k < 2; ++k) dst[m][k] = *(const PG8_LAS bf16x8*)(lds + PG8_SA(b, h) + aoff + m * 2048 + k * 1024); } while (0)
; #define PG8_LDB(dst, b, h) do { _Pragma("unroll") for (int n = 0; n < 2; ++n) _Pragma("unroll") for (int k = 0; k < 2; ++k) dst[n][k] = *(const PG8_LAS bf16x8*)(lds + PG8_SB(b, h) + boff + n * 2048 + k * 1024); } while (0)
; #define PG8_MMA(ai, bj, At, Bt) do { __builtin_amdgcn_s_setprio(1); _Pragma("unroll") for (int m = 0; m < 4; ++m) _Pragma("unroll") for (int n = 0; n < 2; ++n) _Pragma("unroll") for (int k = 0; k < 2; ++k) \
;         acc[ai][bj][m][n] = __builtin_amdgcn_mfma_f32_16x16x32_bf16(Bt[n][k], At[m][k], acc[ai][bj][m][n], 0, 0, 0); __builtin_amdgcn_s_setprio(0); } while (0)
; #define PG8_WAIT_V(n) asm volatile("s_waitcnt vmcnt(" #n ")" ::: "memory")
; template <class Epi, class Sched, bool ALIGN_EPI = false, bool SP2 = false>
; __device__ __forceinline__ void gemm_phase(PG8_LAS unsigned char* lds, const Gemm g, const Sched& S, const Epi& E) {
;     ...
;             PG8_LDB(B0, 0, 0); PG8_LDB(B1, 0, 1); PG8_SCHED; PG8_LDA(At, 0, 0); PG8_STAGE(PG8_SA(1, 1), a1 + hstep, voffA);
;             PG8_WAIT_V(8); PG8_WAIT_L(0); PG8_BAR; PG8_MMA(0, 0, At, B0); PG8_MMA(0, 1, At, B1); PG8_BAR; PG8_SCHED;
;             PG8_LDA(At, 0, 1); PG8_STAGE(PG8_SB(0, 0), b2, voffB); PG8_STAGE(PG8_SB(0, 1), b2 + hstepB, voffB); PG8_STAGE(PG8_SA(0, 0), a2, voffA);
;             PG8_WAIT_V(8); PG8_WAIT_L(0); PG8_BAR; PG8_MMA(1, 0, At, B0); PG8_MMA(1, 1, At, B1); PG8_BAR; PG8_SCHED;
;             PG8_LDB(B0, 1, 0); PG8_LDB(B1, 1, 1); PG8_SCHED; PG8_LDA(At, 1, 0); PG8_STAGE(PG8_SA(0, 1), a2 + hstep, voffA);
;             PG8_WAIT_V(8); PG8_WAIT_L(0); PG8_BAR; PG8_MMA(0, 0, At, B0); PG8_MMA(0, 1, At, B1); PG8_BAR; PG8_SCHED;
;             PG8_LDA(At, 1, 1); PG8_STAGE(PG8_SB(1, 0), b3, voffB); PG8_STAGE(PG8_SB(1, 1), b3 + hstepB, voffB); PG8_STAGE(PG8_SA(1, 0), a3, voffA);
;             PG8_WAIT_V(8); PG8_WAIT_L(0); PG8_BAR; PG8_MMA(1, 0, At, B0); PG8_MMA(1, 1, At, B1); PG8_BAR; PG8_SCHED;
	s_add_i32 s9, s9, s0
	s_mov_b32 m0, s9
	ds_read_b128 v[182:185], v165 offset:49152
	ds_read_b128 v[206:209], v165 offset:50176
	ds_read_b128 v[210:213], v165 offset:51200
	ds_read_b128 v[214:217], v165 offset:52224
	ds_read_b128 v[218:221], v165 offset:53248
	ds_read_b128 v[236:239], v165 offset:54272
	ds_read_b128 v[240:243], v165 offset:55296
	ds_read_b128 v[244:247], v165 offset:56320
	s_add_u32 s100, s80, s60
	s_addc_u32 s101, s81, s61
	global_load_lds_dwordx4 v132, s[100:101]
	s_add_i32 m0, s9, 0x2000
	s_add_u32 s10, s80, 0x20080
	s_addc_u32 s11, s81, 0
	s_add_i32 s9, s12, s0
	global_load_lds_dwordx4 v136, s[100:101]
	s_mov_b32 m0, s9
	s_nop 0
	global_load_lds_dwordx4 v132, s[10:11]
	s_add_i32 m0, s9, 0x2000
	s_nop 0
	global_load_lds_dwordx4 v136, s[10:11]
	s_mov_b32 m0, s66
	s_add_u32 s100, s84, s60
	s_addc_u32 s101, s85, s61
	global_load_lds_dwordx4 v130, s[100:101]
	s_mov_b32 m0, s67
	s_nop 0
	global_load_lds_dwordx4 v134, s[100:101]
	s_waitcnt vmcnt(8)
	s_waitcnt lgkmcnt(0)
	s_barrier
	v_mfma_f32_16x16x32_bf16 v[62:65], v[148:151], v[182:185], v[62:65]
	v_mfma_f32_16x16x32_bf16 v[54:57], v[148:151], v[210:213], v[54:57]
	v_mfma_f32_16x16x32_bf16 v[46:49], v[148:151], v[218:221], v[46:49]
	v_mfma_f32_16x16x32_bf16 v[38:41], v[148:151], v[240:243], v[38:41]
	v_mfma_f32_16x16x32_bf16 v[58:61], v[156:159], v[182:185], v[58:61]
	v_mfma_f32_16x16x32_bf16 v[50:53], v[156:159], v[210:213], v[50:53]
	v_mfma_f32_16x16x32_bf16 v[42:45], v[156:159], v[218:221], v[42:45]
	v_mfma_f32_16x16x32_bf16 v[34:37], v[156:159], v[240:243], v[34:37]
	v_mfma_f32_16x16x32_bf16 v[62:65], v[152:155], v[206:209], v[62:65]
	v_mfma_f32_16x16x32_bf16 v[54:57], v[152:155], v[214:217], v[54:57]
	v_mfma_f32_16x16x32_bf16 v[46:49], v[152:155], v[236:239], v[46:49]
	v_mfma_f32_16x16x32_bf16 v[38:41], v[152:155], v[244:247], v[38:41]
	v_mfma_f32_16x16x32_bf16 v[58:61], v[160:163], v[206:209], v[58:61]
	v_mfma_f32_16x16x32_bf16 v[50:53], v[160:163], v[214:217], v[50:53]
	v_mfma_f32_16x16x32_bf16 v[42:45], v[160:163], v[236:239], v[42:45]
	v_mfma_f32_16x16x32_bf16 v[34:37], v[160:163], v[244:247], v[34:37]
	v_mfma_f32_16x16x32_bf16 v[30:33], v[166:169], v[182:185], v[30:33]
	v_mfma_f32_16x16x32_bf16 v[22:25], v[166:169], v[210:213], v[22:25]
	v_mfma_f32_16x16x32_bf16 v[14:17], v[166:169], v[218:221], v[14:17]
	v_mfma_f32_16x16x32_bf16 v[6:9], v[166:169], v[240:243], v[6:9]
	v_mfma_f32_16x16x32_bf16 v[26:29], v[174:177], v[182:185], v[26:29]
	v_mfma_f32_16x16x32_bf16 v[18:21], v[174:177], v[210:213], v[18:21]
	v_mfma_f32_16x16x32_bf16 v[10:13], v[174:177], v[218:221], v[10:13]
	v_mfma_f32_16x16x32_bf16 v[2:5], v[174:177], v[240:243], v[2:5]
	v_mfma_f32_16x16x32_bf16 v[30:33], v[170:173], v[206:209], v[30:33]
	v_mfma_f32_16x16x32_bf16 v[22:25], v[170:173], v[214:217], v[22:25]
	v_mfma_f32_16x16x32_bf16 v[14:17], v[170:173], v[236:239], v[14:17]
	v_mfma_f32_16x16x32_bf16 v[6:9], v[170:173], v[244:247], v[6:9]
	v_mfma_f32_16x16x32_bf16 v[26:29], v[178:181], v[206:209], v[26:29]
	v_mfma_f32_16x16x32_bf16 v[18:21], v[178:181], v[214:217], v[18:21]
	v_mfma_f32_16x16x32_bf16 v[10:13], v[178:181], v[236:239], v[10:13]
	v_mfma_f32_16x16x32_bf16 v[2:5], v[178:181], v[244:247], v[2:5]
	s_barrier
	s_add_i32 s8, s8, 2
	s_add_u32 s46, s46, 0x100
	s_addc_u32 s47, s47, 0
	s_cmp_gt_u32 s8, 29
.LBB0_170:
	s_add_u32 s9, s70, s46
	s_addc_u32 s10, s71, s47
	s_add_u32 s9, s9, 0x100
	s_addc_u32 s10, s10, 0
	s_add_u32 s100, s9, 0x7ff80
	s_addc_u32 s101, s10, 0
	s_add_u32 s11, s93, s46
	s_addc_u32 s12, s94, s47
	s_add_i32 s13, 0, 0x10000
	s_cmpk_eq_i32 s46, 0xf00
	s_cselect_b32 s85, s4, s10
	s_cselect_b32 s84, s5, s9
	s_cselect_b32 s81, s6, s12
	s_cselect_b32 s80, s7, s11
	s_add_i32 s9, 0, 0x14000
	ds_read_b128 v[148:151], v186
	ds_read_b128 v[152:155], v186 offset:1024
	ds_read_b128 v[156:159], v186 offset:2048
	ds_read_b128 v[160:163], v186 offset:3072
	ds_read_b128 v[166:169], v187
	ds_read_b128 v[170:173], v187 offset:1024
	ds_read_b128 v[174:177], v187 offset:2048
	ds_read_b128 v[178:181], v187 offset:3072
	s_add_i32 m0, s1, 0xc000
	ds_read_b128 v[182:185], v165
	ds_read_b128 v[206:209], v165 offset:1024
	ds_read_b128 v[210:213], v165 offset:2048
	ds_read_b128 v[214:217], v165 offset:3072
	ds_read_b128 v[218:221], v165 offset:4096
	ds_read_b128 v[236:239], v165 offset:5120
	ds_read_b128 v[240:243], v165 offset:6144
	ds_read_b128 v[244:247], v165 offset:7168
	global_load_lds_dwordx4 v140, s[100:101]
	s_add_i32 m0, s1, 0xe000
	s_nop 0
	global_load_lds_dwordx4 v142, s[100:101]
	s_waitcnt vmcnt(8)
	s_waitcnt lgkmcnt(0)
	s_barrier
; #define PG8_STAGE(bufoff, gbase, voff) do { _Pragma("unroll") for (int _i = 0; _i < 2; ++_i) \
;         __builtin_amdgcn_global_load_lds((const unsigned*)((const char*)(gbase) + (voff)[_i]), (PG8_LAS unsigned*)(lds + (bufoff) + ldsw + _i * 8192), 16, 0, 0); } while (0)
; #define PG8_LDA(dst, b, h) do { _Pragma("unroll") for (int m = 0; m < 4; ++m) _Pragma("unroll") for (int k = 0; k < 2; ++k) dst[m][k] = *(const PG8_LAS bf16x8*)(lds + PG8_SA(b, h) + aoff + m * 2048 + k * 1024); } while (0)
; #define PG8_MMA(ai, bj, At, Bt) do { __builtin_amdgcn_s_setprio(1); _Pragma("unroll") for (int m = 0; m < 4; ++m) _Pragma("unroll") for (int n = 0; n < 2; ++n) _Pragma("unroll") for (int k = 0; k < 2; ++k) \
;         acc[ai][bj][m][n] = __builtin_amdgcn_mfma_f32_16x16x32_bf16(Bt[n][k], At[m][k], acc[ai][bj][m][n], 0, 0, 0); __builtin_amdgcn_s_setprio(0); } while (0)
; #define PG8_WAIT_V(n) asm volatile("s_waitcnt vmcnt(" #n ")" ::: "memory")
; #define PG8_WAIT_L(n) asm volatile("s_waitcnt lgkmcnt(" #n ")" ::: "memory")
; #define PG8_BAR __builtin_amdgcn_s_barrier()
; #define PG8_SCHED __builtin_amdgcn_sched_barrier(0)
; template <class Epi, class Sched, bool ALIGN_EPI = false, bool SP2 = false>
; __device__ __forceinline__ void gemm_phase(PG8_LAS unsigned char* lds, const Gemm g, const Sched& S, const Epi& E) {
;     ...
;             PG8_WAIT_V(8); PG8_WAIT_L(0); PG8_BAR; PG8_MMA(0, 0, At, B0); PG8_MMA(0, 1, At, B1); PG8_BAR; PG8_SCHED;
;             PG8_LDA(At, 0, 1); PG8_STAGE(PG8_SB(0, 0), b2, voffB); PG8_STAGE(PG8_SB(0, 1), b2 + hstepB, voffB); PG8_STAGE(PG8_SA(0, 0), a2, voffA);
;             PG8_WAIT_V(8); PG8_WAIT_L(0); PG8_BAR; PG8_MMA(1, 0, At, B0); PG8_MMA(1, 1, At, B1); PG8_BAR; PG8_SCHED;
	v_mfma_f32_16x16x32_bf16 v[126:129], v[148:151], v[182:185], v[126:129]
	v_mfma_f32_16x16x32_bf16 v[118:121], v[148:151], v[210:213], v[118:121]
	v_mfma_f32_16x16x32_bf16 v[110:113], v[148:151], v[218:221], v[110:113]
	v_mfma_f32_16x16x32_bf16 v[102:105], v[148:151], v[240:243], v[102:105]
	v_mfma_f32_16x16x32_bf16 v[122:125], v[156:159], v[182:185], v[122:125]
	v_mfma_f32_16x16x32_bf16 v[114:117], v[156:159], v[210:213], v[114:117]
	v_mfma_f32_16x16x32_bf16 v[106:109], v[156:159], v[218:221], v[106:109]
	v_mfma_f32_16x16x32_bf16 v[98:101], v[156:159], v[240:243], v[98:101]
	v_mfma_f32_16x16x32_bf16 v[126:129], v[152:155], v[206:209], v[126:129]
	v_mfma_f32_16x16x32_bf16 v[118:121], v[152:155], v[214:217], v[118:121]
	v_mfma_f32_16x16x32_bf16 v[110:113], v[152:155], v[236:239], v[110:113]
	v_mfma_f32_16x16x32_bf16 v[102:105], v[152:155], v[244:247], v[102:105]
	v_mfma_f32_16x16x32_bf16 v[122:125], v[160:163], v[206:209], v[122:125]
	v_mfma_f32_16x16x32_bf16 v[114:117], v[160:163], v[214:217], v[114:117]
	v_mfma_f32_16x16x32_bf16 v[106:109], v[160:163], v[236:239], v[106:109]
	v_mfma_f32_16x16x32_bf16 v[98:101], v[160:163], v[244:247], v[98:101]
	v_mfma_f32_16x16x32_bf16 v[94:97], v[166:169], v[182:185], v[94:97]
	v_mfma_f32_16x16x32_bf16 v[86:89], v[166:169], v[210:213], v[86:89]
	v_mfma_f32_16x16x32_bf16 v[78:81], v[166:169], v[218:221], v[78:81]
	v_mfma_f32_16x16x32_bf16 v[70:73], v[166:169], v[240:243], v[70:73]
	v_mfma_f32_16x16x32_bf16 v[90:93], v[174:177], v[182:185], v[90:93]
	v_mfma_f32_16x16x32_bf16 v[82:85], v[174:177], v[210:213], v[82:85]
	v_mfma_f32_16x16x32_bf16 v[74:77], v[174:177], v[218:221], v[74:77]
	v_mfma_f32_16x16x32_bf16 v[66:69], v[174:177], v[240:243], v[66:69]
	v_mfma_f32_16x16x32_bf16 v[94:97], v[170:173], v[206:209], v[94:97]
	v_mfma_f32_16x16x32_bf16 v[86:89], v[170:173], v[214:217], v[86:89]
	v_mfma_f32_16x16x32_bf16 v[78:81], v[170:173], v[236:239], v[78:81]
	v_mfma_f32_16x16x32_bf16 v[70:73], v[170:173], v[244:247], v[70:73]
	v_mfma_f32_16x16x32_bf16 v[90:93], v[178:181], v[206:209], v[90:93]
	v_mfma_f32_16x16x32_bf16 v[82:85], v[178:181], v[214:217], v[82:85]
	v_mfma_f32_16x16x32_bf16 v[74:77], v[178:181], v[236:239], v[74:77]
	v_mfma_f32_16x16x32_bf16 v[66:69], v[178:181], v[244:247], v[66:69]
	s_barrier
	s_add_i32 s10, s13, s0
	s_mov_b32 m0, s10
	ds_read_b128 v[182:185], v165 offset:16384
	ds_read_b128 v[206:209], v165 offset:17408
	ds_read_b128 v[210:213], v165 offset:18432
	ds_read_b128 v[214:217], v165 offset:19456
	ds_read_b128 v[218:221], v165 offset:20480
	ds_read_b128 v[236:239], v165 offset:21504
	ds_read_b128 v[240:243], v165 offset:22528
	ds_read_b128 v[244:247], v165 offset:23552
	global_load_lds_dwordx4 v132, s[80:81]
	s_add_i32 m0, s10, 0x2000
	s_add_u32 s10, s80, 0x20000
	s_addc_u32 s11, s81, 0
	s_add_i32 s9, s9, s0
	global_load_lds_dwordx4 v136, s[80:81]
	s_mov_b32 m0, s9
	s_nop 0
	global_load_lds_dwordx4 v132, s[10:11]
	s_add_i32 m0, s9, 0x2000
	s_nop 0
	global_load_lds_dwordx4 v136, s[10:11]
	s_mov_b32 m0, s1
	s_nop 0
	global_load_lds_dwordx4 v130, s[84:85]
	s_mov_b32 m0, s25
	s_nop 0
	global_load_lds_dwordx4 v134, s[84:85]
	s_waitcnt vmcnt(8)
	s_waitcnt lgkmcnt(0)
	s_barrier
	v_mfma_f32_16x16x32_bf16 v[62:65], v[148:151], v[182:185], v[62:65]
	v_mfma_f32_16x16x32_bf16 v[54:57], v[148:151], v[210:213], v[54:57]
	v_mfma_f32_16x16x32_bf16 v[46:49], v[148:151], v[218:221], v[46:49]
	v_mfma_f32_16x16x32_bf16 v[38:41], v[148:151], v[240:243], v[38:41]
	v_mfma_f32_16x16x32_bf16 v[58:61], v[156:159], v[182:185], v[58:61]
	v_mfma_f32_16x16x32_bf16 v[50:53], v[156:159], v[210:213], v[50:53]
	v_mfma_f32_16x16x32_bf16 v[42:45], v[156:159], v[218:221], v[42:45]
	v_mfma_f32_16x16x32_bf16 v[34:37], v[156:159], v[240:243], v[34:37]
	v_mfma_f32_16x16x32_bf16 v[62:65], v[152:155], v[206:209], v[62:65]
	v_mfma_f32_16x16x32_bf16 v[54:57], v[152:155], v[214:217], v[54:57]
	v_mfma_f32_16x16x32_bf16 v[46:49], v[152:155], v[236:239], v[46:49]
	v_mfma_f32_16x16x32_bf16 v[38:41], v[152:155], v[244:247], v[38:41]
	v_mfma_f32_16x16x32_bf16 v[58:61], v[160:163], v[206:209], v[58:61]
	v_mfma_f32_16x16x32_bf16 v[50:53], v[160:163], v[214:217], v[50:53]
	v_mfma_f32_16x16x32_bf16 v[42:45], v[160:163], v[236:239], v[42:45]
	v_mfma_f32_16x16x32_bf16 v[34:37], v[160:163], v[244:247], v[34:37]
	v_mfma_f32_16x16x32_bf16 v[30:33], v[166:169], v[182:185], v[30:33]
	v_mfma_f32_16x16x32_bf16 v[22:25], v[166:169], v[210:213], v[22:25]
	v_mfma_f32_16x16x32_bf16 v[14:17], v[166:169], v[218:221], v[14:17]
	v_mfma_f32_16x16x32_bf16 v[6:9], v[166:169], v[240:243], v[6:9]
	v_mfma_f32_16x16x32_bf16 v[26:29], v[174:177], v[182:185], v[26:29]
	v_mfma_f32_16x16x32_bf16 v[18:21], v[174:177], v[210:213], v[18:21]
	v_mfma_f32_16x16x32_bf16 v[10:13], v[174:177], v[218:221], v[10:13]
	v_mfma_f32_16x16x32_bf16 v[2:5], v[174:177], v[240:243], v[2:5]
	v_mfma_f32_16x16x32_bf16 v[30:33], v[170:173], v[206:209], v[30:33]
	v_mfma_f32_16x16x32_bf16 v[22:25], v[170:173], v[214:217], v[22:25]
	v_mfma_f32_16x16x32_bf16 v[14:17], v[170:173], v[236:239], v[14:17]
	v_mfma_f32_16x16x32_bf16 v[6:9], v[170:173], v[244:247], v[6:9]
	v_mfma_f32_16x16x32_bf16 v[26:29], v[178:181], v[206:209], v[26:29]
	v_mfma_f32_16x16x32_bf16 v[18:21], v[178:181], v[214:217], v[18:21]
	v_mfma_f32_16x16x32_bf16 v[10:13], v[178:181], v[236:239], v[10:13]
	v_mfma_f32_16x16x32_bf16 v[2:5], v[178:181], v[244:247], v[2:5]
	s_barrier
; #define PG8_STAGE(bufoff, gbase, voff) do { _Pragma("unroll") for (int _i = 0; _i < 2; ++_i) \
;         __builtin_amdgcn_global_load_lds((const unsigned*)((const char*)(gbase) + (voff)[_i]), (PG8_LAS unsigned*)(lds + (bufoff) + ldsw + _i * 8192), 16, 0, 0); } while (0)
; #define PG8_LDA(dst, b, h) do { _Pragma("unroll") for (int m = 0; m < 4; ++m) _Pragma("unroll") for (int k = 0; k < 2; ++k) dst[m][k] = *(const PG8_LAS bf16x8*)(lds + PG8_SA(b, h) + aoff + m * 2048 + k * 1024); } while (0)
; #define PG8_LDB(dst, b, h) do { _Pragma("unroll") for (int n = 0; n < 2; ++n) _Pragma("unroll") for (int k = 0; k < 2; ++k) dst[n][k] = *(const PG8_LAS bf16x8*)(lds + PG8_SB(b, h) + boff + n * 2048 + k * 1024); } while (0)
; #define PG8_MMA(ai, bj, At, Bt) do { __builtin_amdgcn_s_setprio(1); _Pragma("unroll") for (int m = 0; m < 4; ++m) _Pragma("unroll") for (int n = 0; n < 2; ++n) _Pragma("unroll") for (int k = 0; k < 2; ++k) \
;         acc[ai][bj][m][n] = __builtin_amdgcn_mfma_f32_16x16x32_bf16(Bt[n][k], At[m][k], acc[ai][bj][m][n], 0, 0, 0); __builtin_amdgcn_s_setprio(0); } while (0)
; #define PG8_WAIT_V(n) asm volatile("s_waitcnt vmcnt(" #n ")" ::: "memory")
; #define PG8_WAIT_L(n) asm volatile("s_waitcnt lgkmcnt(" #n ")" ::: "memory")
; #define PG8_BAR __builtin_amdgcn_s_barrier()
; #define PG8_SCHED __builtin_amdgcn_sched_barrier(0)
; template <class Epi, class Sched, bool ALIGN_EPI = false, bool SP2 = false>
; __device__ __forceinline__ void gemm_phase(PG8_LAS unsigned char* lds, const Gemm g, const Sched& S, const Epi& E) {
;     ...
;             PG8_LDB(B0, 1, 0); PG8_LDB(B1, 1, 1); PG8_SCHED; PG8_LDA(At, 1, 0); PG8_STAGE(PG8_SA(0, 1), a2 + hstep, voffA);
;             PG8_WAIT_V(8); PG8_WAIT_L(0); PG8_BAR; PG8_MMA(0, 0, At, B0); PG8_MMA(0, 1, At, B1); PG8_BAR; PG8_SCHED;
;             PG8_LDA(At, 1, 1); PG8_STAGE(PG8_SB(1, 0), b3, voffB); PG8_STAGE(PG8_SB(1, 1), b3 + hstepB, voffB); PG8_STAGE(PG8_SA(1, 0), a3, voffA);
;             PG8_WAIT_V(8); PG8_WAIT_L(0); PG8_BAR; PG8_MMA(1, 0, At, B0); PG8_MMA(1, 1, At, B1); PG8_BAR; PG8_SCHED;
;     ...
;         if constexpr (ALIGN_EPI) { if (wr == 0) PG8_BAR; }
	s_add_i32 s9, 0, 0x18000
	s_add_i32 s12, 0, 0x1c000
	ds_read_b128 v[148:151], v198
	ds_read_b128 v[152:155], v198 offset:1024
	ds_read_b128 v[156:159], v198 offset:2048
	ds_read_b128 v[160:163], v198 offset:3072
	ds_read_b128 v[166:169], v199
	ds_read_b128 v[170:173], v199 offset:1024
	ds_read_b128 v[174:177], v199 offset:2048
	ds_read_b128 v[178:181], v199 offset:3072
	s_add_u32 s10, s84, 0x80000
	s_addc_u32 s11, s85, 0
	s_mov_b32 m0, s42
	ds_read_b128 v[182:185], v165 offset:32768
	ds_read_b128 v[206:209], v165 offset:33792
	ds_read_b128 v[210:213], v165 offset:34816
	ds_read_b128 v[214:217], v165 offset:35840
	ds_read_b128 v[218:221], v165 offset:36864
	ds_read_b128 v[236:239], v165 offset:37888
	ds_read_b128 v[240:243], v165 offset:38912
	ds_read_b128 v[244:247], v165 offset:39936
	global_load_lds_dwordx4 v130, s[10:11]
	s_mov_b32 m0, s51
	s_nop 0
	global_load_lds_dwordx4 v134, s[10:11]
	s_waitcnt vmcnt(8)
	s_waitcnt lgkmcnt(0)
	s_barrier
	v_mfma_f32_16x16x32_bf16 v[126:129], v[148:151], v[182:185], v[126:129]
	v_mfma_f32_16x16x32_bf16 v[118:121], v[148:151], v[210:213], v[118:121]
	v_mfma_f32_16x16x32_bf16 v[110:113], v[148:151], v[218:221], v[110:113]
	v_mfma_f32_16x16x32_bf16 v[102:105], v[148:151], v[240:243], v[102:105]
	v_mfma_f32_16x16x32_bf16 v[122:125], v[156:159], v[182:185], v[122:125]
	v_mfma_f32_16x16x32_bf16 v[114:117], v[156:159], v[210:213], v[114:117]
	v_mfma_f32_16x16x32_bf16 v[106:109], v[156:159], v[218:221], v[106:109]
	v_mfma_f32_16x16x32_bf16 v[98:101], v[156:159], v[240:243], v[98:101]
	v_mfma_f32_16x16x32_bf16 v[126:129], v[152:155], v[206:209], v[126:129]
	v_mfma_f32_16x16x32_bf16 v[118:121], v[152:155], v[214:217], v[118:121]
	v_mfma_f32_16x16x32_bf16 v[110:113], v[152:155], v[236:239], v[110:113]
	v_mfma_f32_16x16x32_bf16 v[102:105], v[152:155], v[244:247], v[102:105]
	v_mfma_f32_16x16x32_bf16 v[122:125], v[160:163], v[206:209], v[122:125]
	v_mfma_f32_16x16x32_bf16 v[114:117], v[160:163], v[214:217], v[114:117]
	v_mfma_f32_16x16x32_bf16 v[106:109], v[160:163], v[236:239], v[106:109]
	v_mfma_f32_16x16x32_bf16 v[98:101], v[160:163], v[244:247], v[98:101]
	v_mfma_f32_16x16x32_bf16 v[94:97], v[166:169], v[182:185], v[94:97]
	v_mfma_f32_16x16x32_bf16 v[86:89], v[166:169], v[210:213], v[86:89]
	v_mfma_f32_16x16x32_bf16 v[78:81], v[166:169], v[218:221], v[78:81]
	v_mfma_f32_16x16x32_bf16 v[70:73], v[166:169], v[240:243], v[70:73]
	v_mfma_f32_16x16x32_bf16 v[90:93], v[174:177], v[182:185], v[90:93]
	v_mfma_f32_16x16x32_bf16 v[82:85], v[174:177], v[210:213], v[82:85]
	v_mfma_f32_16x16x32_bf16 v[74:77], v[174:177], v[218:221], v[74:77]
	v_mfma_f32_16x16x32_bf16 v[66:69], v[174:177], v[240:243], v[66:69]
	v_mfma_f32_16x16x32_bf16 v[94:97], v[170:173], v[206:209], v[94:97]
	v_mfma_f32_16x16x32_bf16 v[86:89], v[170:173], v[214:217], v[86:89]
	v_mfma_f32_16x16x32_bf16 v[78:81], v[170:173], v[236:239], v[78:81]
	v_mfma_f32_16x16x32_bf16 v[70:73], v[170:173], v[244:247], v[70:73]
	v_mfma_f32_16x16x32_bf16 v[90:93], v[178:181], v[206:209], v[90:93]
	v_mfma_f32_16x16x32_bf16 v[82:85], v[178:181], v[214:217], v[82:85]
	v_mfma_f32_16x16x32_bf16 v[74:77], v[178:181], v[236:239], v[74:77]
	v_mfma_f32_16x16x32_bf16 v[66:69], v[178:181], v[244:247], v[66:69]
	s_barrier
	s_add_i32 s9, s9, s0
	s_mov_b32 m0, s9
	ds_read_b128 v[182:185], v165 offset:49152
	ds_read_b128 v[206:209], v165 offset:50176
	ds_read_b128 v[210:213], v165 offset:51200
	ds_read_b128 v[214:217], v165 offset:52224
	ds_read_b128 v[218:221], v165 offset:53248
	ds_read_b128 v[236:239], v165 offset:54272
	ds_read_b128 v[240:243], v165 offset:55296
	ds_read_b128 v[244:247], v165 offset:56320
	s_add_u32 s100, s80, s60
	s_addc_u32 s101, s81, s61
	global_load_lds_dwordx4 v132, s[100:101]
	s_add_i32 m0, s9, 0x2000
	s_add_u32 s10, s80, 0x20080
	s_addc_u32 s11, s81, 0
	s_add_i32 s9, s12, s0
	global_load_lds_dwordx4 v136, s[100:101]
	s_mov_b32 m0, s9
	s_nop 0
	global_load_lds_dwordx4 v132, s[10:11]
	s_add_i32 m0, s9, 0x2000
	s_nop 0
	global_load_lds_dwordx4 v136, s[10:11]
	s_mov_b32 m0, s66
	s_add_u32 s100, s84, s60
	s_addc_u32 s101, s85, s61
	global_load_lds_dwordx4 v130, s[100:101]
	s_mov_b32 m0, s67
	s_nop 0
	global_load_lds_dwordx4 v134, s[100:101]
	s_waitcnt vmcnt(8)
	s_waitcnt lgkmcnt(0)
	s_barrier
	v_mfma_f32_16x16x32_bf16 v[62:65], v[148:151], v[182:185], v[62:65]
	v_mfma_f32_16x16x32_bf16 v[54:57], v[148:151], v[210:213], v[54:57]
	v_mfma_f32_16x16x32_bf16 v[46:49], v[148:151], v[218:221], v[46:49]
	v_mfma_f32_16x16x32_bf16 v[38:41], v[148:151], v[240:243], v[38:41]
	v_mfma_f32_16x16x32_bf16 v[58:61], v[156:159], v[182:185], v[58:61]
	v_mfma_f32_16x16x32_bf16 v[50:53], v[156:159], v[210:213], v[50:53]
	v_mfma_f32_16x16x32_bf16 v[42:45], v[156:159], v[218:221], v[42:45]
	v_mfma_f32_16x16x32_bf16 v[34:37], v[156:159], v[240:243], v[34:37]
	v_mfma_f32_16x16x32_bf16 v[62:65], v[152:155], v[206:209], v[62:65]
	v_mfma_f32_16x16x32_bf16 v[54:57], v[152:155], v[214:217], v[54:57]
	v_mfma_f32_16x16x32_bf16 v[46:49], v[152:155], v[236:239], v[46:49]
	v_mfma_f32_16x16x32_bf16 v[38:41], v[152:155], v[244:247], v[38:41]
	v_mfma_f32_16x16x32_bf16 v[58:61], v[160:163], v[206:209], v[58:61]
	v_mfma_f32_16x16x32_bf16 v[50:53], v[160:163], v[214:217], v[50:53]
	v_mfma_f32_16x16x32_bf16 v[42:45], v[160:163], v[236:239], v[42:45]
	v_mfma_f32_16x16x32_bf16 v[34:37], v[160:163], v[244:247], v[34:37]
	v_mfma_f32_16x16x32_bf16 v[30:33], v[166:169], v[182:185], v[30:33]
	v_mfma_f32_16x16x32_bf16 v[22:25], v[166:169], v[210:213], v[22:25]
	v_mfma_f32_16x16x32_bf16 v[14:17], v[166:169], v[218:221], v[14:17]
	v_mfma_f32_16x16x32_bf16 v[6:9], v[166:169], v[240:243], v[6:9]
	v_mfma_f32_16x16x32_bf16 v[26:29], v[174:177], v[182:185], v[26:29]
	v_mfma_f32_16x16x32_bf16 v[18:21], v[174:177], v[210:213], v[18:21]
	v_mfma_f32_16x16x32_bf16 v[10:13], v[174:177], v[218:221], v[10:13]
	v_mfma_f32_16x16x32_bf16 v[2:5], v[174:177], v[240:243], v[2:5]
	v_mfma_f32_16x16x32_bf16 v[30:33], v[170:173], v[206:209], v[30:33]
	v_mfma_f32_16x16x32_bf16 v[22:25], v[170:173], v[214:217], v[22:25]
	v_mfma_f32_16x16x32_bf16 v[14:17], v[170:173], v[236:239], v[14:17]
	v_mfma_f32_16x16x32_bf16 v[6:9], v[170:173], v[244:247], v[6:9]
	v_mfma_f32_16x16x32_bf16 v[26:29], v[178:181], v[206:209], v[26:29]
	v_mfma_f32_16x16x32_bf16 v[18:21], v[178:181], v[214:217], v[18:21]
	v_mfma_f32_16x16x32_bf16 v[10:13], v[178:181], v[236:239], v[10:13]
	v_mfma_f32_16x16x32_bf16 v[2:5], v[178:181], v[244:247], v[2:5]
	s_barrier
	s_add_i32 s8, s8, 2
	s_add_u32 s46, s46, 0x100
	s_addc_u32 s47, s47, 0
	s_cmp_gt_u32 s8, 29
	s_cbranch_scc0 .LBB0_170
	s_and_b64 vcc, exec, s[54:55]
	s_cbranch_vccz .LBB0_173
	s_barrier

; #define PG8_STAGE(bufoff, gbase, voff) do { _Pragma("unroll") for (int _i = 0; _i < 2; ++_i) \
;         __builtin_amdgcn_global_load_lds((const unsigned*)((const char*)(gbase) + (voff)[_i]), (PG8_LAS unsigned*)(lds + (bufoff) + ldsw + _i * 8192), 16, 0, 0); } while (0)
; #define PG8_LDA(dst, b, h) do { _Pragma("unroll") for (int m = 0; m < 4; ++m) _Pragma("unroll") for (int k = 0; k < 2; ++k) dst[m][k] = *(const PG8_LAS bf16x8*)(lds + PG8_SA(b, h) + aoff + m * 2048 + k * 1024); } while (0)
; #define PG8_LDB(dst, b, h) do { _Pragma("unroll") for (int n = 0; n < 2; ++n) _Pragma("unroll") for (int k = 0; k < 2; ++k) dst[n][k] = *(const PG8_LAS bf16x8*)(lds + PG8_SB(b, h) + boff + n * 2048 + k * 1024); } while (0)
; #define PG8_MMA(ai, bj, At, Bt) do { __builtin_amdgcn_s_setprio(1); _Pragma("unroll") for (int m = 0; m < 4; ++m) _Pragma("unroll") for (int n = 0; n < 2; ++n) _Pragma("unroll") for (int k = 0; k < 2; ++k) \
;         acc[ai][bj][m][n] = __builtin_amdgcn_mfma_f32_16x16x32_bf16(Bt[n][k], At[m][k], acc[ai][bj][m][n], 0, 0, 0); __builtin_amdgcn_s_setprio(0); } while (0)
; #define PG8_BAR __builtin_amdgcn_s_barrier()
; template <class Epi, class Sched, bool ALIGN_EPI = false, bool SP2 = false>
; __device__ __forceinline__ void gemm_phase(PG8_LAS unsigned char* lds, const Gemm g, const Sched& S, const Epi& E) {
;     ...
;         const bool has_next = S.next(ui + 1, nxt);
;         const char* nA = has_next ? (const char*)g.A + (size_t)nxt.pm * tstep : cA; const char* nB = has_next ? (const char*)g.Bt + (size_t)nxt.pn * tstep : cB;
;         for (int t = 0; t < nt; t += 2) {
;             const bool last = (t == nt - 2);
;             const char* a1 = cA + (size_t)(t + 1) * kstep;
;             const char* a2 = last ? nA : cA + (size_t)(t + 2) * kstep; const char* b2 = last ? nB : cB + (size_t)(t + 2) * kstep;
;             const char* a3 = a2 + kstep; const char* b3 = b2 + kstep;
;             if (last && has_next) S.a_ready(nxt);
;             if constexpr (SP2) {
;             PG8_LDB(B0, 0, 0); PG8_LDB(B1, 0, 1); PG8_SCHED; PG8_LDA(At, 0, 0); PG8_STAGE(PG8_SA(1, 1), a1 + hstep, voffA);
;             PG8_WAIT_V(8); PG8_WAIT_L(0); PG8_BAR; PG8_MMA(0, 0, At, B0); PG8_MMA(0, 1, At, B1); PG8_BAR; PG8_SCHED;
;             PG8_LDA(At, 0, 1); PG8_STAGE(PG8_SB(0, 0), b2, voffB); PG8_STAGE(PG8_SB(0, 1), b2 + hstepB, voffB); PG8_STAGE(PG8_SA(0, 0), a2, voffA);
.LBB0_926:
	s_ashr_i32 s73, s72, 31
	s_lshl_b64 s[4:5], s[72:73], 20
	v_readlane_b32 s6, v249, 9
	v_readlane_b32 s7, v249, 10
	s_add_u32 s76, s6, s4
	s_addc_u32 s77, s7, s5
	s_and_b64 s[4:5], s[92:93], exec
	s_cselect_b32 s36, s77, s39
	s_cselect_b32 s37, s76, s38
	s_ashr_i32 s69, s68, 31
	s_lshl_b64 s[4:5], s[68:69], 20
	v_readlane_b32 s6, v249, 17
	v_readlane_b32 s7, v249, 18
	s_add_u32 s80, s6, s4
	s_addc_u32 s81, s7, s5
	s_and_b64 s[4:5], s[92:93], exec
	s_cselect_b32 s4, s81, s47
	s_cselect_b32 s5, s80, s46
	s_add_u32 s38, s38, 0x80080
	s_addc_u32 s39, s39, 0
	s_add_u32 s6, s46, 0x100
	v_mov_b32_e32 v2, 0
	s_addc_u32 s7, s47, 0
	s_mov_b32 s8, -2
	v_mov_b32_e32 v3, v2
	v_mov_b32_e32 v4, v2
	v_mov_b32_e32 v5, v2
	v_mov_b32_e32 v6, v2
	v_mov_b32_e32 v7, v2
	v_mov_b32_e32 v8, v2
	v_mov_b32_e32 v9, v2
	v_mov_b32_e32 v18, v2
	v_mov_b32_e32 v19, v2
	v_mov_b32_e32 v20, v2
	v_mov_b32_e32 v21, v2
	v_mov_b32_e32 v22, v2
	v_mov_b32_e32 v23, v2
	v_mov_b32_e32 v24, v2
	v_mov_b32_e32 v25, v2
	v_mov_b32_e32 v34, v2
	s_waitcnt lgkmcnt(0)
	v_add_u32_e32 v186, 0x10000, v193
	v_add_u32_e32 v187, 0x14000, v193
	v_add_u32_e32 v198, 0x18000, v193
	v_add_u32_e32 v199, 0x1c000, v193
	s_add_u32 s9, s38, 0xfff80080
	s_addc_u32 s10, s39, -1
	s_add_i32 s11, 0, 0x10000
	s_cmp_eq_u32 s8, 28
	s_cselect_b32 s95, s36, s10
	s_cselect_b32 s94, s37, s9
	s_cselect_b32 s47, s4, s7
	s_cselect_b32 s46, s5, s6
	s_add_i32 s9, 0, 0x14000
	ds_read_b128 v[66:69], v186
	ds_read_b128 v[70:73], v186 offset:1024
	ds_read_b128 v[78:81], v186 offset:2048
	ds_read_b128 v[86:89], v186 offset:3072
	ds_read_b128 v[146:149], v187
	ds_read_b128 v[150:153], v187 offset:1024
	ds_read_b128 v[154:157], v187 offset:2048
	ds_read_b128 v[158:161], v187 offset:3072
	s_add_i32 m0, s66, 0xc000
	ds_read_b128 v[162:165], v236
	ds_read_b128 v[166:169], v236 offset:1024
	ds_read_b128 v[170:173], v236 offset:2048
	ds_read_b128 v[174:177], v236 offset:3072
	ds_read_b128 v[178:181], v236 offset:4096
	ds_read_b128 v[182:185], v236 offset:5120
	ds_read_b128 v[216:219], v236 offset:6144
	ds_read_b128 v[220:223], v236 offset:7168
	global_load_lds_dwordx4 v212, s[38:39]
	s_add_i32 m0, s66, 0xe000
	s_nop 0
	global_load_lds_dwordx4 v214, s[38:39]
	s_waitcnt vmcnt(8)
	s_waitcnt lgkmcnt(0)
	s_barrier
	v_mfma_f32_16x16x32_bf16 v[142:145], v[66:69], v[162:165], 0
	v_mfma_f32_16x16x32_bf16 v[126:129], v[66:69], v[170:173], 0
	v_mfma_f32_16x16x32_bf16 v[110:113], v[66:69], v[178:181], 0
	v_mfma_f32_16x16x32_bf16 v[94:97], v[66:69], v[216:219], 0
	v_mfma_f32_16x16x32_bf16 v[138:141], v[78:81], v[162:165], 0
	v_mfma_f32_16x16x32_bf16 v[122:125], v[78:81], v[170:173], 0
	v_mfma_f32_16x16x32_bf16 v[106:109], v[78:81], v[178:181], 0
	v_mfma_f32_16x16x32_bf16 v[90:93], v[78:81], v[216:219], 0
	v_mfma_f32_16x16x32_bf16 v[142:145], v[70:73], v[166:169], v[142:145]
	v_mfma_f32_16x16x32_bf16 v[126:129], v[70:73], v[174:177], v[126:129]
	v_mfma_f32_16x16x32_bf16 v[110:113], v[70:73], v[182:185], v[110:113]
	v_mfma_f32_16x16x32_bf16 v[94:97], v[70:73], v[220:223], v[94:97]
	v_mfma_f32_16x16x32_bf16 v[138:141], v[86:89], v[166:169], v[138:141]
	v_mfma_f32_16x16x32_bf16 v[122:125], v[86:89], v[174:177], v[122:125]
	v_mfma_f32_16x16x32_bf16 v[106:109], v[86:89], v[182:185], v[106:109]
	v_mfma_f32_16x16x32_bf16 v[90:93], v[86:89], v[220:223], v[90:93]
	v_mfma_f32_16x16x32_bf16 v[134:137], v[146:149], v[162:165], 0
	v_mfma_f32_16x16x32_bf16 v[118:121], v[146:149], v[170:173], 0
	v_mfma_f32_16x16x32_bf16 v[102:105], v[146:149], v[178:181], 0
	v_mfma_f32_16x16x32_bf16 v[82:85], v[146:149], v[216:219], 0
	v_mfma_f32_16x16x32_bf16 v[130:133], v[154:157], v[162:165], 0
	v_mfma_f32_16x16x32_bf16 v[114:117], v[154:157], v[170:173], 0
	v_mfma_f32_16x16x32_bf16 v[98:101], v[154:157], v[178:181], 0
	v_mfma_f32_16x16x32_bf16 v[74:77], v[154:157], v[216:219], 0
	v_mfma_f32_16x16x32_bf16 v[134:137], v[150:153], v[166:169], v[134:137]
	v_mfma_f32_16x16x32_bf16 v[118:121], v[150:153], v[174:177], v[118:121]
	v_mfma_f32_16x16x32_bf16 v[102:105], v[150:153], v[182:185], v[102:105]
	v_mfma_f32_16x16x32_bf16 v[82:85], v[150:153], v[220:223], v[82:85]
	v_mfma_f32_16x16x32_bf16 v[130:133], v[158:161], v[166:169], v[130:133]
	v_mfma_f32_16x16x32_bf16 v[114:117], v[158:161], v[174:177], v[114:117]
	v_mfma_f32_16x16x32_bf16 v[98:101], v[158:161], v[182:185], v[98:101]
	v_mfma_f32_16x16x32_bf16 v[74:77], v[158:161], v[220:223], v[74:77]
	s_barrier
	s_add_i32 s10, s11, s25
	s_mov_b32 m0, s10
	ds_read_b128 v[162:165], v236 offset:16384
	ds_read_b128 v[166:169], v236 offset:17408
	ds_read_b128 v[170:173], v236 offset:18432
	ds_read_b128 v[174:177], v236 offset:19456
	ds_read_b128 v[178:181], v236 offset:20480
	ds_read_b128 v[182:185], v236 offset:21504
	ds_read_b128 v[216:219], v236 offset:22528
	ds_read_b128 v[220:223], v236 offset:23552
	global_load_lds_dwordx4 v190, s[46:47]
	s_add_i32 m0, s10, 0x2000
	s_add_u32 s10, s46, 0x20000
	s_addc_u32 s11, s47, 0
	s_add_i32 s9, s9, s25
	global_load_lds_dwordx4 v206, s[46:47]
	s_mov_b32 m0, s9
	s_nop 0
	global_load_lds_dwordx4 v190, s[10:11]
	s_add_i32 m0, s9, 0x2000
	s_nop 0
	global_load_lds_dwordx4 v206, s[10:11]
	s_mov_b32 m0, s66
	s_nop 0
	global_load_lds_dwordx4 v210, s[94:95]
	s_mov_b32 m0, s67
	s_nop 0
	global_load_lds_dwordx4 v208, s[94:95]
	s_waitcnt vmcnt(8)
	s_waitcnt lgkmcnt(0)
	s_barrier
; #define PG8_STAGE(bufoff, gbase, voff) do { _Pragma("unroll") for (int _i = 0; _i < 2; ++_i) \
;         __builtin_amdgcn_global_load_lds((const unsigned*)((const char*)(gbase) + (voff)[_i]), (PG8_LAS unsigned*)(lds + (bufoff) + ldsw + _i * 8192), 16, 0, 0); } while (0)
; #define PG8_LDA(dst, b, h) do { _Pragma("unroll") for (int m = 0; m < 4; ++m) _Pragma("unroll") for (int k = 0; k < 2; ++k) dst[m][k] = *(const PG8_LAS bf16x8*)(lds + PG8_SA(b, h) + aoff + m * 2048 + k * 1024); } while (0)
; #define PG8_LDB(dst, b, h) do { _Pragma("unroll") for (int n = 0; n < 2; ++n) _Pragma("unroll") for (int k = 0; k < 2; ++k) dst[n][k] = *(const PG8_LAS bf16x8*)(lds + PG8_SB(b, h) + boff + n * 2048 + k * 1024); } while (0)
; #define PG8_MMA(ai, bj, At, Bt) do { __builtin_amdgcn_s_setprio(1); _Pragma("unroll") for (int m = 0; m < 4; ++m) _Pragma("unroll") for (int n = 0; n < 2; ++n) _Pragma("unroll") for (int k = 0; k < 2; ++k) \
;         acc[ai][bj][m][n] = __builtin_amdgcn_mfma_f32_16x16x32_bf16(Bt[n][k], At[m][k], acc[ai][bj][m][n], 0, 0, 0); __builtin_amdgcn_s_setprio(0); } while (0)
; #define PG8_WAIT_V(n) asm volatile("s_waitcnt vmcnt(" #n ")" ::: "memory")
; #define PG8_WAIT_L(n) asm volatile("s_waitcnt lgkmcnt(" #n ")" ::: "memory")
; #define PG8_BAR __builtin_amdgcn_s_barrier()
; #define PG8_SCHED __builtin_amdgcn_sched_barrier(0)
; template <class Epi, class Sched, bool ALIGN_EPI = false, bool SP2 = false>
; __device__ __forceinline__ void gemm_phase(PG8_LAS unsigned char* lds, const Gemm g, const Sched& S, const Epi& E) {
;     ...
;             PG8_WAIT_V(8); PG8_WAIT_L(0); PG8_BAR; PG8_MMA(1, 0, At, B0); PG8_MMA(1, 1, At, B1); PG8_BAR; PG8_SCHED;
;             PG8_LDB(B0, 1, 0); PG8_LDB(B1, 1, 1); PG8_SCHED; PG8_LDA(At, 1, 0); PG8_STAGE(PG8_SA(0, 1), a2 + hstep, voffA);
;             PG8_WAIT_V(8); PG8_WAIT_L(0); PG8_BAR; PG8_MMA(0, 0, At, B0); PG8_MMA(0, 1, At, B1); PG8_BAR; PG8_SCHED;
	v_mfma_f32_16x16x32_bf16 v[62:65], v[66:69], v[162:165], 0
	v_mfma_f32_16x16x32_bf16 v[46:49], v[66:69], v[170:173], 0
	v_mfma_f32_16x16x32_bf16 v[30:33], v[66:69], v[178:181], 0
	v_mfma_f32_16x16x32_bf16 v[14:17], v[66:69], v[216:219], 0
	v_mfma_f32_16x16x32_bf16 v[58:61], v[78:81], v[162:165], 0
	v_mfma_f32_16x16x32_bf16 v[42:45], v[78:81], v[170:173], 0
	v_mfma_f32_16x16x32_bf16 v[26:29], v[78:81], v[178:181], 0
	v_mfma_f32_16x16x32_bf16 v[10:13], v[78:81], v[216:219], 0
	v_mfma_f32_16x16x32_bf16 v[62:65], v[70:73], v[166:169], v[62:65]
	v_mfma_f32_16x16x32_bf16 v[46:49], v[70:73], v[174:177], v[46:49]
	v_mfma_f32_16x16x32_bf16 v[30:33], v[70:73], v[182:185], v[30:33]
	v_mfma_f32_16x16x32_bf16 v[14:17], v[70:73], v[220:223], v[14:17]
	v_mfma_f32_16x16x32_bf16 v[58:61], v[86:89], v[166:169], v[58:61]
	v_mfma_f32_16x16x32_bf16 v[42:45], v[86:89], v[174:177], v[42:45]
	v_mfma_f32_16x16x32_bf16 v[26:29], v[86:89], v[182:185], v[26:29]
	v_mfma_f32_16x16x32_bf16 v[10:13], v[86:89], v[220:223], v[10:13]
	v_mfma_f32_16x16x32_bf16 v[54:57], v[146:149], v[162:165], 0
	v_mfma_f32_16x16x32_bf16 v[38:41], v[146:149], v[170:173], 0
	v_mfma_f32_16x16x32_bf16 v[22:25], v[146:149], v[178:181], 0
	v_mfma_f32_16x16x32_bf16 v[6:9], v[146:149], v[216:219], 0
	v_mfma_f32_16x16x32_bf16 v[50:53], v[154:157], v[162:165], 0
	v_mfma_f32_16x16x32_bf16 v[34:37], v[154:157], v[170:173], 0
	v_mfma_f32_16x16x32_bf16 v[18:21], v[154:157], v[178:181], 0
	v_mfma_f32_16x16x32_bf16 v[2:5], v[154:157], v[216:219], 0
	v_mfma_f32_16x16x32_bf16 v[54:57], v[150:153], v[166:169], v[54:57]
	v_mfma_f32_16x16x32_bf16 v[38:41], v[150:153], v[174:177], v[38:41]
	v_mfma_f32_16x16x32_bf16 v[22:25], v[150:153], v[182:185], v[22:25]
	v_mfma_f32_16x16x32_bf16 v[6:9], v[150:153], v[220:223], v[6:9]
	v_mfma_f32_16x16x32_bf16 v[50:53], v[158:161], v[166:169], v[50:53]
	v_mfma_f32_16x16x32_bf16 v[34:37], v[158:161], v[174:177], v[34:37]
	v_mfma_f32_16x16x32_bf16 v[18:21], v[158:161], v[182:185], v[18:21]
	v_mfma_f32_16x16x32_bf16 v[2:5], v[158:161], v[220:223], v[2:5]
	s_barrier
	s_add_i32 s9, 0, 0x18000
	s_add_i32 s12, 0, 0x1c000
	ds_read_b128 v[66:69], v198
	ds_read_b128 v[70:73], v198 offset:1024
	ds_read_b128 v[78:81], v198 offset:2048
	ds_read_b128 v[86:89], v198 offset:3072
	ds_read_b128 v[146:149], v199
	ds_read_b128 v[150:153], v199 offset:1024
	ds_read_b128 v[154:157], v199 offset:2048
	ds_read_b128 v[158:161], v199 offset:3072
	s_add_u32 s10, s94, 0x80000
	s_addc_u32 s11, s95, 0
	s_mov_b32 m0, s59
	ds_read_b128 v[162:165], v236 offset:32768
	ds_read_b128 v[166:169], v236 offset:33792
	ds_read_b128 v[170:173], v236 offset:34816
	ds_read_b128 v[174:177], v236 offset:35840
	ds_read_b128 v[178:181], v236 offset:36864
	ds_read_b128 v[182:185], v236 offset:37888
	ds_read_b128 v[216:219], v236 offset:38912
	ds_read_b128 v[220:223], v236 offset:39936
	global_load_lds_dwordx4 v210, s[10:11]
	s_mov_b32 m0, s74
	s_nop 0
	global_load_lds_dwordx4 v208, s[10:11]
	s_waitcnt vmcnt(8)
	s_waitcnt lgkmcnt(0)
	s_barrier
	v_mfma_f32_16x16x32_bf16 v[142:145], v[66:69], v[162:165], v[142:145]
	v_mfma_f32_16x16x32_bf16 v[126:129], v[66:69], v[170:173], v[126:129]
	v_mfma_f32_16x16x32_bf16 v[110:113], v[66:69], v[178:181], v[110:113]
	v_mfma_f32_16x16x32_bf16 v[94:97], v[66:69], v[216:219], v[94:97]
	v_mfma_f32_16x16x32_bf16 v[138:141], v[78:81], v[162:165], v[138:141]
	v_mfma_f32_16x16x32_bf16 v[122:125], v[78:81], v[170:173], v[122:125]
	v_mfma_f32_16x16x32_bf16 v[106:109], v[78:81], v[178:181], v[106:109]
	v_mfma_f32_16x16x32_bf16 v[90:93], v[78:81], v[216:219], v[90:93]
	v_mfma_f32_16x16x32_bf16 v[142:145], v[70:73], v[166:169], v[142:145]
	v_mfma_f32_16x16x32_bf16 v[126:129], v[70:73], v[174:177], v[126:129]
	v_mfma_f32_16x16x32_bf16 v[110:113], v[70:73], v[182:185], v[110:113]
	v_mfma_f32_16x16x32_bf16 v[94:97], v[70:73], v[220:223], v[94:97]
	v_mfma_f32_16x16x32_bf16 v[138:141], v[86:89], v[166:169], v[138:141]
	v_mfma_f32_16x16x32_bf16 v[122:125], v[86:89], v[174:177], v[122:125]
	v_mfma_f32_16x16x32_bf16 v[106:109], v[86:89], v[182:185], v[106:109]
	v_mfma_f32_16x16x32_bf16 v[90:93], v[86:89], v[220:223], v[90:93]
	v_mfma_f32_16x16x32_bf16 v[134:137], v[146:149], v[162:165], v[134:137]
	v_mfma_f32_16x16x32_bf16 v[118:121], v[146:149], v[170:173], v[118:121]
	v_mfma_f32_16x16x32_bf16 v[102:105], v[146:149], v[178:181], v[102:105]
	v_mfma_f32_16x16x32_bf16 v[82:85], v[146:149], v[216:219], v[82:85]
	v_mfma_f32_16x16x32_bf16 v[130:133], v[154:157], v[162:165], v[130:133]
	v_mfma_f32_16x16x32_bf16 v[114:117], v[154:157], v[170:173], v[114:117]
	v_mfma_f32_16x16x32_bf16 v[98:101], v[154:157], v[178:181], v[98:101]
	v_mfma_f32_16x16x32_bf16 v[74:77], v[154:157], v[216:219], v[74:77]
	v_mfma_f32_16x16x32_bf16 v[134:137], v[150:153], v[166:169], v[134:137]
	v_mfma_f32_16x16x32_bf16 v[118:121], v[150:153], v[174:177], v[118:121]
	v_mfma_f32_16x16x32_bf16 v[102:105], v[150:153], v[182:185], v[102:105]
	v_mfma_f32_16x16x32_bf16 v[82:85], v[150:153], v[220:223], v[82:85]
	v_mfma_f32_16x16x32_bf16 v[130:133], v[158:161], v[166:169], v[130:133]
	v_mfma_f32_16x16x32_bf16 v[114:117], v[158:161], v[174:177], v[114:117]
	v_mfma_f32_16x16x32_bf16 v[98:101], v[158:161], v[182:185], v[98:101]
	v_mfma_f32_16x16x32_bf16 v[74:77], v[158:161], v[220:223], v[74:77]
	s_barrier
; #define PG8_STAGE(bufoff, gbase, voff) do { _Pragma("unroll") for (int _i = 0; _i < 2; ++_i) \
;         __builtin_amdgcn_global_load_lds((const unsigned*)((const char*)(gbase) + (voff)[_i]), (PG8_LAS unsigned*)(lds + (bufoff) + ldsw + _i * 8192), 16, 0, 0); } while (0)
; #define PG8_LDA(dst, b, h) do { _Pragma("unroll") for (int m = 0; m < 4; ++m) _Pragma("unroll") for (int k = 0; k < 2; ++k) dst[m][k] = *(const PG8_LAS bf16x8*)(lds + PG8_SA(b, h) + aoff + m * 2048 + k * 1024); } while (0)
; #define PG8_LDB(dst, b, h) do { _Pragma("unroll") for (int n = 0; n < 2; ++n) _Pragma("unroll") for (int k = 0; k < 2; ++k) dst[n][k] = *(const PG8_LAS bf16x8*)(lds + PG8_SB(b, h) + boff + n * 2048 + k * 1024); } while (0)
; #define PG8_MMA(ai, bj, At, Bt) do { __builtin_amdgcn_s_setprio(1); _Pragma("unroll") for (int m = 0; m < 4; ++m) _Pragma("unroll") for (int n = 0; n < 2; ++n) _Pragma("unroll") for (int k = 0; k < 2; ++k) \
;         acc[ai][bj][m][n] = __builtin_amdgcn_mfma_f32_16x16x32_bf16(Bt[n][k], At[m][k], acc[ai][bj][m][n], 0, 0, 0); __builtin_amdgcn_s_setprio(0); } while (0)
; #define PG8_WAIT_V(n) asm volatile("s_waitcnt vmcnt(" #n ")" ::: "memory")
; template <class Epi, class Sched, bool ALIGN_EPI = false, bool SP2 = false>
; __device__ __forceinline__ void gemm_phase(PG8_LAS unsigned char* lds, const Gemm g, const Sched& S, const Epi& E) {
;     ...
;             PG8_LDB(B0, 0, 0); PG8_LDB(B1, 0, 1); PG8_SCHED; PG8_LDA(At, 0, 0); PG8_STAGE(PG8_SA(1, 1), a1 + hstep, voffA);
;             PG8_WAIT_V(8); PG8_WAIT_L(0); PG8_BAR; PG8_MMA(0, 0, At, B0); PG8_MMA(0, 1, At, B1); PG8_BAR; PG8_SCHED;
;             PG8_LDA(At, 0, 1); PG8_STAGE(PG8_SB(0, 0), b2, voffB); PG8_STAGE(PG8_SB(0, 1), b2 + hstepB, voffB); PG8_STAGE(PG8_SA(0, 0), a2, voffA);
;             PG8_WAIT_V(8); PG8_WAIT_L(0); PG8_BAR; PG8_MMA(1, 0, At, B0); PG8_MMA(1, 1, At, B1); PG8_BAR; PG8_SCHED;
;             PG8_LDB(B0, 1, 0); PG8_LDB(B1, 1, 1); PG8_SCHED; PG8_LDA(At, 1, 0); PG8_STAGE(PG8_SA(0, 1), a2 + hstep, voffA);
;             PG8_WAIT_V(8); PG8_WAIT_L(0); PG8_BAR; PG8_MMA(0, 0, At, B0); PG8_MMA(0, 1, At, B1); PG8_BAR; PG8_SCHED;
;             PG8_LDA(At, 1, 1); PG8_STAGE(PG8_SB(1, 0), b3, voffB); PG8_STAGE(PG8_SB(1, 1), b3 + hstepB, voffB); PG8_STAGE(PG8_SA(1, 0), a3, voffA);
;             PG8_WAIT_V(8); PG8_WAIT_L(0); PG8_BAR; PG8_MMA(1, 0, At, B0); PG8_MMA(1, 1, At, B1); PG8_BAR; PG8_SCHED;
	s_add_i32 s9, s9, s25
	s_mov_b32 m0, s9
	ds_read_b128 v[162:165], v236 offset:49152
	ds_read_b128 v[166:169], v236 offset:50176
	ds_read_b128 v[170:173], v236 offset:51200
	ds_read_b128 v[174:177], v236 offset:52224
	ds_read_b128 v[178:181], v236 offset:53248
	ds_read_b128 v[182:185], v236 offset:54272
	ds_read_b128 v[216:219], v236 offset:55296
	ds_read_b128 v[220:223], v236 offset:56320
	s_add_u32 s100, s46, s60
	s_addc_u32 s101, s47, s61
	global_load_lds_dwordx4 v190, s[100:101]
	s_add_i32 m0, s9, 0x2000
	s_add_u32 s10, s46, 0x20080
	s_addc_u32 s11, s47, 0
	s_add_i32 s9, s12, s25
	global_load_lds_dwordx4 v206, s[100:101]
	s_mov_b32 m0, s9
	s_nop 0
	global_load_lds_dwordx4 v190, s[10:11]
	s_add_i32 m0, s9, 0x2000
	s_nop 0
	global_load_lds_dwordx4 v206, s[10:11]
	s_mov_b32 m0, s75
	s_add_u32 s100, s94, s60
	s_addc_u32 s101, s95, s61
	global_load_lds_dwordx4 v210, s[100:101]
	s_mov_b32 m0, s0
	s_nop 0
	global_load_lds_dwordx4 v208, s[100:101]
	s_waitcnt vmcnt(8)
	s_waitcnt lgkmcnt(0)
	s_barrier
	v_mfma_f32_16x16x32_bf16 v[62:65], v[66:69], v[162:165], v[62:65]
	v_mfma_f32_16x16x32_bf16 v[46:49], v[66:69], v[170:173], v[46:49]
	v_mfma_f32_16x16x32_bf16 v[30:33], v[66:69], v[178:181], v[30:33]
	v_mfma_f32_16x16x32_bf16 v[14:17], v[66:69], v[216:219], v[14:17]
	v_mfma_f32_16x16x32_bf16 v[58:61], v[78:81], v[162:165], v[58:61]
	v_mfma_f32_16x16x32_bf16 v[42:45], v[78:81], v[170:173], v[42:45]
	v_mfma_f32_16x16x32_bf16 v[26:29], v[78:81], v[178:181], v[26:29]
	v_mfma_f32_16x16x32_bf16 v[10:13], v[78:81], v[216:219], v[10:13]
	v_mfma_f32_16x16x32_bf16 v[62:65], v[70:73], v[166:169], v[62:65]
	v_mfma_f32_16x16x32_bf16 v[46:49], v[70:73], v[174:177], v[46:49]
	v_mfma_f32_16x16x32_bf16 v[30:33], v[70:73], v[182:185], v[30:33]
	v_mfma_f32_16x16x32_bf16 v[14:17], v[70:73], v[220:223], v[14:17]
	v_mfma_f32_16x16x32_bf16 v[58:61], v[86:89], v[166:169], v[58:61]
	v_mfma_f32_16x16x32_bf16 v[42:45], v[86:89], v[174:177], v[42:45]
	v_mfma_f32_16x16x32_bf16 v[26:29], v[86:89], v[182:185], v[26:29]
	v_mfma_f32_16x16x32_bf16 v[10:13], v[86:89], v[220:223], v[10:13]
	v_mfma_f32_16x16x32_bf16 v[54:57], v[146:149], v[162:165], v[54:57]
	v_mfma_f32_16x16x32_bf16 v[38:41], v[146:149], v[170:173], v[38:41]
	v_mfma_f32_16x16x32_bf16 v[22:25], v[146:149], v[178:181], v[22:25]
	v_mfma_f32_16x16x32_bf16 v[6:9], v[146:149], v[216:219], v[6:9]
	v_mfma_f32_16x16x32_bf16 v[50:53], v[154:157], v[162:165], v[50:53]
	v_mfma_f32_16x16x32_bf16 v[34:37], v[154:157], v[170:173], v[34:37]
	v_mfma_f32_16x16x32_bf16 v[18:21], v[154:157], v[178:181], v[18:21]
	v_mfma_f32_16x16x32_bf16 v[2:5], v[154:157], v[216:219], v[2:5]
	v_mfma_f32_16x16x32_bf16 v[54:57], v[150:153], v[166:169], v[54:57]
	v_mfma_f32_16x16x32_bf16 v[38:41], v[150:153], v[174:177], v[38:41]
	v_mfma_f32_16x16x32_bf16 v[22:25], v[150:153], v[182:185], v[22:25]
	v_mfma_f32_16x16x32_bf16 v[6:9], v[150:153], v[220:223], v[6:9]
	v_mfma_f32_16x16x32_bf16 v[50:53], v[158:161], v[166:169], v[50:53]
	v_mfma_f32_16x16x32_bf16 v[34:37], v[158:161], v[174:177], v[34:37]
	v_mfma_f32_16x16x32_bf16 v[18:21], v[158:161], v[182:185], v[18:21]
	v_mfma_f32_16x16x32_bf16 v[2:5], v[158:161], v[220:223], v[2:5]
	s_barrier
	s_add_i32 s8, s8, 2
	s_add_u32 s38, s38, 0x100
	s_addc_u32 s39, s39, 0
	s_add_u32 s6, s6, 0x100
	s_addc_u32 s7, s7, 0
	s_cmp_gt_u32 s8, 29
.LBB0_927:
	s_add_u32 s9, s38, 0xfff80080
	s_addc_u32 s10, s39, -1
	s_add_i32 s11, 0, 0x10000
	s_cmp_eq_u32 s8, 28
	s_cselect_b32 s95, s36, s10
	s_cselect_b32 s94, s37, s9
	s_cselect_b32 s47, s4, s7
	s_cselect_b32 s46, s5, s6
	s_add_i32 s9, 0, 0x14000
	ds_read_b128 v[66:69], v186
	ds_read_b128 v[70:73], v186 offset:1024
	ds_read_b128 v[78:81], v186 offset:2048
	ds_read_b128 v[86:89], v186 offset:3072
	ds_read_b128 v[146:149], v187
	ds_read_b128 v[150:153], v187 offset:1024
	ds_read_b128 v[154:157], v187 offset:2048
	ds_read_b128 v[158:161], v187 offset:3072
	s_add_i32 m0, s66, 0xc000
	ds_read_b128 v[162:165], v236
	ds_read_b128 v[166:169], v236 offset:1024
	ds_read_b128 v[170:173], v236 offset:2048
	ds_read_b128 v[174:177], v236 offset:3072
	ds_read_b128 v[178:181], v236 offset:4096
	ds_read_b128 v[182:185], v236 offset:5120
	ds_read_b128 v[216:219], v236 offset:6144
	ds_read_b128 v[220:223], v236 offset:7168
	global_load_lds_dwordx4 v212, s[38:39]
	s_add_i32 m0, s66, 0xe000
	s_nop 0
	global_load_lds_dwordx4 v214, s[38:39]
	s_waitcnt vmcnt(8)
	s_waitcnt lgkmcnt(0)
	s_barrier
	v_mfma_f32_16x16x32_bf16 v[142:145], v[66:69], v[162:165], v[142:145]
	v_mfma_f32_16x16x32_bf16 v[126:129], v[66:69], v[170:173], v[126:129]
	v_mfma_f32_16x16x32_bf16 v[110:113], v[66:69], v[178:181], v[110:113]
	v_mfma_f32_16x16x32_bf16 v[94:97], v[66:69], v[216:219], v[94:97]
	v_mfma_f32_16x16x32_bf16 v[138:141], v[78:81], v[162:165], v[138:141]
	v_mfma_f32_16x16x32_bf16 v[122:125], v[78:81], v[170:173], v[122:125]
	v_mfma_f32_16x16x32_bf16 v[106:109], v[78:81], v[178:181], v[106:109]
	v_mfma_f32_16x16x32_bf16 v[90:93], v[78:81], v[216:219], v[90:93]
	v_mfma_f32_16x16x32_bf16 v[142:145], v[70:73], v[166:169], v[142:145]
	v_mfma_f32_16x16x32_bf16 v[126:129], v[70:73], v[174:177], v[126:129]
	v_mfma_f32_16x16x32_bf16 v[110:113], v[70:73], v[182:185], v[110:113]
	v_mfma_f32_16x16x32_bf16 v[94:97], v[70:73], v[220:223], v[94:97]
	v_mfma_f32_16x16x32_bf16 v[138:141], v[86:89], v[166:169], v[138:141]
	v_mfma_f32_16x16x32_bf16 v[122:125], v[86:89], v[174:177], v[122:125]
	v_mfma_f32_16x16x32_bf16 v[106:109], v[86:89], v[182:185], v[106:109]
	v_mfma_f32_16x16x32_bf16 v[90:93], v[86:89], v[220:223], v[90:93]
	v_mfma_f32_16x16x32_bf16 v[134:137], v[146:149], v[162:165], v[134:137]
	v_mfma_f32_16x16x32_bf16 v[118:121], v[146:149], v[170:173], v[118:121]
	v_mfma_f32_16x16x32_bf16 v[102:105], v[146:149], v[178:181], v[102:105]
	v_mfma_f32_16x16x32_bf16 v[82:85], v[146:149], v[216:219], v[82:85]
	v_mfma_f32_16x16x32_bf16 v[130:133], v[154:157], v[162:165], v[130:133]
	v_mfma_f32_16x16x32_bf16 v[114:117], v[154:157], v[170:173], v[114:117]
	v_mfma_f32_16x16x32_bf16 v[98:101], v[154:157], v[178:181], v[98:101]
	v_mfma_f32_16x16x32_bf16 v[74:77], v[154:157], v[216:219], v[74:77]
	v_mfma_f32_16x16x32_bf16 v[134:137], v[150:153], v[166:169], v[134:137]
	v_mfma_f32_16x16x32_bf16 v[118:121], v[150:153], v[174:177], v[118:121]
	v_mfma_f32_16x16x32_bf16 v[102:105], v[150:153], v[182:185], v[102:105]
	v_mfma_f32_16x16x32_bf16 v[82:85], v[150:153], v[220:223], v[82:85]
	v_mfma_f32_16x16x32_bf16 v[130:133], v[158:161], v[166:169], v[130:133]
	v_mfma_f32_16x16x32_bf16 v[114:117], v[158:161], v[174:177], v[114:117]
	v_mfma_f32_16x16x32_bf16 v[98:101], v[158:161], v[182:185], v[98:101]
	v_mfma_f32_16x16x32_bf16 v[74:77], v[158:161], v[220:223], v[74:77]
	s_barrier
; #define PG8_STAGE(bufoff, gbase, voff) do { _Pragma("unroll") for (int _i = 0; _i < 2; ++_i) \
;         __builtin_amdgcn_global_load_lds((const unsigned*)((const char*)(gbase) + (voff)[_i]), (PG8_LAS unsigned*)(lds + (bufoff) + ldsw + _i * 8192), 16, 0, 0); } while (0)
; #define PG8_LDA(dst, b, h) do { _Pragma("unroll") for (int m = 0; m < 4; ++m) _Pragma("unroll") for (int k = 0; k < 2; ++k) dst[m][k] = *(const PG8_LAS bf16x8*)(lds + PG8_SA(b, h) + aoff + m * 2048 + k * 1024); } while (0)
; #define PG8_LDB(dst, b, h) do { _Pragma("unroll") for (int n = 0; n < 2; ++n) _Pragma("unroll") for (int k = 0; k < 2; ++k) dst[n][k] = *(const PG8_LAS bf16x8*)(lds + PG8_SB(b, h) + boff + n * 2048 + k * 1024); } while (0)
; #define PG8_MMA(ai, bj, At, Bt) do { __builtin_amdgcn_s_setprio(1); _Pragma("unroll") for (int m = 0; m < 4; ++m) _Pragma("unroll") for (int n = 0; n < 2; ++n) _Pragma("unroll") for (int k = 0; k < 2; ++k) \
;         acc[ai][bj][m][n] = __builtin_amdgcn_mfma_f32_16x16x32_bf16(Bt[n][k], At[m][k], acc[ai][bj][m][n], 0, 0, 0); __builtin_amdgcn_s_setprio(0); } while (0)
; #define PG8_WAIT_V(n) asm volatile("s_waitcnt vmcnt(" #n ")" ::: "memory")
; #define PG8_WAIT_L(n) asm volatile("s_waitcnt lgkmcnt(" #n ")" ::: "memory")
; #define PG8_BAR __builtin_amdgcn_s_barrier()
; #define PG8_SCHED __builtin_amdgcn_sched_barrier(0)
; template <class Epi, class Sched, bool ALIGN_EPI = false, bool SP2 = false>
; __device__ __forceinline__ void gemm_phase(PG8_LAS unsigned char* lds, const Gemm g, const Sched& S, const Epi& E) {
;     ...
;             PG8_LDA(At, 0, 1); PG8_STAGE(PG8_SB(0, 0), b2, voffB); PG8_STAGE(PG8_SB(0, 1), b2 + hstepB, voffB); PG8_STAGE(PG8_SA(0, 0), a2, voffA);
;             PG8_WAIT_V(8); PG8_WAIT_L(0); PG8_BAR; PG8_MMA(1, 0, At, B0); PG8_MMA(1, 1, At, B1); PG8_BAR; PG8_SCHED;
;             PG8_LDB(B0, 1, 0); PG8_LDB(B1, 1, 1); PG8_SCHED; PG8_LDA(At, 1, 0); PG8_STAGE(PG8_SA(0, 1), a2 + hstep, voffA);
	s_add_i32 s10, s11, s25
	s_mov_b32 m0, s10
	ds_read_b128 v[162:165], v236 offset:16384
	ds_read_b128 v[166:169], v236 offset:17408
	ds_read_b128 v[170:173], v236 offset:18432
	ds_read_b128 v[174:177], v236 offset:19456
	ds_read_b128 v[178:181], v236 offset:20480
	ds_read_b128 v[182:185], v236 offset:21504
	ds_read_b128 v[216:219], v236 offset:22528
	ds_read_b128 v[220:223], v236 offset:23552
	global_load_lds_dwordx4 v190, s[46:47]
	s_add_i32 m0, s10, 0x2000
	s_add_u32 s10, s46, 0x20000
	s_addc_u32 s11, s47, 0
	s_add_i32 s9, s9, s25
	global_load_lds_dwordx4 v206, s[46:47]
	s_mov_b32 m0, s9
	s_nop 0
	global_load_lds_dwordx4 v190, s[10:11]
	s_add_i32 m0, s9, 0x2000
	s_nop 0
	global_load_lds_dwordx4 v206, s[10:11]
	s_mov_b32 m0, s66
	s_nop 0
	global_load_lds_dwordx4 v210, s[94:95]
	s_mov_b32 m0, s67
	s_nop 0
	global_load_lds_dwordx4 v208, s[94:95]
	s_waitcnt vmcnt(8)
	s_waitcnt lgkmcnt(0)
	s_barrier
	v_mfma_f32_16x16x32_bf16 v[62:65], v[66:69], v[162:165], v[62:65]
	v_mfma_f32_16x16x32_bf16 v[46:49], v[66:69], v[170:173], v[46:49]
	v_mfma_f32_16x16x32_bf16 v[30:33], v[66:69], v[178:181], v[30:33]
	v_mfma_f32_16x16x32_bf16 v[14:17], v[66:69], v[216:219], v[14:17]
	v_mfma_f32_16x16x32_bf16 v[58:61], v[78:81], v[162:165], v[58:61]
	v_mfma_f32_16x16x32_bf16 v[42:45], v[78:81], v[170:173], v[42:45]
	v_mfma_f32_16x16x32_bf16 v[26:29], v[78:81], v[178:181], v[26:29]
	v_mfma_f32_16x16x32_bf16 v[10:13], v[78:81], v[216:219], v[10:13]
	v_mfma_f32_16x16x32_bf16 v[62:65], v[70:73], v[166:169], v[62:65]
	v_mfma_f32_16x16x32_bf16 v[46:49], v[70:73], v[174:177], v[46:49]
	v_mfma_f32_16x16x32_bf16 v[30:33], v[70:73], v[182:185], v[30:33]
	v_mfma_f32_16x16x32_bf16 v[14:17], v[70:73], v[220:223], v[14:17]
	v_mfma_f32_16x16x32_bf16 v[58:61], v[86:89], v[166:169], v[58:61]
	v_mfma_f32_16x16x32_bf16 v[42:45], v[86:89], v[174:177], v[42:45]
	v_mfma_f32_16x16x32_bf16 v[26:29], v[86:89], v[182:185], v[26:29]
	v_mfma_f32_16x16x32_bf16 v[10:13], v[86:89], v[220:223], v[10:13]
	v_mfma_f32_16x16x32_bf16 v[54:57], v[146:149], v[162:165], v[54:57]
	v_mfma_f32_16x16x32_bf16 v[38:41], v[146:149], v[170:173], v[38:41]
	v_mfma_f32_16x16x32_bf16 v[22:25], v[146:149], v[178:181], v[22:25]
	v_mfma_f32_16x16x32_bf16 v[6:9], v[146:149], v[216:219], v[6:9]
	v_mfma_f32_16x16x32_bf16 v[50:53], v[154:157], v[162:165], v[50:53]
	v_mfma_f32_16x16x32_bf16 v[34:37], v[154:157], v[170:173], v[34:37]
	v_mfma_f32_16x16x32_bf16 v[18:21], v[154:157], v[178:181], v[18:21]
	v_mfma_f32_16x16x32_bf16 v[2:5], v[154:157], v[216:219], v[2:5]
	v_mfma_f32_16x16x32_bf16 v[54:57], v[150:153], v[166:169], v[54:57]
	v_mfma_f32_16x16x32_bf16 v[38:41], v[150:153], v[174:177], v[38:41]
	v_mfma_f32_16x16x32_bf16 v[22:25], v[150:153], v[182:185], v[22:25]
	v_mfma_f32_16x16x32_bf16 v[6:9], v[150:153], v[220:223], v[6:9]
	v_mfma_f32_16x16x32_bf16 v[50:53], v[158:161], v[166:169], v[50:53]
	v_mfma_f32_16x16x32_bf16 v[34:37], v[158:161], v[174:177], v[34:37]
	v_mfma_f32_16x16x32_bf16 v[18:21], v[158:161], v[182:185], v[18:21]
	v_mfma_f32_16x16x32_bf16 v[2:5], v[158:161], v[220:223], v[2:5]
	s_barrier
	s_add_i32 s9, 0, 0x18000
	s_add_i32 s12, 0, 0x1c000
	ds_read_b128 v[66:69], v198
	ds_read_b128 v[70:73], v198 offset:1024
	ds_read_b128 v[78:81], v198 offset:2048
	ds_read_b128 v[86:89], v198 offset:3072
	ds_read_b128 v[146:149], v199
	ds_read_b128 v[150:153], v199 offset:1024
	ds_read_b128 v[154:157], v199 offset:2048
	ds_read_b128 v[158:161], v199 offset:3072
	s_add_u32 s10, s94, 0x80000
	s_addc_u32 s11, s95, 0
	s_mov_b32 m0, s59
	ds_read_b128 v[162:165], v236 offset:32768
	ds_read_b128 v[166:169], v236 offset:33792
	ds_read_b128 v[170:173], v236 offset:34816
	ds_read_b128 v[174:177], v236 offset:35840
	ds_read_b128 v[178:181], v236 offset:36864
	ds_read_b128 v[182:185], v236 offset:37888
	ds_read_b128 v[216:219], v236 offset:38912
	ds_read_b128 v[220:223], v236 offset:39936
	global_load_lds_dwordx4 v210, s[10:11]
	s_mov_b32 m0, s74
	s_nop 0
	global_load_lds_dwordx4 v208, s[10:11]
	s_waitcnt vmcnt(8)
	s_waitcnt lgkmcnt(0)
	s_barrier
; #define PG8_STAGE(bufoff, gbase, voff) do { _Pragma("unroll") for (int _i = 0; _i < 2; ++_i) \
;         __builtin_amdgcn_global_load_lds((const unsigned*)((const char*)(gbase) + (voff)[_i]), (PG8_LAS unsigned*)(lds + (bufoff) + ldsw + _i * 8192), 16, 0, 0); } while (0)
; #define PG8_LDA(dst, b, h) do { _Pragma("unroll") for (int m = 0; m < 4; ++m) _Pragma("unroll") for (int k = 0; k < 2; ++k) dst[m][k] = *(const PG8_LAS bf16x8*)(lds + PG8_SA(b, h) + aoff + m * 2048 + k * 1024); } while (0)
; #define PG8_MMA(ai, bj, At, Bt) do { __builtin_amdgcn_s_setprio(1); _Pragma("unroll") for (int m = 0; m < 4; ++m) _Pragma("unroll") for (int n = 0; n < 2; ++n) _Pragma("unroll") for (int k = 0; k < 2; ++k) \
;         acc[ai][bj][m][n] = __builtin_amdgcn_mfma_f32_16x16x32_bf16(Bt[n][k], At[m][k], acc[ai][bj][m][n], 0, 0, 0); __builtin_amdgcn_s_setprio(0); } while (0)
; #define PG8_WAIT_V(n) asm volatile("s_waitcnt vmcnt(" #n ")" ::: "memory")
; #define PG8_WAIT_L(n) asm volatile("s_waitcnt lgkmcnt(" #n ")" ::: "memory")
; #define PG8_BAR __builtin_amdgcn_s_barrier()
; #define PG8_SCHED __builtin_amdgcn_sched_barrier(0)
; template <class Epi, class Sched, bool ALIGN_EPI = false, bool SP2 = false>
; __device__ __forceinline__ void gemm_phase(PG8_LAS unsigned char* lds, const Gemm g, const Sched& S, const Epi& E) {
;     ...
;             PG8_WAIT_V(8); PG8_WAIT_L(0); PG8_BAR; PG8_MMA(0, 0, At, B0); PG8_MMA(0, 1, At, B1); PG8_BAR; PG8_SCHED;
;             PG8_LDA(At, 1, 1); PG8_STAGE(PG8_SB(1, 0), b3, voffB); PG8_STAGE(PG8_SB(1, 1), b3 + hstepB, voffB); PG8_STAGE(PG8_SA(1, 0), a3, voffA);
;             PG8_WAIT_V(8); PG8_WAIT_L(0); PG8_BAR; PG8_MMA(1, 0, At, B0); PG8_MMA(1, 1, At, B1); PG8_BAR; PG8_SCHED;
;     ...
;         if constexpr (ALIGN_EPI) { if (wr == 0) PG8_BAR; }
	v_mfma_f32_16x16x32_bf16 v[142:145], v[66:69], v[162:165], v[142:145]
	v_mfma_f32_16x16x32_bf16 v[126:129], v[66:69], v[170:173], v[126:129]
	v_mfma_f32_16x16x32_bf16 v[110:113], v[66:69], v[178:181], v[110:113]
	v_mfma_f32_16x16x32_bf16 v[94:97], v[66:69], v[216:219], v[94:97]
	v_mfma_f32_16x16x32_bf16 v[138:141], v[78:81], v[162:165], v[138:141]
	v_mfma_f32_16x16x32_bf16 v[122:125], v[78:81], v[170:173], v[122:125]
	v_mfma_f32_16x16x32_bf16 v[106:109], v[78:81], v[178:181], v[106:109]
	v_mfma_f32_16x16x32_bf16 v[90:93], v[78:81], v[216:219], v[90:93]
	v_mfma_f32_16x16x32_bf16 v[142:145], v[70:73], v[166:169], v[142:145]
	v_mfma_f32_16x16x32_bf16 v[126:129], v[70:73], v[174:177], v[126:129]
	v_mfma_f32_16x16x32_bf16 v[110:113], v[70:73], v[182:185], v[110:113]
	v_mfma_f32_16x16x32_bf16 v[94:97], v[70:73], v[220:223], v[94:97]
	v_mfma_f32_16x16x32_bf16 v[138:141], v[86:89], v[166:169], v[138:141]
	v_mfma_f32_16x16x32_bf16 v[122:125], v[86:89], v[174:177], v[122:125]
	v_mfma_f32_16x16x32_bf16 v[106:109], v[86:89], v[182:185], v[106:109]
	v_mfma_f32_16x16x32_bf16 v[90:93], v[86:89], v[220:223], v[90:93]
	v_mfma_f32_16x16x32_bf16 v[134:137], v[146:149], v[162:165], v[134:137]
	v_mfma_f32_16x16x32_bf16 v[118:121], v[146:149], v[170:173], v[118:121]
	v_mfma_f32_16x16x32_bf16 v[102:105], v[146:149], v[178:181], v[102:105]
	v_mfma_f32_16x16x32_bf16 v[82:85], v[146:149], v[216:219], v[82:85]
	v_mfma_f32_16x16x32_bf16 v[130:133], v[154:157], v[162:165], v[130:133]
	v_mfma_f32_16x16x32_bf16 v[114:117], v[154:157], v[170:173], v[114:117]
	v_mfma_f32_16x16x32_bf16 v[98:101], v[154:157], v[178:181], v[98:101]
	v_mfma_f32_16x16x32_bf16 v[74:77], v[154:157], v[216:219], v[74:77]
	v_mfma_f32_16x16x32_bf16 v[134:137], v[150:153], v[166:169], v[134:137]
	v_mfma_f32_16x16x32_bf16 v[118:121], v[150:153], v[174:177], v[118:121]
	v_mfma_f32_16x16x32_bf16 v[102:105], v[150:153], v[182:185], v[102:105]
	v_mfma_f32_16x16x32_bf16 v[82:85], v[150:153], v[220:223], v[82:85]
	v_mfma_f32_16x16x32_bf16 v[130:133], v[158:161], v[166:169], v[130:133]
	v_mfma_f32_16x16x32_bf16 v[114:117], v[158:161], v[174:177], v[114:117]
	v_mfma_f32_16x16x32_bf16 v[98:101], v[158:161], v[182:185], v[98:101]
	v_mfma_f32_16x16x32_bf16 v[74:77], v[158:161], v[220:223], v[74:77]
	s_barrier
	s_add_i32 s9, s9, s25
	s_mov_b32 m0, s9
	ds_read_b128 v[162:165], v236 offset:49152
	ds_read_b128 v[166:169], v236 offset:50176
	ds_read_b128 v[170:173], v236 offset:51200
	ds_read_b128 v[174:177], v236 offset:52224
	ds_read_b128 v[178:181], v236 offset:53248
	ds_read_b128 v[182:185], v236 offset:54272
	ds_read_b128 v[216:219], v236 offset:55296
	ds_read_b128 v[220:223], v236 offset:56320
	s_add_u32 s100, s46, s60
	s_addc_u32 s101, s47, s61
	global_load_lds_dwordx4 v190, s[100:101]
	s_add_i32 m0, s9, 0x2000
	s_add_u32 s10, s46, 0x20080
	s_addc_u32 s11, s47, 0
	s_add_i32 s9, s12, s25
	global_load_lds_dwordx4 v206, s[100:101]
	s_mov_b32 m0, s9
	s_nop 0
	global_load_lds_dwordx4 v190, s[10:11]
	s_add_i32 m0, s9, 0x2000
	s_nop 0
	global_load_lds_dwordx4 v206, s[10:11]
	s_mov_b32 m0, s75
	s_add_u32 s100, s94, s60
	s_addc_u32 s101, s95, s61
	global_load_lds_dwordx4 v210, s[100:101]
	s_mov_b32 m0, s0
	s_nop 0
	global_load_lds_dwordx4 v208, s[100:101]
	s_waitcnt vmcnt(8)
	s_waitcnt lgkmcnt(0)
	s_barrier
	v_mfma_f32_16x16x32_bf16 v[62:65], v[66:69], v[162:165], v[62:65]
	v_mfma_f32_16x16x32_bf16 v[46:49], v[66:69], v[170:173], v[46:49]
	v_mfma_f32_16x16x32_bf16 v[30:33], v[66:69], v[178:181], v[30:33]
	v_mfma_f32_16x16x32_bf16 v[14:17], v[66:69], v[216:219], v[14:17]
	v_mfma_f32_16x16x32_bf16 v[58:61], v[78:81], v[162:165], v[58:61]
	v_mfma_f32_16x16x32_bf16 v[42:45], v[78:81], v[170:173], v[42:45]
	v_mfma_f32_16x16x32_bf16 v[26:29], v[78:81], v[178:181], v[26:29]
	v_mfma_f32_16x16x32_bf16 v[10:13], v[78:81], v[216:219], v[10:13]
	v_mfma_f32_16x16x32_bf16 v[62:65], v[70:73], v[166:169], v[62:65]
	v_mfma_f32_16x16x32_bf16 v[46:49], v[70:73], v[174:177], v[46:49]
	v_mfma_f32_16x16x32_bf16 v[30:33], v[70:73], v[182:185], v[30:33]
	v_mfma_f32_16x16x32_bf16 v[14:17], v[70:73], v[220:223], v[14:17]
	v_mfma_f32_16x16x32_bf16 v[58:61], v[86:89], v[166:169], v[58:61]
	v_mfma_f32_16x16x32_bf16 v[42:45], v[86:89], v[174:177], v[42:45]
	v_mfma_f32_16x16x32_bf16 v[26:29], v[86:89], v[182:185], v[26:29]
	v_mfma_f32_16x16x32_bf16 v[10:13], v[86:89], v[220:223], v[10:13]
	v_mfma_f32_16x16x32_bf16 v[54:57], v[146:149], v[162:165], v[54:57]
	v_mfma_f32_16x16x32_bf16 v[38:41], v[146:149], v[170:173], v[38:41]
	v_mfma_f32_16x16x32_bf16 v[22:25], v[146:149], v[178:181], v[22:25]
	v_mfma_f32_16x16x32_bf16 v[6:9], v[146:149], v[216:219], v[6:9]
	v_mfma_f32_16x16x32_bf16 v[50:53], v[154:157], v[162:165], v[50:53]
	v_mfma_f32_16x16x32_bf16 v[34:37], v[154:157], v[170:173], v[34:37]
	v_mfma_f32_16x16x32_bf16 v[18:21], v[154:157], v[178:181], v[18:21]
	v_mfma_f32_16x16x32_bf16 v[2:5], v[154:157], v[216:219], v[2:5]
	v_mfma_f32_16x16x32_bf16 v[54:57], v[150:153], v[166:169], v[54:57]
	v_mfma_f32_16x16x32_bf16 v[38:41], v[150:153], v[174:177], v[38:41]
	v_mfma_f32_16x16x32_bf16 v[22:25], v[150:153], v[182:185], v[22:25]
	v_mfma_f32_16x16x32_bf16 v[6:9], v[150:153], v[220:223], v[6:9]
	v_mfma_f32_16x16x32_bf16 v[50:53], v[158:161], v[166:169], v[50:53]
	v_mfma_f32_16x16x32_bf16 v[34:37], v[158:161], v[174:177], v[34:37]
	v_mfma_f32_16x16x32_bf16 v[18:21], v[158:161], v[182:185], v[18:21]
	v_mfma_f32_16x16x32_bf16 v[2:5], v[158:161], v[220:223], v[2:5]
	s_barrier
	s_add_i32 s8, s8, 2
	s_add_u32 s38, s38, 0x100
	s_addc_u32 s39, s39, 0
	s_add_u32 s6, s6, 0x100
	s_addc_u32 s7, s7, 0
	s_cmp_gt_u32 s8, 29
	s_cbranch_scc0 .LBB0_927
	s_and_b64 vcc, exec, s[70:71]
	s_cbranch_vccz .LBB0_930
	s_barrier

; #define PG8_STAGE(bufoff, gbase, voff) do { _Pragma("unroll") for (int _i = 0; _i < 2; ++_i) \
;         __builtin_amdgcn_global_load_lds((const unsigned*)((const char*)(gbase) + (voff)[_i]), (PG8_LAS unsigned*)(lds + (bufoff) + ldsw + _i * 8192), 16, 0, 0); } while (0)
; #define PG8_LDA(dst, b, h) do { _Pragma("unroll") for (int m = 0; m < 4; ++m) _Pragma("unroll") for (int k = 0; k < 2; ++k) dst[m][k] = *(const PG8_LAS bf16x8*)(lds + PG8_SA(b, h) + aoff + m * 2048 + k * 1024); } while (0)
; #define PG8_LDB(dst, b, h) do { _Pragma("unroll") for (int n = 0; n < 2; ++n) _Pragma("unroll") for (int k = 0; k < 2; ++k) dst[n][k] = *(const PG8_LAS bf16x8*)(lds + PG8_SB(b, h) + boff + n * 2048 + k * 1024); } while (0)
; #define PG8_MMA(ai, bj, At, Bt) do { __builtin_amdgcn_s_setprio(1); _Pragma("unroll") for (int m = 0; m < 4; ++m) _Pragma("unroll") for (int n = 0; n < 2; ++n) _Pragma("unroll") for (int k = 0; k < 2; ++k) \
;         acc[ai][bj][m][n] = __builtin_amdgcn_mfma_f32_16x16x32_bf16(Bt[n][k], At[m][k], acc[ai][bj][m][n], 0, 0, 0); __builtin_amdgcn_s_setprio(0); } while (0)
; #define PG8_BAR __builtin_amdgcn_s_barrier()
; template <class Epi, class Sched, bool ALIGN_EPI = false, bool SP2 = false>
; __device__ __forceinline__ void gemm_phase(PG8_LAS unsigned char* lds, const Gemm g, const Sched& S, const Epi& E) {
;     ...
;         const bool has_next = S.next(ui + 1, nxt);
;         const char* nA = has_next ? (const char*)g.A + (size_t)nxt.pm * tstep : cA; const char* nB = has_next ? (const char*)g.Bt + (size_t)nxt.pn * tstep : cB;
;         for (int t = 0; t < nt; t += 2) {
;             const bool last = (t == nt - 2);
;             const char* a1 = cA + (size_t)(t + 1) * kstep;
;             const char* a2 = last ? nA : cA + (size_t)(t + 2) * kstep; const char* b2 = last ? nB : cB + (size_t)(t + 2) * kstep;
;             const char* a3 = a2 + kstep; const char* b3 = b2 + kstep;
;             if (last && has_next) S.a_ready(nxt);
;             if constexpr (SP2) {
;             PG8_LDB(B0, 0, 0); PG8_LDB(B1, 0, 1); PG8_SCHED; PG8_LDA(At, 0, 0); PG8_STAGE(PG8_SA(1, 1), a1 + hstep, voffA);
;             PG8_WAIT_V(8); PG8_WAIT_L(0); PG8_BAR; PG8_MMA(0, 0, At, B0); PG8_MMA(0, 1, At, B1); PG8_BAR; PG8_SCHED;
;             PG8_LDA(At, 0, 1); PG8_STAGE(PG8_SB(0, 0), b2, voffB); PG8_STAGE(PG8_SB(0, 1), b2 + hstepB, voffB); PG8_STAGE(PG8_SA(0, 0), a2, voffA);
.LBB0_1070:
	s_ashr_i32 s97, s96, 31
	s_lshl_b64 s[4:5], s[96:97], 22
	s_add_u32 s26, s0, s4
	s_addc_u32 s27, s1, s5
	s_and_b64 s[4:5], s[92:93], exec
	s_cselect_b32 s97, s27, s39
	s_cselect_b32 s4, s26, s38
	s_ashr_i32 s85, s84, 31
	s_lshl_b64 s[6:7], s[84:85], 22
	s_add_u32 s94, s56, s6
	s_addc_u32 s95, s57, s7
	s_and_b64 s[6:7], s[92:93], exec
	s_cselect_b32 s5, s95, s47
	s_cselect_b32 s6, s94, s46
	s_add_u32 s38, s38, 0x200080
	s_addc_u32 s39, s39, 0
	s_add_u32 s7, s46, 0x100
	s_addc_u32 s8, s47, 0
	s_mov_b32 s9, -2
	s_waitcnt lgkmcnt(0)
	v_add_u32_e32 v186, 0x10000, v164
	v_add_u32_e32 v187, 0x14000, v164
	v_add_u32_e32 v198, 0x18000, v164
	v_add_u32_e32 v199, 0x1c000, v164
	s_add_u32 s10, s38, 0xffe00080
	s_addc_u32 s11, s39, -1
	s_add_i32 s12, 0, 0x10000
	s_cmpk_eq_i32 s9, 0x7c
	s_cselect_b32 vcc_hi, s97, s11
	s_cselect_b32 vcc_lo, s4, s10
	s_cselect_b32 s47, s5, s8
	s_cselect_b32 s46, s6, s7
	s_add_i32 s13, 0, 0x14000
	ds_read_b128 v[130:133], v186
	ds_read_b128 v[134:137], v186 offset:1024
	ds_read_b128 v[138:141], v186 offset:2048
	ds_read_b128 v[152:155], v186 offset:3072
	ds_read_b128 v[156:159], v187
	ds_read_b128 v[160:163], v187 offset:1024
	ds_read_b128 v[168:171], v187 offset:2048
	ds_read_b128 v[172:175], v187 offset:3072
	s_add_i32 m0, s74, 0xc000
	ds_read_b128 v[176:179], v166
	ds_read_b128 v[180:183], v166 offset:1024
	ds_read_b128 v[206:209], v166 offset:2048
	ds_read_b128 v[210:213], v166 offset:3072
	ds_read_b128 v[214:217], v166 offset:4096
	ds_read_b128 v[218:221], v166 offset:5120
	ds_read_b128 v[236:239], v166 offset:6144
	ds_read_b128 v[240:243], v166 offset:7168
	global_load_lds_dwordx4 v148, s[38:39]
	s_add_i32 m0, s74, 0xe000
	s_nop 0
	global_load_lds_dwordx4 v150, s[38:39]
	s_waitcnt vmcnt(8)
	s_waitcnt lgkmcnt(0)
	s_barrier
	v_mfma_f32_16x16x32_bf16 v[126:129], v[130:133], v[176:179], 0
	v_mfma_f32_16x16x32_bf16 v[110:113], v[130:133], v[206:209], 0
	v_mfma_f32_16x16x32_bf16 v[94:97], v[130:133], v[214:217], 0
	v_mfma_f32_16x16x32_bf16 v[78:81], v[130:133], v[236:239], 0
	v_mfma_f32_16x16x32_bf16 v[122:125], v[138:141], v[176:179], 0
	v_mfma_f32_16x16x32_bf16 v[106:109], v[138:141], v[206:209], 0
	v_mfma_f32_16x16x32_bf16 v[90:93], v[138:141], v[214:217], 0
	v_mfma_f32_16x16x32_bf16 v[74:77], v[138:141], v[236:239], 0
	v_mfma_f32_16x16x32_bf16 v[126:129], v[134:137], v[180:183], v[126:129]
	v_mfma_f32_16x16x32_bf16 v[110:113], v[134:137], v[210:213], v[110:113]
	v_mfma_f32_16x16x32_bf16 v[94:97], v[134:137], v[218:221], v[94:97]
	v_mfma_f32_16x16x32_bf16 v[78:81], v[134:137], v[240:243], v[78:81]
	v_mfma_f32_16x16x32_bf16 v[122:125], v[152:155], v[180:183], v[122:125]
	v_mfma_f32_16x16x32_bf16 v[106:109], v[152:155], v[210:213], v[106:109]
	v_mfma_f32_16x16x32_bf16 v[90:93], v[152:155], v[218:221], v[90:93]
	v_mfma_f32_16x16x32_bf16 v[74:77], v[152:155], v[240:243], v[74:77]
	v_mfma_f32_16x16x32_bf16 v[118:121], v[156:159], v[176:179], 0
	v_mfma_f32_16x16x32_bf16 v[102:105], v[156:159], v[206:209], 0
	v_mfma_f32_16x16x32_bf16 v[86:89], v[156:159], v[214:217], 0
	v_mfma_f32_16x16x32_bf16 v[70:73], v[156:159], v[236:239], 0
	v_mfma_f32_16x16x32_bf16 v[114:117], v[168:171], v[176:179], 0
	v_mfma_f32_16x16x32_bf16 v[98:101], v[168:171], v[206:209], 0
	v_mfma_f32_16x16x32_bf16 v[82:85], v[168:171], v[214:217], 0
	v_mfma_f32_16x16x32_bf16 v[66:69], v[168:171], v[236:239], 0
	v_mfma_f32_16x16x32_bf16 v[118:121], v[160:163], v[180:183], v[118:121]
	v_mfma_f32_16x16x32_bf16 v[102:105], v[160:163], v[210:213], v[102:105]
	v_mfma_f32_16x16x32_bf16 v[86:89], v[160:163], v[218:221], v[86:89]
	v_mfma_f32_16x16x32_bf16 v[70:73], v[160:163], v[240:243], v[70:73]
	v_mfma_f32_16x16x32_bf16 v[114:117], v[172:175], v[180:183], v[114:117]
	v_mfma_f32_16x16x32_bf16 v[98:101], v[172:175], v[210:213], v[98:101]
	v_mfma_f32_16x16x32_bf16 v[82:85], v[172:175], v[218:221], v[82:85]
	v_mfma_f32_16x16x32_bf16 v[66:69], v[172:175], v[240:243], v[66:69]
	s_barrier
	s_add_i32 s10, s12, s67
	s_mov_b32 m0, s10
	ds_read_b128 v[176:179], v166 offset:16384
	ds_read_b128 v[180:183], v166 offset:17408
	ds_read_b128 v[206:209], v166 offset:18432
	ds_read_b128 v[210:213], v166 offset:19456
	ds_read_b128 v[214:217], v166 offset:20480
	ds_read_b128 v[218:221], v166 offset:21504
	ds_read_b128 v[236:239], v166 offset:22528
	ds_read_b128 v[240:243], v166 offset:23552
	global_load_lds_dwordx4 v146, s[46:47]
	s_add_i32 m0, s10, 0x2000
	s_add_u32 s10, s46, 0x80000
	s_addc_u32 s11, s47, 0
	s_add_i32 s12, s13, s67
	global_load_lds_dwordx4 v142, s[46:47]
	s_mov_b32 m0, s12
	s_nop 0
	global_load_lds_dwordx4 v146, s[10:11]
	s_add_i32 m0, s12, 0x2000
	s_nop 0
	global_load_lds_dwordx4 v142, s[10:11]
	s_mov_b32 m0, s74
	s_nop 0
	global_load_lds_dwordx4 v190, vcc
	s_mov_b32 m0, s75
	s_nop 0
	global_load_lds_dwordx4 v144, vcc
	s_waitcnt vmcnt(8)
	s_waitcnt lgkmcnt(0)
	s_barrier
; #define PG8_STAGE(bufoff, gbase, voff) do { _Pragma("unroll") for (int _i = 0; _i < 2; ++_i) \
;         __builtin_amdgcn_global_load_lds((const unsigned*)((const char*)(gbase) + (voff)[_i]), (PG8_LAS unsigned*)(lds + (bufoff) + ldsw + _i * 8192), 16, 0, 0); } while (0)
; #define PG8_LDA(dst, b, h) do { _Pragma("unroll") for (int m = 0; m < 4; ++m) _Pragma("unroll") for (int k = 0; k < 2; ++k) dst[m][k] = *(const PG8_LAS bf16x8*)(lds + PG8_SA(b, h) + aoff + m * 2048 + k * 1024); } while (0)
; #define PG8_LDB(dst, b, h) do { _Pragma("unroll") for (int n = 0; n < 2; ++n) _Pragma("unroll") for (int k = 0; k < 2; ++k) dst[n][k] = *(const PG8_LAS bf16x8*)(lds + PG8_SB(b, h) + boff + n * 2048 + k * 1024); } while (0)
; #define PG8_MMA(ai, bj, At, Bt) do { __builtin_amdgcn_s_setprio(1); _Pragma("unroll") for (int m = 0; m < 4; ++m) _Pragma("unroll") for (int n = 0; n < 2; ++n) _Pragma("unroll") for (int k = 0; k < 2; ++k) \
;         acc[ai][bj][m][n] = __builtin_amdgcn_mfma_f32_16x16x32_bf16(Bt[n][k], At[m][k], acc[ai][bj][m][n], 0, 0, 0); __builtin_amdgcn_s_setprio(0); } while (0)
; #define PG8_WAIT_V(n) asm volatile("s_waitcnt vmcnt(" #n ")" ::: "memory")
; #define PG8_WAIT_L(n) asm volatile("s_waitcnt lgkmcnt(" #n ")" ::: "memory")
; #define PG8_BAR __builtin_amdgcn_s_barrier()
; #define PG8_SCHED __builtin_amdgcn_sched_barrier(0)
; template <class Epi, class Sched, bool ALIGN_EPI = false, bool SP2 = false>
; __device__ __forceinline__ void gemm_phase(PG8_LAS unsigned char* lds, const Gemm g, const Sched& S, const Epi& E) {
;     ...
;             PG8_WAIT_V(8); PG8_WAIT_L(0); PG8_BAR; PG8_MMA(1, 0, At, B0); PG8_MMA(1, 1, At, B1); PG8_BAR; PG8_SCHED;
;             PG8_LDB(B0, 1, 0); PG8_LDB(B1, 1, 1); PG8_SCHED; PG8_LDA(At, 1, 0); PG8_STAGE(PG8_SA(0, 1), a2 + hstep, voffA);
;             PG8_WAIT_V(8); PG8_WAIT_L(0); PG8_BAR; PG8_MMA(0, 0, At, B0); PG8_MMA(0, 1, At, B1); PG8_BAR; PG8_SCHED;
	v_mfma_f32_16x16x32_bf16 v[62:65], v[130:133], v[176:179], 0
	v_mfma_f32_16x16x32_bf16 v[46:49], v[130:133], v[206:209], 0
	v_mfma_f32_16x16x32_bf16 v[30:33], v[130:133], v[214:217], 0
	v_mfma_f32_16x16x32_bf16 v[14:17], v[130:133], v[236:239], 0
	v_mfma_f32_16x16x32_bf16 v[58:61], v[138:141], v[176:179], 0
	v_mfma_f32_16x16x32_bf16 v[42:45], v[138:141], v[206:209], 0
	v_mfma_f32_16x16x32_bf16 v[26:29], v[138:141], v[214:217], 0
	v_mfma_f32_16x16x32_bf16 v[10:13], v[138:141], v[236:239], 0
	v_mfma_f32_16x16x32_bf16 v[62:65], v[134:137], v[180:183], v[62:65]
	v_mfma_f32_16x16x32_bf16 v[46:49], v[134:137], v[210:213], v[46:49]
	v_mfma_f32_16x16x32_bf16 v[30:33], v[134:137], v[218:221], v[30:33]
	v_mfma_f32_16x16x32_bf16 v[14:17], v[134:137], v[240:243], v[14:17]
	v_mfma_f32_16x16x32_bf16 v[58:61], v[152:155], v[180:183], v[58:61]
	v_mfma_f32_16x16x32_bf16 v[42:45], v[152:155], v[210:213], v[42:45]
	v_mfma_f32_16x16x32_bf16 v[26:29], v[152:155], v[218:221], v[26:29]
	v_mfma_f32_16x16x32_bf16 v[10:13], v[152:155], v[240:243], v[10:13]
	v_mfma_f32_16x16x32_bf16 v[54:57], v[156:159], v[176:179], 0
	v_mfma_f32_16x16x32_bf16 v[38:41], v[156:159], v[206:209], 0
	v_mfma_f32_16x16x32_bf16 v[22:25], v[156:159], v[214:217], 0
	v_mfma_f32_16x16x32_bf16 v[6:9], v[156:159], v[236:239], 0
	v_mfma_f32_16x16x32_bf16 v[50:53], v[168:171], v[176:179], 0
	v_mfma_f32_16x16x32_bf16 v[34:37], v[168:171], v[206:209], 0
	v_mfma_f32_16x16x32_bf16 v[18:21], v[168:171], v[214:217], 0
	v_mfma_f32_16x16x32_bf16 v[2:5], v[168:171], v[236:239], 0
	v_mfma_f32_16x16x32_bf16 v[54:57], v[160:163], v[180:183], v[54:57]
	v_mfma_f32_16x16x32_bf16 v[38:41], v[160:163], v[210:213], v[38:41]
	v_mfma_f32_16x16x32_bf16 v[22:25], v[160:163], v[218:221], v[22:25]
	v_mfma_f32_16x16x32_bf16 v[6:9], v[160:163], v[240:243], v[6:9]
	v_mfma_f32_16x16x32_bf16 v[50:53], v[172:175], v[180:183], v[50:53]
	v_mfma_f32_16x16x32_bf16 v[34:37], v[172:175], v[210:213], v[34:37]
	v_mfma_f32_16x16x32_bf16 v[18:21], v[172:175], v[218:221], v[18:21]
	v_mfma_f32_16x16x32_bf16 v[2:5], v[172:175], v[240:243], v[2:5]
	s_barrier
	s_add_i32 s12, 0, 0x18000
	s_add_i32 s13, 0, 0x1c000
	ds_read_b128 v[130:133], v198
	ds_read_b128 v[134:137], v198 offset:1024
	ds_read_b128 v[138:141], v198 offset:2048
	ds_read_b128 v[152:155], v198 offset:3072
	ds_read_b128 v[156:159], v199
	ds_read_b128 v[160:163], v199 offset:1024
	ds_read_b128 v[168:171], v199 offset:2048
	ds_read_b128 v[172:175], v199 offset:3072
	s_add_u32 s10, vcc_lo, 0x200000
	s_addc_u32 s11, vcc_hi, 0
	s_mov_b32 m0, s86
	ds_read_b128 v[176:179], v166 offset:32768
	ds_read_b128 v[180:183], v166 offset:33792
	ds_read_b128 v[206:209], v166 offset:34816
	ds_read_b128 v[210:213], v166 offset:35840
	ds_read_b128 v[214:217], v166 offset:36864
	ds_read_b128 v[218:221], v166 offset:37888
	ds_read_b128 v[236:239], v166 offset:38912
	ds_read_b128 v[240:243], v166 offset:39936
	global_load_lds_dwordx4 v190, s[10:11]
	s_mov_b32 m0, s87
	s_nop 0
	global_load_lds_dwordx4 v144, s[10:11]
	s_waitcnt vmcnt(8)
	s_waitcnt lgkmcnt(0)
	s_barrier
	v_mfma_f32_16x16x32_bf16 v[126:129], v[130:133], v[176:179], v[126:129]
	v_mfma_f32_16x16x32_bf16 v[110:113], v[130:133], v[206:209], v[110:113]
	v_mfma_f32_16x16x32_bf16 v[94:97], v[130:133], v[214:217], v[94:97]
	v_mfma_f32_16x16x32_bf16 v[78:81], v[130:133], v[236:239], v[78:81]
	v_mfma_f32_16x16x32_bf16 v[122:125], v[138:141], v[176:179], v[122:125]
	v_mfma_f32_16x16x32_bf16 v[106:109], v[138:141], v[206:209], v[106:109]
	v_mfma_f32_16x16x32_bf16 v[90:93], v[138:141], v[214:217], v[90:93]
	v_mfma_f32_16x16x32_bf16 v[74:77], v[138:141], v[236:239], v[74:77]
	v_mfma_f32_16x16x32_bf16 v[126:129], v[134:137], v[180:183], v[126:129]
	v_mfma_f32_16x16x32_bf16 v[110:113], v[134:137], v[210:213], v[110:113]
	v_mfma_f32_16x16x32_bf16 v[94:97], v[134:137], v[218:221], v[94:97]
	v_mfma_f32_16x16x32_bf16 v[78:81], v[134:137], v[240:243], v[78:81]
	v_mfma_f32_16x16x32_bf16 v[122:125], v[152:155], v[180:183], v[122:125]
	v_mfma_f32_16x16x32_bf16 v[106:109], v[152:155], v[210:213], v[106:109]
	v_mfma_f32_16x16x32_bf16 v[90:93], v[152:155], v[218:221], v[90:93]
	v_mfma_f32_16x16x32_bf16 v[74:77], v[152:155], v[240:243], v[74:77]
	v_mfma_f32_16x16x32_bf16 v[118:121], v[156:159], v[176:179], v[118:121]
	v_mfma_f32_16x16x32_bf16 v[102:105], v[156:159], v[206:209], v[102:105]
	v_mfma_f32_16x16x32_bf16 v[86:89], v[156:159], v[214:217], v[86:89]
	v_mfma_f32_16x16x32_bf16 v[70:73], v[156:159], v[236:239], v[70:73]
	v_mfma_f32_16x16x32_bf16 v[114:117], v[168:171], v[176:179], v[114:117]
	v_mfma_f32_16x16x32_bf16 v[98:101], v[168:171], v[206:209], v[98:101]
	v_mfma_f32_16x16x32_bf16 v[82:85], v[168:171], v[214:217], v[82:85]
	v_mfma_f32_16x16x32_bf16 v[66:69], v[168:171], v[236:239], v[66:69]
	v_mfma_f32_16x16x32_bf16 v[118:121], v[160:163], v[180:183], v[118:121]
	v_mfma_f32_16x16x32_bf16 v[102:105], v[160:163], v[210:213], v[102:105]
	v_mfma_f32_16x16x32_bf16 v[86:89], v[160:163], v[218:221], v[86:89]
	v_mfma_f32_16x16x32_bf16 v[70:73], v[160:163], v[240:243], v[70:73]
	v_mfma_f32_16x16x32_bf16 v[114:117], v[172:175], v[180:183], v[114:117]
	v_mfma_f32_16x16x32_bf16 v[98:101], v[172:175], v[210:213], v[98:101]
	v_mfma_f32_16x16x32_bf16 v[82:85], v[172:175], v[218:221], v[82:85]
	v_mfma_f32_16x16x32_bf16 v[66:69], v[172:175], v[240:243], v[66:69]
	s_barrier
; #define PG8_STAGE(bufoff, gbase, voff) do { _Pragma("unroll") for (int _i = 0; _i < 2; ++_i) \
;         __builtin_amdgcn_global_load_lds((const unsigned*)((const char*)(gbase) + (voff)[_i]), (PG8_LAS unsigned*)(lds + (bufoff) + ldsw + _i * 8192), 16, 0, 0); } while (0)
; #define PG8_LDA(dst, b, h) do { _Pragma("unroll") for (int m = 0; m < 4; ++m) _Pragma("unroll") for (int k = 0; k < 2; ++k) dst[m][k] = *(const PG8_LAS bf16x8*)(lds + PG8_SA(b, h) + aoff + m * 2048 + k * 1024); } while (0)
; #define PG8_LDB(dst, b, h) do { _Pragma("unroll") for (int n = 0; n < 2; ++n) _Pragma("unroll") for (int k = 0; k < 2; ++k) dst[n][k] = *(const PG8_LAS bf16x8*)(lds + PG8_SB(b, h) + boff + n * 2048 + k * 1024); } while (0)
; #define PG8_MMA(ai, bj, At, Bt) do { __builtin_amdgcn_s_setprio(1); _Pragma("unroll") for (int m = 0; m < 4; ++m) _Pragma("unroll") for (int n = 0; n < 2; ++n) _Pragma("unroll") for (int k = 0; k < 2; ++k) \
;         acc[ai][bj][m][n] = __builtin_amdgcn_mfma_f32_16x16x32_bf16(Bt[n][k], At[m][k], acc[ai][bj][m][n], 0, 0, 0); __builtin_amdgcn_s_setprio(0); } while (0)
; #define PG8_WAIT_V(n) asm volatile("s_waitcnt vmcnt(" #n ")" ::: "memory")
; template <class Epi, class Sched, bool ALIGN_EPI = false, bool SP2 = false>
; __device__ __forceinline__ void gemm_phase(PG8_LAS unsigned char* lds, const Gemm g, const Sched& S, const Epi& E) {
;     ...
;             PG8_LDB(B0, 0, 0); PG8_LDB(B1, 0, 1); PG8_SCHED; PG8_LDA(At, 0, 0); PG8_STAGE(PG8_SA(1, 1), a1 + hstep, voffA);
;             PG8_WAIT_V(8); PG8_WAIT_L(0); PG8_BAR; PG8_MMA(0, 0, At, B0); PG8_MMA(0, 1, At, B1); PG8_BAR; PG8_SCHED;
;             PG8_LDA(At, 0, 1); PG8_STAGE(PG8_SB(0, 0), b2, voffB); PG8_STAGE(PG8_SB(0, 1), b2 + hstepB, voffB); PG8_STAGE(PG8_SA(0, 0), a2, voffA);
;             PG8_WAIT_V(8); PG8_WAIT_L(0); PG8_BAR; PG8_MMA(1, 0, At, B0); PG8_MMA(1, 1, At, B1); PG8_BAR; PG8_SCHED;
;             PG8_LDB(B0, 1, 0); PG8_LDB(B1, 1, 1); PG8_SCHED; PG8_LDA(At, 1, 0); PG8_STAGE(PG8_SA(0, 1), a2 + hstep, voffA);
;             PG8_WAIT_V(8); PG8_WAIT_L(0); PG8_BAR; PG8_MMA(0, 0, At, B0); PG8_MMA(0, 1, At, B1); PG8_BAR; PG8_SCHED;
;             PG8_LDA(At, 1, 1); PG8_STAGE(PG8_SB(1, 0), b3, voffB); PG8_STAGE(PG8_SB(1, 1), b3 + hstepB, voffB); PG8_STAGE(PG8_SA(1, 0), a3, voffA);
;             PG8_WAIT_V(8); PG8_WAIT_L(0); PG8_BAR; PG8_MMA(1, 0, At, B0); PG8_MMA(1, 1, At, B1); PG8_BAR; PG8_SCHED;
	s_add_i32 s10, s12, s67
	s_mov_b32 m0, s10
	ds_read_b128 v[176:179], v166 offset:49152
	ds_read_b128 v[180:183], v166 offset:50176
	ds_read_b128 v[206:209], v166 offset:51200
	ds_read_b128 v[210:213], v166 offset:52224
	ds_read_b128 v[214:217], v166 offset:53248
	ds_read_b128 v[218:221], v166 offset:54272
	ds_read_b128 v[236:239], v166 offset:55296
	ds_read_b128 v[240:243], v166 offset:56320
	s_add_u32 s100, s46, s60
	s_addc_u32 s101, s47, s61
	global_load_lds_dwordx4 v146, s[100:101]
	s_add_i32 m0, s10, 0x2000
	s_add_u32 s10, s46, 0x80080
	s_addc_u32 s11, s47, 0
	s_add_i32 s12, s13, s67
	global_load_lds_dwordx4 v142, s[100:101]
	s_mov_b32 m0, s12
	s_nop 0
	global_load_lds_dwordx4 v146, s[10:11]
	s_add_i32 m0, s12, 0x2000
	s_nop 0
	global_load_lds_dwordx4 v142, s[10:11]
	s_mov_b32 m0, s82
	s_add_u32 s100, vcc_lo, s60
	s_addc_u32 s101, vcc_hi, s61
	global_load_lds_dwordx4 v190, s[100:101]
	s_mov_b32 m0, s42
	s_nop 0
	global_load_lds_dwordx4 v144, s[100:101]
	s_waitcnt vmcnt(8)
	s_waitcnt lgkmcnt(0)
	s_barrier
	v_mfma_f32_16x16x32_bf16 v[62:65], v[130:133], v[176:179], v[62:65]
	v_mfma_f32_16x16x32_bf16 v[46:49], v[130:133], v[206:209], v[46:49]
	v_mfma_f32_16x16x32_bf16 v[30:33], v[130:133], v[214:217], v[30:33]
	v_mfma_f32_16x16x32_bf16 v[14:17], v[130:133], v[236:239], v[14:17]
	v_mfma_f32_16x16x32_bf16 v[58:61], v[138:141], v[176:179], v[58:61]
	v_mfma_f32_16x16x32_bf16 v[42:45], v[138:141], v[206:209], v[42:45]
	v_mfma_f32_16x16x32_bf16 v[26:29], v[138:141], v[214:217], v[26:29]
	v_mfma_f32_16x16x32_bf16 v[10:13], v[138:141], v[236:239], v[10:13]
	v_mfma_f32_16x16x32_bf16 v[62:65], v[134:137], v[180:183], v[62:65]
	v_mfma_f32_16x16x32_bf16 v[46:49], v[134:137], v[210:213], v[46:49]
	v_mfma_f32_16x16x32_bf16 v[30:33], v[134:137], v[218:221], v[30:33]
	v_mfma_f32_16x16x32_bf16 v[14:17], v[134:137], v[240:243], v[14:17]
	v_mfma_f32_16x16x32_bf16 v[58:61], v[152:155], v[180:183], v[58:61]
	v_mfma_f32_16x16x32_bf16 v[42:45], v[152:155], v[210:213], v[42:45]
	v_mfma_f32_16x16x32_bf16 v[26:29], v[152:155], v[218:221], v[26:29]
	v_mfma_f32_16x16x32_bf16 v[10:13], v[152:155], v[240:243], v[10:13]
	v_mfma_f32_16x16x32_bf16 v[54:57], v[156:159], v[176:179], v[54:57]
	v_mfma_f32_16x16x32_bf16 v[38:41], v[156:159], v[206:209], v[38:41]
	v_mfma_f32_16x16x32_bf16 v[22:25], v[156:159], v[214:217], v[22:25]
	v_mfma_f32_16x16x32_bf16 v[6:9], v[156:159], v[236:239], v[6:9]
	v_mfma_f32_16x16x32_bf16 v[50:53], v[168:171], v[176:179], v[50:53]
	v_mfma_f32_16x16x32_bf16 v[34:37], v[168:171], v[206:209], v[34:37]
	v_mfma_f32_16x16x32_bf16 v[18:21], v[168:171], v[214:217], v[18:21]
	v_mfma_f32_16x16x32_bf16 v[2:5], v[168:171], v[236:239], v[2:5]
	v_mfma_f32_16x16x32_bf16 v[54:57], v[160:163], v[180:183], v[54:57]
	v_mfma_f32_16x16x32_bf16 v[38:41], v[160:163], v[210:213], v[38:41]
	v_mfma_f32_16x16x32_bf16 v[22:25], v[160:163], v[218:221], v[22:25]
	v_mfma_f32_16x16x32_bf16 v[6:9], v[160:163], v[240:243], v[6:9]
	v_mfma_f32_16x16x32_bf16 v[50:53], v[172:175], v[180:183], v[50:53]
	v_mfma_f32_16x16x32_bf16 v[34:37], v[172:175], v[210:213], v[34:37]
	v_mfma_f32_16x16x32_bf16 v[18:21], v[172:175], v[218:221], v[18:21]
	v_mfma_f32_16x16x32_bf16 v[2:5], v[172:175], v[240:243], v[2:5]
	s_barrier
	s_add_i32 s9, s9, 2
	s_add_u32 s38, s38, 0x100
	s_addc_u32 s39, s39, 0
	s_add_u32 s7, s7, 0x100
	s_addc_u32 s8, s8, 0
	s_cmpk_gt_u32 s9, 0x7d
.LBB0_1071:
	s_add_u32 s10, s38, 0xffe00080
	s_addc_u32 s11, s39, -1
	s_add_i32 s12, 0, 0x10000
	s_cmpk_eq_i32 s9, 0x7c
	s_cselect_b32 vcc_hi, s97, s11
	s_cselect_b32 vcc_lo, s4, s10
	s_cselect_b32 s47, s5, s8
	s_cselect_b32 s46, s6, s7
	s_add_i32 s13, 0, 0x14000
	ds_read_b128 v[130:133], v186
	ds_read_b128 v[134:137], v186 offset:1024
	ds_read_b128 v[138:141], v186 offset:2048
	ds_read_b128 v[152:155], v186 offset:3072
	ds_read_b128 v[156:159], v187
	ds_read_b128 v[160:163], v187 offset:1024
	ds_read_b128 v[168:171], v187 offset:2048
	ds_read_b128 v[172:175], v187 offset:3072
	s_add_i32 m0, s74, 0xc000
	ds_read_b128 v[176:179], v166
	ds_read_b128 v[180:183], v166 offset:1024
	ds_read_b128 v[206:209], v166 offset:2048
	ds_read_b128 v[210:213], v166 offset:3072
	ds_read_b128 v[214:217], v166 offset:4096
	ds_read_b128 v[218:221], v166 offset:5120
	ds_read_b128 v[236:239], v166 offset:6144
	ds_read_b128 v[240:243], v166 offset:7168
	global_load_lds_dwordx4 v148, s[38:39]
	s_add_i32 m0, s74, 0xe000
	s_nop 0
	global_load_lds_dwordx4 v150, s[38:39]
	s_waitcnt vmcnt(8)
	s_waitcnt lgkmcnt(0)
	s_barrier
	v_mfma_f32_16x16x32_bf16 v[126:129], v[130:133], v[176:179], v[126:129]
	v_mfma_f32_16x16x32_bf16 v[110:113], v[130:133], v[206:209], v[110:113]
	v_mfma_f32_16x16x32_bf16 v[94:97], v[130:133], v[214:217], v[94:97]
	v_mfma_f32_16x16x32_bf16 v[78:81], v[130:133], v[236:239], v[78:81]
	v_mfma_f32_16x16x32_bf16 v[122:125], v[138:141], v[176:179], v[122:125]
	v_mfma_f32_16x16x32_bf16 v[106:109], v[138:141], v[206:209], v[106:109]
	v_mfma_f32_16x16x32_bf16 v[90:93], v[138:141], v[214:217], v[90:93]
	v_mfma_f32_16x16x32_bf16 v[74:77], v[138:141], v[236:239], v[74:77]
	v_mfma_f32_16x16x32_bf16 v[126:129], v[134:137], v[180:183], v[126:129]
	v_mfma_f32_16x16x32_bf16 v[110:113], v[134:137], v[210:213], v[110:113]
	v_mfma_f32_16x16x32_bf16 v[94:97], v[134:137], v[218:221], v[94:97]
	v_mfma_f32_16x16x32_bf16 v[78:81], v[134:137], v[240:243], v[78:81]
	v_mfma_f32_16x16x32_bf16 v[122:125], v[152:155], v[180:183], v[122:125]
	v_mfma_f32_16x16x32_bf16 v[106:109], v[152:155], v[210:213], v[106:109]
	v_mfma_f32_16x16x32_bf16 v[90:93], v[152:155], v[218:221], v[90:93]
	v_mfma_f32_16x16x32_bf16 v[74:77], v[152:155], v[240:243], v[74:77]
	v_mfma_f32_16x16x32_bf16 v[118:121], v[156:159], v[176:179], v[118:121]
	v_mfma_f32_16x16x32_bf16 v[102:105], v[156:159], v[206:209], v[102:105]
	v_mfma_f32_16x16x32_bf16 v[86:89], v[156:159], v[214:217], v[86:89]
	v_mfma_f32_16x16x32_bf16 v[70:73], v[156:159], v[236:239], v[70:73]
	v_mfma_f32_16x16x32_bf16 v[114:117], v[168:171], v[176:179], v[114:117]
	v_mfma_f32_16x16x32_bf16 v[98:101], v[168:171], v[206:209], v[98:101]
	v_mfma_f32_16x16x32_bf16 v[82:85], v[168:171], v[214:217], v[82:85]
	v_mfma_f32_16x16x32_bf16 v[66:69], v[168:171], v[236:239], v[66:69]
	v_mfma_f32_16x16x32_bf16 v[118:121], v[160:163], v[180:183], v[118:121]
	v_mfma_f32_16x16x32_bf16 v[102:105], v[160:163], v[210:213], v[102:105]
	v_mfma_f32_16x16x32_bf16 v[86:89], v[160:163], v[218:221], v[86:89]
	v_mfma_f32_16x16x32_bf16 v[70:73], v[160:163], v[240:243], v[70:73]
	v_mfma_f32_16x16x32_bf16 v[114:117], v[172:175], v[180:183], v[114:117]
	v_mfma_f32_16x16x32_bf16 v[98:101], v[172:175], v[210:213], v[98:101]
	v_mfma_f32_16x16x32_bf16 v[82:85], v[172:175], v[218:221], v[82:85]
	v_mfma_f32_16x16x32_bf16 v[66:69], v[172:175], v[240:243], v[66:69]
	s_barrier
; #define PG8_STAGE(bufoff, gbase, voff) do { _Pragma("unroll") for (int _i = 0; _i < 2; ++_i) \
;         __builtin_amdgcn_global_load_lds((const unsigned*)((const char*)(gbase) + (voff)[_i]), (PG8_LAS unsigned*)(lds + (bufoff) + ldsw + _i * 8192), 16, 0, 0); } while (0)
; #define PG8_LDA(dst, b, h) do { _Pragma("unroll") for (int m = 0; m < 4; ++m) _Pragma("unroll") for (int k = 0; k < 2; ++k) dst[m][k] = *(const PG8_LAS bf16x8*)(lds + PG8_SA(b, h) + aoff + m * 2048 + k * 1024); } while (0)
; #define PG8_MMA(ai, bj, At, Bt) do { __builtin_amdgcn_s_setprio(1); _Pragma("unroll") for (int m = 0; m < 4; ++m) _Pragma("unroll") for (int n = 0; n < 2; ++n) _Pragma("unroll") for (int k = 0; k < 2; ++k) \
;         acc[ai][bj][m][n] = __builtin_amdgcn_mfma_f32_16x16x32_bf16(Bt[n][k], At[m][k], acc[ai][bj][m][n], 0, 0, 0); __builtin_amdgcn_s_setprio(0); } while (0)
; #define PG8_WAIT_V(n) asm volatile("s_waitcnt vmcnt(" #n ")" ::: "memory")
; #define PG8_WAIT_L(n) asm volatile("s_waitcnt lgkmcnt(" #n ")" ::: "memory")
; #define PG8_BAR __builtin_amdgcn_s_barrier()
; #define PG8_SCHED __builtin_amdgcn_sched_barrier(0)
; template <class Epi, class Sched, bool ALIGN_EPI = false, bool SP2 = false>
; __device__ __forceinline__ void gemm_phase(PG8_LAS unsigned char* lds, const Gemm g, const Sched& S, const Epi& E) {
;     ...
;             PG8_LDA(At, 0, 1); PG8_STAGE(PG8_SB(0, 0), b2, voffB); PG8_STAGE(PG8_SB(0, 1), b2 + hstepB, voffB); PG8_STAGE(PG8_SA(0, 0), a2, voffA);
;             PG8_WAIT_V(8); PG8_WAIT_L(0); PG8_BAR; PG8_MMA(1, 0, At, B0); PG8_MMA(1, 1, At, B1); PG8_BAR; PG8_SCHED;
	s_add_i32 s10, s12, s67
	s_mov_b32 m0, s10
	ds_read_b128 v[176:179], v166 offset:16384
	ds_read_b128 v[180:183], v166 offset:17408
	ds_read_b128 v[206:209], v166 offset:18432
	ds_read_b128 v[210:213], v166 offset:19456
	ds_read_b128 v[214:217], v166 offset:20480
	ds_read_b128 v[218:221], v166 offset:21504
	ds_read_b128 v[236:239], v166 offset:22528
	ds_read_b128 v[240:243], v166 offset:23552
	global_load_lds_dwordx4 v146, s[46:47]
	s_add_i32 m0, s10, 0x2000
	s_add_u32 s10, s46, 0x80000
	s_addc_u32 s11, s47, 0
	s_add_i32 s12, s13, s67
	global_load_lds_dwordx4 v142, s[46:47]
	s_mov_b32 m0, s12
	s_nop 0
	global_load_lds_dwordx4 v146, s[10:11]
	s_add_i32 m0, s12, 0x2000
	s_nop 0
	global_load_lds_dwordx4 v142, s[10:11]
	s_mov_b32 m0, s74
	s_nop 0
	global_load_lds_dwordx4 v190, vcc
	s_mov_b32 m0, s75
	s_nop 0
	global_load_lds_dwordx4 v144, vcc
	s_waitcnt vmcnt(8)
	s_waitcnt lgkmcnt(0)
	s_barrier
	v_mfma_f32_16x16x32_bf16 v[62:65], v[130:133], v[176:179], v[62:65]
	v_mfma_f32_16x16x32_bf16 v[46:49], v[130:133], v[206:209], v[46:49]
	v_mfma_f32_16x16x32_bf16 v[30:33], v[130:133], v[214:217], v[30:33]
	v_mfma_f32_16x16x32_bf16 v[14:17], v[130:133], v[236:239], v[14:17]
	v_mfma_f32_16x16x32_bf16 v[58:61], v[138:141], v[176:179], v[58:61]
	v_mfma_f32_16x16x32_bf16 v[42:45], v[138:141], v[206:209], v[42:45]
	v_mfma_f32_16x16x32_bf16 v[26:29], v[138:141], v[214:217], v[26:29]
	v_mfma_f32_16x16x32_bf16 v[10:13], v[138:141], v[236:239], v[10:13]
	v_mfma_f32_16x16x32_bf16 v[62:65], v[134:137], v[180:183], v[62:65]
	v_mfma_f32_16x16x32_bf16 v[46:49], v[134:137], v[210:213], v[46:49]
	v_mfma_f32_16x16x32_bf16 v[30:33], v[134:137], v[218:221], v[30:33]
	v_mfma_f32_16x16x32_bf16 v[14:17], v[134:137], v[240:243], v[14:17]
	v_mfma_f32_16x16x32_bf16 v[58:61], v[152:155], v[180:183], v[58:61]
	v_mfma_f32_16x16x32_bf16 v[42:45], v[152:155], v[210:213], v[42:45]
	v_mfma_f32_16x16x32_bf16 v[26:29], v[152:155], v[218:221], v[26:29]
	v_mfma_f32_16x16x32_bf16 v[10:13], v[152:155], v[240:243], v[10:13]
	v_mfma_f32_16x16x32_bf16 v[54:57], v[156:159], v[176:179], v[54:57]
	v_mfma_f32_16x16x32_bf16 v[38:41], v[156:159], v[206:209], v[38:41]
	v_mfma_f32_16x16x32_bf16 v[22:25], v[156:159], v[214:217], v[22:25]
	v_mfma_f32_16x16x32_bf16 v[6:9], v[156:159], v[236:239], v[6:9]
	v_mfma_f32_16x16x32_bf16 v[50:53], v[168:171], v[176:179], v[50:53]
	v_mfma_f32_16x16x32_bf16 v[34:37], v[168:171], v[206:209], v[34:37]
	v_mfma_f32_16x16x32_bf16 v[18:21], v[168:171], v[214:217], v[18:21]
	v_mfma_f32_16x16x32_bf16 v[2:5], v[168:171], v[236:239], v[2:5]
	v_mfma_f32_16x16x32_bf16 v[54:57], v[160:163], v[180:183], v[54:57]
	v_mfma_f32_16x16x32_bf16 v[38:41], v[160:163], v[210:213], v[38:41]
	v_mfma_f32_16x16x32_bf16 v[22:25], v[160:163], v[218:221], v[22:25]
	v_mfma_f32_16x16x32_bf16 v[6:9], v[160:163], v[240:243], v[6:9]
	v_mfma_f32_16x16x32_bf16 v[50:53], v[172:175], v[180:183], v[50:53]
	v_mfma_f32_16x16x32_bf16 v[34:37], v[172:175], v[210:213], v[34:37]
	v_mfma_f32_16x16x32_bf16 v[18:21], v[172:175], v[218:221], v[18:21]
	v_mfma_f32_16x16x32_bf16 v[2:5], v[172:175], v[240:243], v[2:5]
	s_barrier
	s_add_i32 s12, 0, 0x18000
	s_add_i32 s13, 0, 0x1c000
	ds_read_b128 v[130:133], v198
	ds_read_b128 v[134:137], v198 offset:1024
	ds_read_b128 v[138:141], v198 offset:2048
	ds_read_b128 v[152:155], v198 offset:3072
	ds_read_b128 v[156:159], v199
	ds_read_b128 v[160:163], v199 offset:1024
	ds_read_b128 v[168:171], v199 offset:2048
	ds_read_b128 v[172:175], v199 offset:3072
	s_add_u32 s10, vcc_lo, 0x200000
	s_addc_u32 s11, vcc_hi, 0
	s_mov_b32 m0, s86
	ds_read_b128 v[176:179], v166 offset:32768
	ds_read_b128 v[180:183], v166 offset:33792
	ds_read_b128 v[206:209], v166 offset:34816
	ds_read_b128 v[210:213], v166 offset:35840
	ds_read_b128 v[214:217], v166 offset:36864
	ds_read_b128 v[218:221], v166 offset:37888
	ds_read_b128 v[236:239], v166 offset:38912
	ds_read_b128 v[240:243], v166 offset:39936
	global_load_lds_dwordx4 v190, s[10:11]
	s_mov_b32 m0, s87
	s_nop 0
	global_load_lds_dwordx4 v144, s[10:11]
	s_waitcnt vmcnt(8)
	s_waitcnt lgkmcnt(0)
	s_barrier
; #define PG8_STAGE(bufoff, gbase, voff) do { _Pragma("unroll") for (int _i = 0; _i < 2; ++_i) \
;         __builtin_amdgcn_global_load_lds((const unsigned*)((const char*)(gbase) + (voff)[_i]), (PG8_LAS unsigned*)(lds + (bufoff) + ldsw + _i * 8192), 16, 0, 0); } while (0)
; #define PG8_LDA(dst, b, h) do { _Pragma("unroll") for (int m = 0; m < 4; ++m) _Pragma("unroll") for (int k = 0; k < 2; ++k) dst[m][k] = *(const PG8_LAS bf16x8*)(lds + PG8_SA(b, h) + aoff + m * 2048 + k * 1024); } while (0)
; #define PG8_LDB(dst, b, h) do { _Pragma("unroll") for (int n = 0; n < 2; ++n) _Pragma("unroll") for (int k = 0; k < 2; ++k) dst[n][k] = *(const PG8_LAS bf16x8*)(lds + PG8_SB(b, h) + boff + n * 2048 + k * 1024); } while (0)
; #define PG8_MMA(ai, bj, At, Bt) do { __builtin_amdgcn_s_setprio(1); _Pragma("unroll") for (int m = 0; m < 4; ++m) _Pragma("unroll") for (int n = 0; n < 2; ++n) _Pragma("unroll") for (int k = 0; k < 2; ++k) \
;         acc[ai][bj][m][n] = __builtin_amdgcn_mfma_f32_16x16x32_bf16(Bt[n][k], At[m][k], acc[ai][bj][m][n], 0, 0, 0); __builtin_amdgcn_s_setprio(0); } while (0)
; #define PG8_WAIT_V(n) asm volatile("s_waitcnt vmcnt(" #n ")" ::: "memory")
; #define PG8_WAIT_L(n) asm volatile("s_waitcnt lgkmcnt(" #n ")" ::: "memory")
; #define PG8_BAR __builtin_amdgcn_s_barrier()
; #define PG8_SCHED __builtin_amdgcn_sched_barrier(0)
; template <class Epi, class Sched, bool ALIGN_EPI = false, bool SP2 = false>
; __device__ __forceinline__ void gemm_phase(PG8_LAS unsigned char* lds, const Gemm g, const Sched& S, const Epi& E) {
;     ...
;             PG8_LDB(B0, 1, 0); PG8_LDB(B1, 1, 1); PG8_SCHED; PG8_LDA(At, 1, 0); PG8_STAGE(PG8_SA(0, 1), a2 + hstep, voffA);
;             PG8_WAIT_V(8); PG8_WAIT_L(0); PG8_BAR; PG8_MMA(0, 0, At, B0); PG8_MMA(0, 1, At, B1); PG8_BAR; PG8_SCHED;
;             PG8_LDA(At, 1, 1); PG8_STAGE(PG8_SB(1, 0), b3, voffB); PG8_STAGE(PG8_SB(1, 1), b3 + hstepB, voffB); PG8_STAGE(PG8_SA(1, 0), a3, voffA);
;             PG8_WAIT_V(8); PG8_WAIT_L(0); PG8_BAR; PG8_MMA(1, 0, At, B0); PG8_MMA(1, 1, At, B1); PG8_BAR; PG8_SCHED;
;     ...
;         if constexpr (ALIGN_EPI) { if (wr == 0) PG8_BAR; }
;         if constexpr (!Epi::AFTER_DRAIN) { E(acc, cur, wr, wc, fr, fq, ui); S.done(cur); }
;         if (!has_next) break;
	v_mfma_f32_16x16x32_bf16 v[126:129], v[130:133], v[176:179], v[126:129]
	v_mfma_f32_16x16x32_bf16 v[110:113], v[130:133], v[206:209], v[110:113]
	v_mfma_f32_16x16x32_bf16 v[94:97], v[130:133], v[214:217], v[94:97]
	v_mfma_f32_16x16x32_bf16 v[78:81], v[130:133], v[236:239], v[78:81]
	v_mfma_f32_16x16x32_bf16 v[122:125], v[138:141], v[176:179], v[122:125]
	v_mfma_f32_16x16x32_bf16 v[106:109], v[138:141], v[206:209], v[106:109]
	v_mfma_f32_16x16x32_bf16 v[90:93], v[138:141], v[214:217], v[90:93]
	v_mfma_f32_16x16x32_bf16 v[74:77], v[138:141], v[236:239], v[74:77]
	v_mfma_f32_16x16x32_bf16 v[126:129], v[134:137], v[180:183], v[126:129]
	v_mfma_f32_16x16x32_bf16 v[110:113], v[134:137], v[210:213], v[110:113]
	v_mfma_f32_16x16x32_bf16 v[94:97], v[134:137], v[218:221], v[94:97]
	v_mfma_f32_16x16x32_bf16 v[78:81], v[134:137], v[240:243], v[78:81]
	v_mfma_f32_16x16x32_bf16 v[122:125], v[152:155], v[180:183], v[122:125]
	v_mfma_f32_16x16x32_bf16 v[106:109], v[152:155], v[210:213], v[106:109]
	v_mfma_f32_16x16x32_bf16 v[90:93], v[152:155], v[218:221], v[90:93]
	v_mfma_f32_16x16x32_bf16 v[74:77], v[152:155], v[240:243], v[74:77]
	v_mfma_f32_16x16x32_bf16 v[118:121], v[156:159], v[176:179], v[118:121]
	v_mfma_f32_16x16x32_bf16 v[102:105], v[156:159], v[206:209], v[102:105]
	v_mfma_f32_16x16x32_bf16 v[86:89], v[156:159], v[214:217], v[86:89]
	v_mfma_f32_16x16x32_bf16 v[70:73], v[156:159], v[236:239], v[70:73]
	v_mfma_f32_16x16x32_bf16 v[114:117], v[168:171], v[176:179], v[114:117]
	v_mfma_f32_16x16x32_bf16 v[98:101], v[168:171], v[206:209], v[98:101]
	v_mfma_f32_16x16x32_bf16 v[82:85], v[168:171], v[214:217], v[82:85]
	v_mfma_f32_16x16x32_bf16 v[66:69], v[168:171], v[236:239], v[66:69]
	v_mfma_f32_16x16x32_bf16 v[118:121], v[160:163], v[180:183], v[118:121]
	v_mfma_f32_16x16x32_bf16 v[102:105], v[160:163], v[210:213], v[102:105]
	v_mfma_f32_16x16x32_bf16 v[86:89], v[160:163], v[218:221], v[86:89]
	v_mfma_f32_16x16x32_bf16 v[70:73], v[160:163], v[240:243], v[70:73]
	v_mfma_f32_16x16x32_bf16 v[114:117], v[172:175], v[180:183], v[114:117]
	v_mfma_f32_16x16x32_bf16 v[98:101], v[172:175], v[210:213], v[98:101]
	v_mfma_f32_16x16x32_bf16 v[82:85], v[172:175], v[218:221], v[82:85]
	v_mfma_f32_16x16x32_bf16 v[66:69], v[172:175], v[240:243], v[66:69]
	s_barrier
	s_add_i32 s10, s12, s67
	s_mov_b32 m0, s10
	ds_read_b128 v[176:179], v166 offset:49152
	ds_read_b128 v[180:183], v166 offset:50176
	ds_read_b128 v[206:209], v166 offset:51200
	ds_read_b128 v[210:213], v166 offset:52224
	ds_read_b128 v[214:217], v166 offset:53248
	ds_read_b128 v[218:221], v166 offset:54272
	ds_read_b128 v[236:239], v166 offset:55296
	ds_read_b128 v[240:243], v166 offset:56320
	s_add_u32 s100, s46, s60
	s_addc_u32 s101, s47, s61
	global_load_lds_dwordx4 v146, s[100:101]
	s_add_i32 m0, s10, 0x2000
	s_add_u32 s10, s46, 0x80080
	s_addc_u32 s11, s47, 0
	s_add_i32 s12, s13, s67
	global_load_lds_dwordx4 v142, s[100:101]
	s_mov_b32 m0, s12
	s_nop 0
	global_load_lds_dwordx4 v146, s[10:11]
	s_add_i32 m0, s12, 0x2000
	s_nop 0
	global_load_lds_dwordx4 v142, s[10:11]
	s_mov_b32 m0, s82
	s_add_u32 s100, vcc_lo, s60
	s_addc_u32 s101, vcc_hi, s61
	global_load_lds_dwordx4 v190, s[100:101]
	s_mov_b32 m0, s42
	s_nop 0
	global_load_lds_dwordx4 v144, s[100:101]
	s_waitcnt vmcnt(8)
	s_waitcnt lgkmcnt(0)
	s_barrier
	v_mfma_f32_16x16x32_bf16 v[62:65], v[130:133], v[176:179], v[62:65]
	v_mfma_f32_16x16x32_bf16 v[46:49], v[130:133], v[206:209], v[46:49]
	v_mfma_f32_16x16x32_bf16 v[30:33], v[130:133], v[214:217], v[30:33]
	v_mfma_f32_16x16x32_bf16 v[14:17], v[130:133], v[236:239], v[14:17]
	v_mfma_f32_16x16x32_bf16 v[58:61], v[138:141], v[176:179], v[58:61]
	v_mfma_f32_16x16x32_bf16 v[42:45], v[138:141], v[206:209], v[42:45]
	v_mfma_f32_16x16x32_bf16 v[26:29], v[138:141], v[214:217], v[26:29]
	v_mfma_f32_16x16x32_bf16 v[10:13], v[138:141], v[236:239], v[10:13]
	v_mfma_f32_16x16x32_bf16 v[62:65], v[134:137], v[180:183], v[62:65]
	v_mfma_f32_16x16x32_bf16 v[46:49], v[134:137], v[210:213], v[46:49]
	v_mfma_f32_16x16x32_bf16 v[30:33], v[134:137], v[218:221], v[30:33]
	v_mfma_f32_16x16x32_bf16 v[14:17], v[134:137], v[240:243], v[14:17]
	v_mfma_f32_16x16x32_bf16 v[58:61], v[152:155], v[180:183], v[58:61]
	v_mfma_f32_16x16x32_bf16 v[42:45], v[152:155], v[210:213], v[42:45]
	v_mfma_f32_16x16x32_bf16 v[26:29], v[152:155], v[218:221], v[26:29]
	v_mfma_f32_16x16x32_bf16 v[10:13], v[152:155], v[240:243], v[10:13]
	v_mfma_f32_16x16x32_bf16 v[54:57], v[156:159], v[176:179], v[54:57]
	v_mfma_f32_16x16x32_bf16 v[38:41], v[156:159], v[206:209], v[38:41]
	v_mfma_f32_16x16x32_bf16 v[22:25], v[156:159], v[214:217], v[22:25]
	v_mfma_f32_16x16x32_bf16 v[6:9], v[156:159], v[236:239], v[6:9]
	v_mfma_f32_16x16x32_bf16 v[50:53], v[168:171], v[176:179], v[50:53]
	v_mfma_f32_16x16x32_bf16 v[34:37], v[168:171], v[206:209], v[34:37]
	v_mfma_f32_16x16x32_bf16 v[18:21], v[168:171], v[214:217], v[18:21]
	v_mfma_f32_16x16x32_bf16 v[2:5], v[168:171], v[236:239], v[2:5]
	v_mfma_f32_16x16x32_bf16 v[54:57], v[160:163], v[180:183], v[54:57]
	v_mfma_f32_16x16x32_bf16 v[38:41], v[160:163], v[210:213], v[38:41]
	v_mfma_f32_16x16x32_bf16 v[22:25], v[160:163], v[218:221], v[22:25]
	v_mfma_f32_16x16x32_bf16 v[6:9], v[160:163], v[240:243], v[6:9]
	v_mfma_f32_16x16x32_bf16 v[50:53], v[172:175], v[180:183], v[50:53]
	v_mfma_f32_16x16x32_bf16 v[34:37], v[172:175], v[210:213], v[34:37]
	v_mfma_f32_16x16x32_bf16 v[18:21], v[172:175], v[218:221], v[18:21]
	v_mfma_f32_16x16x32_bf16 v[2:5], v[172:175], v[240:243], v[2:5]
	s_barrier
	s_add_i32 s9, s9, 2
	s_add_u32 s38, s38, 0x100
	s_addc_u32 s39, s39, 0
	s_add_u32 s7, s7, 0x100
	s_addc_u32 s8, s8, 0
	s_cmpk_gt_u32 s9, 0x7d
	s_cbranch_scc0 .LBB0_1071
	s_and_b64 vcc, exec, s[72:73]
	s_cbranch_vccz .LBB0_1074
	s_barrier

; #define PG8_STAGE(bufoff, gbase, voff) do { _Pragma("unroll") for (int _i = 0; _i < 2; ++_i) \
;         __builtin_amdgcn_global_load_lds((const unsigned*)((const char*)(gbase) + (voff)[_i]), (PG8_LAS unsigned*)(lds + (bufoff) + ldsw + _i * 8192), 16, 0, 0); } while (0)
; #define PG8_LDA(dst, b, h) do { _Pragma("unroll") for (int m = 0; m < 4; ++m) _Pragma("unroll") for (int k = 0; k < 2; ++k) dst[m][k] = *(const PG8_LAS bf16x8*)(lds + PG8_SA(b, h) + aoff + m * 2048 + k * 1024); } while (0)
; #define PG8_LDB(dst, b, h) do { _Pragma("unroll") for (int n = 0; n < 2; ++n) _Pragma("unroll") for (int k = 0; k < 2; ++k) dst[n][k] = *(const PG8_LAS bf16x8*)(lds + PG8_SB(b, h) + boff + n * 2048 + k * 1024); } while (0)
; #define PG8_MMA(ai, bj, At, Bt) do { __builtin_amdgcn_s_setprio(1); _Pragma("unroll") for (int m = 0; m < 4; ++m) _Pragma("unroll") for (int n = 0; n < 2; ++n) _Pragma("unroll") for (int k = 0; k < 2; ++k) \
;         acc[ai][bj][m][n] = __builtin_amdgcn_mfma_f32_16x16x32_bf16(Bt[n][k], At[m][k], acc[ai][bj][m][n], 0, 0, 0); __builtin_amdgcn_s_setprio(0); } while (0)
; #define PG8_WAIT_V(n) asm volatile("s_waitcnt vmcnt(" #n ")" ::: "memory")
; #define PG8_WAIT_L(n) asm volatile("s_waitcnt lgkmcnt(" #n ")" ::: "memory")
; #define PG8_BAR __builtin_amdgcn_s_barrier()
; template <class Epi, class Sched, bool ALIGN_EPI = false, bool SP2 = false>
; __device__ __forceinline__ void gemm_phase(PG8_LAS unsigned char* lds, const Gemm g, const Sched& S, const Epi& E) {
;     ...
;         const bool has_next = S.next(ui + 1, nxt);
;         const char* nA = has_next ? (const char*)g.A + (size_t)nxt.pm * tstep : cA; const char* nB = has_next ? (const char*)g.Bt + (size_t)nxt.pn * tstep : cB;
;         for (int t = 0; t < nt; t += 2) {
;             const bool last = (t == nt - 2);
;             const char* a1 = cA + (size_t)(t + 1) * kstep;
;             const char* a2 = last ? nA : cA + (size_t)(t + 2) * kstep; const char* b2 = last ? nB : cB + (size_t)(t + 2) * kstep;
;             const char* a3 = a2 + kstep; const char* b3 = b2 + kstep;
;             if (last && has_next) S.a_ready(nxt);
;             if constexpr (SP2) {
;             PG8_LDB(B0, 0, 0); PG8_LDB(B1, 0, 1); PG8_SCHED; PG8_LDA(At, 0, 0); PG8_STAGE(PG8_SA(1, 1), a1 + hstep, voffA);
;             PG8_WAIT_V(8); PG8_WAIT_L(0); PG8_BAR; PG8_MMA(0, 0, At, B0); PG8_MMA(0, 1, At, B1); PG8_BAR; PG8_SCHED;
.LBB0_1232:
	s_add_u32 s36, s80, 0x100
	s_addc_u32 s37, s81, 0
	s_ashr_i32 s73, s72, 31
	s_lshl_b64 s[4:5], s[72:73], 20
	s_add_u32 s78, s0, s4
	s_addc_u32 s79, s1, s5
	s_and_b64 s[4:5], s[46:47], exec
	s_cselect_b32 s4, s79, s69
	s_cselect_b32 s5, s78, s68
	s_ashr_i32 s71, s70, 31
	s_lshl_b64 s[6:7], s[70:71], 20
	s_add_u32 s76, s34, s6
	s_addc_u32 s77, s35, s7
	s_and_b64 s[6:7], s[46:47], exec
	s_cselect_b32 s6, s77, s81
	s_cselect_b32 s7, s76, s80
	s_add_u32 s8, s68, 0x80080
	s_addc_u32 s9, s69, 0
	v_lshl_add_u64 v[140:141], s[8:9], 0, v[136:137]
	v_lshl_add_u64 v[142:143], s[8:9], 0, v[138:139]
	s_mov_b32 s8, -2
	s_mov_b64 s[80:81], 0
	v_add_u32_e32 v186, 0x10000, v145
	v_add_u32_e32 v187, 0x14000, v145
	v_add_u32_e32 v198, 0x18000, v145
	v_add_u32_e32 v199, 0x1c000, v145
	s_add_u32 s9, s68, s80
	s_addc_u32 s10, s69, s81
	s_add_u32 s9, s9, 0x100
	s_addc_u32 s10, s10, 0
	s_add_u32 s100, s9, 0x7ff80
	s_addc_u32 s101, s10, 0
	s_add_u32 s11, s36, s80
	s_addc_u32 s12, s37, s81
	s_add_i32 s13, 0, 0x10000
	s_cmpk_eq_i32 s80, 0xf00
	s_cselect_b32 s93, s4, s10
	s_cselect_b32 s92, s5, s9
	s_cselect_b32 s85, s6, s12
	s_cselect_b32 s84, s7, s11
	s_add_i32 s9, 0, 0x14000
	ds_read_b128 v[152:155], v186
	ds_read_b128 v[156:159], v186 offset:1024
	ds_read_b128 v[160:163], v186 offset:2048
	ds_read_b128 v[164:167], v186 offset:3072
	ds_read_b128 v[168:171], v187
	ds_read_b128 v[172:175], v187 offset:1024
	ds_read_b128 v[176:179], v187 offset:2048
	ds_read_b128 v[180:183], v187 offset:3072
	s_add_i32 m0, s51, 0xc000
	ds_read_b128 v[206:209], v151
	ds_read_b128 v[210:213], v151 offset:1024
	ds_read_b128 v[214:217], v151 offset:2048
	ds_read_b128 v[218:221], v151 offset:3072
	ds_read_b128 v[236:239], v151 offset:4096
	ds_read_b128 v[240:243], v151 offset:5120
	ds_read_b128 v[244:247], v151 offset:6144
	ds_read_b128 v[194:197], v151 offset:7168
	global_load_lds_dwordx4 v136, s[100:101]
	s_add_i32 m0, s51, 0xe000
	s_nop 0
	global_load_lds_dwordx4 v138, s[100:101]
	s_waitcnt vmcnt(8)
	s_waitcnt lgkmcnt(0)
	s_barrier
	v_mfma_f32_16x16x32_bf16 v[126:129], v[152:155], v[206:209], 0
	v_mfma_f32_16x16x32_bf16 v[118:121], v[152:155], v[214:217], 0
	v_mfma_f32_16x16x32_bf16 v[110:113], v[152:155], v[236:239], 0
	v_mfma_f32_16x16x32_bf16 v[102:105], v[152:155], v[244:247], 0
	v_mfma_f32_16x16x32_bf16 v[122:125], v[160:163], v[206:209], 0
	v_mfma_f32_16x16x32_bf16 v[114:117], v[160:163], v[214:217], 0
	v_mfma_f32_16x16x32_bf16 v[106:109], v[160:163], v[236:239], 0
	v_mfma_f32_16x16x32_bf16 v[98:101], v[160:163], v[244:247], 0
	v_mfma_f32_16x16x32_bf16 v[126:129], v[156:159], v[210:213], v[126:129]
	v_mfma_f32_16x16x32_bf16 v[118:121], v[156:159], v[218:221], v[118:121]
	v_mfma_f32_16x16x32_bf16 v[110:113], v[156:159], v[240:243], v[110:113]
	v_mfma_f32_16x16x32_bf16 v[102:105], v[156:159], v[194:197], v[102:105]
	v_mfma_f32_16x16x32_bf16 v[122:125], v[164:167], v[210:213], v[122:125]
	v_mfma_f32_16x16x32_bf16 v[114:117], v[164:167], v[218:221], v[114:117]
	v_mfma_f32_16x16x32_bf16 v[106:109], v[164:167], v[240:243], v[106:109]
	v_mfma_f32_16x16x32_bf16 v[98:101], v[164:167], v[194:197], v[98:101]
	v_mfma_f32_16x16x32_bf16 v[94:97], v[168:171], v[206:209], 0
	v_mfma_f32_16x16x32_bf16 v[86:89], v[168:171], v[214:217], 0
	v_mfma_f32_16x16x32_bf16 v[78:81], v[168:171], v[236:239], 0
	v_mfma_f32_16x16x32_bf16 v[70:73], v[168:171], v[244:247], 0
	v_mfma_f32_16x16x32_bf16 v[90:93], v[176:179], v[206:209], 0
	v_mfma_f32_16x16x32_bf16 v[82:85], v[176:179], v[214:217], 0
	v_mfma_f32_16x16x32_bf16 v[74:77], v[176:179], v[236:239], 0
	v_mfma_f32_16x16x32_bf16 v[66:69], v[176:179], v[244:247], 0
	v_mfma_f32_16x16x32_bf16 v[94:97], v[172:175], v[210:213], v[94:97]
	v_mfma_f32_16x16x32_bf16 v[86:89], v[172:175], v[218:221], v[86:89]
	v_mfma_f32_16x16x32_bf16 v[78:81], v[172:175], v[240:243], v[78:81]
	v_mfma_f32_16x16x32_bf16 v[70:73], v[172:175], v[194:197], v[70:73]
	v_mfma_f32_16x16x32_bf16 v[90:93], v[180:183], v[210:213], v[90:93]
	v_mfma_f32_16x16x32_bf16 v[82:85], v[180:183], v[218:221], v[82:85]
	v_mfma_f32_16x16x32_bf16 v[74:77], v[180:183], v[240:243], v[74:77]
	v_mfma_f32_16x16x32_bf16 v[66:69], v[180:183], v[194:197], v[66:69]
	s_barrier
	s_add_i32 s10, s13, s42
	s_mov_b32 m0, s10
	ds_read_b128 v[194:197], v151 offset:16384
	ds_read_b128 v[206:209], v151 offset:17408
	ds_read_b128 v[210:213], v151 offset:18432
	ds_read_b128 v[214:217], v151 offset:19456
	ds_read_b128 v[218:221], v151 offset:20480
	ds_read_b128 v[236:239], v151 offset:21504
	ds_read_b128 v[240:243], v151 offset:22528
	ds_read_b128 v[244:247], v151 offset:23552
	global_load_lds_dwordx4 v130, s[84:85]
	s_add_i32 m0, s10, 0x2000
	s_add_u32 s10, s84, 0x20000
	s_addc_u32 s11, s85, 0
	s_add_i32 s9, s9, s42
	global_load_lds_dwordx4 v134, s[84:85]
	s_mov_b32 m0, s9
	s_nop 0
	global_load_lds_dwordx4 v130, s[10:11]
	s_add_i32 m0, s9, 0x2000
	s_nop 0
	global_load_lds_dwordx4 v134, s[10:11]
	s_mov_b32 m0, s51
	s_nop 0
	global_load_lds_dwordx4 v190, s[92:93]
	s_mov_b32 m0, s67
	s_nop 0
	global_load_lds_dwordx4 v132, s[92:93]
	s_waitcnt vmcnt(8)
	s_waitcnt lgkmcnt(0)
	s_barrier
; #define PG8_STAGE(bufoff, gbase, voff) do { _Pragma("unroll") for (int _i = 0; _i < 2; ++_i) \
;         __builtin_amdgcn_global_load_lds((const unsigned*)((const char*)(gbase) + (voff)[_i]), (PG8_LAS unsigned*)(lds + (bufoff) + ldsw + _i * 8192), 16, 0, 0); } while (0)
; #define PG8_LDA(dst, b, h) do { _Pragma("unroll") for (int m = 0; m < 4; ++m) _Pragma("unroll") for (int k = 0; k < 2; ++k) dst[m][k] = *(const PG8_LAS bf16x8*)(lds + PG8_SA(b, h) + aoff + m * 2048 + k * 1024); } while (0)
; #define PG8_LDB(dst, b, h) do { _Pragma("unroll") for (int n = 0; n < 2; ++n) _Pragma("unroll") for (int k = 0; k < 2; ++k) dst[n][k] = *(const PG8_LAS bf16x8*)(lds + PG8_SB(b, h) + boff + n * 2048 + k * 1024); } while (0)
; #define PG8_MMA(ai, bj, At, Bt) do { __builtin_amdgcn_s_setprio(1); _Pragma("unroll") for (int m = 0; m < 4; ++m) _Pragma("unroll") for (int n = 0; n < 2; ++n) _Pragma("unroll") for (int k = 0; k < 2; ++k) \
;         acc[ai][bj][m][n] = __builtin_amdgcn_mfma_f32_16x16x32_bf16(Bt[n][k], At[m][k], acc[ai][bj][m][n], 0, 0, 0); __builtin_amdgcn_s_setprio(0); } while (0)
; #define PG8_WAIT_V(n) asm volatile("s_waitcnt vmcnt(" #n ")" ::: "memory")
; #define PG8_WAIT_L(n) asm volatile("s_waitcnt lgkmcnt(" #n ")" ::: "memory")
; #define PG8_BAR __builtin_amdgcn_s_barrier()
; #define PG8_SCHED __builtin_amdgcn_sched_barrier(0)
; template <class Epi, class Sched, bool ALIGN_EPI = false, bool SP2 = false>
; __device__ __forceinline__ void gemm_phase(PG8_LAS unsigned char* lds, const Gemm g, const Sched& S, const Epi& E) {
;     ...
;             PG8_LDA(At, 0, 1); PG8_STAGE(PG8_SB(0, 0), b2, voffB); PG8_STAGE(PG8_SB(0, 1), b2 + hstepB, voffB); PG8_STAGE(PG8_SA(0, 0), a2, voffA);
;             PG8_WAIT_V(8); PG8_WAIT_L(0); PG8_BAR; PG8_MMA(1, 0, At, B0); PG8_MMA(1, 1, At, B1); PG8_BAR; PG8_SCHED;
;             PG8_LDB(B0, 1, 0); PG8_LDB(B1, 1, 1); PG8_SCHED; PG8_LDA(At, 1, 0); PG8_STAGE(PG8_SA(0, 1), a2 + hstep, voffA);
;             PG8_WAIT_V(8); PG8_WAIT_L(0); PG8_BAR; PG8_MMA(0, 0, At, B0); PG8_MMA(0, 1, At, B1); PG8_BAR; PG8_SCHED;
	v_mfma_f32_16x16x32_bf16 v[62:65], v[152:155], v[194:197], 0
	v_mfma_f32_16x16x32_bf16 v[54:57], v[152:155], v[210:213], 0
	v_mfma_f32_16x16x32_bf16 v[46:49], v[152:155], v[218:221], 0
	v_mfma_f32_16x16x32_bf16 v[38:41], v[152:155], v[240:243], 0
	v_mfma_f32_16x16x32_bf16 v[58:61], v[160:163], v[194:197], 0
	v_mfma_f32_16x16x32_bf16 v[50:53], v[160:163], v[210:213], 0
	v_mfma_f32_16x16x32_bf16 v[42:45], v[160:163], v[218:221], 0
	v_mfma_f32_16x16x32_bf16 v[34:37], v[160:163], v[240:243], 0
	v_mfma_f32_16x16x32_bf16 v[62:65], v[156:159], v[206:209], v[62:65]
	v_mfma_f32_16x16x32_bf16 v[54:57], v[156:159], v[214:217], v[54:57]
	v_mfma_f32_16x16x32_bf16 v[46:49], v[156:159], v[236:239], v[46:49]
	v_mfma_f32_16x16x32_bf16 v[38:41], v[156:159], v[244:247], v[38:41]
	v_mfma_f32_16x16x32_bf16 v[58:61], v[164:167], v[206:209], v[58:61]
	v_mfma_f32_16x16x32_bf16 v[50:53], v[164:167], v[214:217], v[50:53]
	v_mfma_f32_16x16x32_bf16 v[42:45], v[164:167], v[236:239], v[42:45]
	v_mfma_f32_16x16x32_bf16 v[34:37], v[164:167], v[244:247], v[34:37]
	v_mfma_f32_16x16x32_bf16 v[30:33], v[168:171], v[194:197], 0
	v_mfma_f32_16x16x32_bf16 v[22:25], v[168:171], v[210:213], 0
	v_mfma_f32_16x16x32_bf16 v[14:17], v[168:171], v[218:221], 0
	v_mfma_f32_16x16x32_bf16 v[6:9], v[168:171], v[240:243], 0
	v_mfma_f32_16x16x32_bf16 v[26:29], v[176:179], v[194:197], 0
	v_mfma_f32_16x16x32_bf16 v[18:21], v[176:179], v[210:213], 0
	v_mfma_f32_16x16x32_bf16 v[10:13], v[176:179], v[218:221], 0
	v_mfma_f32_16x16x32_bf16 v[2:5], v[176:179], v[240:243], 0
	v_mfma_f32_16x16x32_bf16 v[30:33], v[172:175], v[206:209], v[30:33]
	v_mfma_f32_16x16x32_bf16 v[22:25], v[172:175], v[214:217], v[22:25]
	v_mfma_f32_16x16x32_bf16 v[14:17], v[172:175], v[236:239], v[14:17]
	v_mfma_f32_16x16x32_bf16 v[6:9], v[172:175], v[244:247], v[6:9]
	v_mfma_f32_16x16x32_bf16 v[26:29], v[180:183], v[206:209], v[26:29]
	v_mfma_f32_16x16x32_bf16 v[18:21], v[180:183], v[214:217], v[18:21]
	v_mfma_f32_16x16x32_bf16 v[10:13], v[180:183], v[236:239], v[10:13]
	v_mfma_f32_16x16x32_bf16 v[2:5], v[180:183], v[244:247], v[2:5]
	s_barrier
	s_add_i32 s9, 0, 0x18000
	s_add_i32 s12, 0, 0x1c000
	ds_read_b128 v[152:155], v198
	ds_read_b128 v[156:159], v198 offset:1024
	ds_read_b128 v[160:163], v198 offset:2048
	ds_read_b128 v[164:167], v198 offset:3072
	ds_read_b128 v[168:171], v199
	ds_read_b128 v[172:175], v199 offset:1024
	ds_read_b128 v[176:179], v199 offset:2048
	ds_read_b128 v[180:183], v199 offset:3072
	s_add_u32 s10, s92, 0x80000
	s_addc_u32 s11, s93, 0
	s_mov_b32 m0, s74
	ds_read_b128 v[194:197], v151 offset:32768
	ds_read_b128 v[206:209], v151 offset:33792
	ds_read_b128 v[210:213], v151 offset:34816
	ds_read_b128 v[214:217], v151 offset:35840
	ds_read_b128 v[218:221], v151 offset:36864
	ds_read_b128 v[236:239], v151 offset:37888
	ds_read_b128 v[240:243], v151 offset:38912
	ds_read_b128 v[244:247], v151 offset:39936
	global_load_lds_dwordx4 v190, s[10:11]
	s_mov_b32 m0, s75
	s_nop 0
	global_load_lds_dwordx4 v132, s[10:11]
	s_waitcnt vmcnt(8)
	s_waitcnt lgkmcnt(0)
	s_barrier
	v_mfma_f32_16x16x32_bf16 v[126:129], v[152:155], v[194:197], v[126:129]
	v_mfma_f32_16x16x32_bf16 v[118:121], v[152:155], v[210:213], v[118:121]
	v_mfma_f32_16x16x32_bf16 v[110:113], v[152:155], v[218:221], v[110:113]
	v_mfma_f32_16x16x32_bf16 v[102:105], v[152:155], v[240:243], v[102:105]
	v_mfma_f32_16x16x32_bf16 v[122:125], v[160:163], v[194:197], v[122:125]
	v_mfma_f32_16x16x32_bf16 v[114:117], v[160:163], v[210:213], v[114:117]
	v_mfma_f32_16x16x32_bf16 v[106:109], v[160:163], v[218:221], v[106:109]
	v_mfma_f32_16x16x32_bf16 v[98:101], v[160:163], v[240:243], v[98:101]
	v_mfma_f32_16x16x32_bf16 v[126:129], v[156:159], v[206:209], v[126:129]
	v_mfma_f32_16x16x32_bf16 v[118:121], v[156:159], v[214:217], v[118:121]
	v_mfma_f32_16x16x32_bf16 v[110:113], v[156:159], v[236:239], v[110:113]
	v_mfma_f32_16x16x32_bf16 v[102:105], v[156:159], v[244:247], v[102:105]
	v_mfma_f32_16x16x32_bf16 v[122:125], v[164:167], v[206:209], v[122:125]
	v_mfma_f32_16x16x32_bf16 v[114:117], v[164:167], v[214:217], v[114:117]
	v_mfma_f32_16x16x32_bf16 v[106:109], v[164:167], v[236:239], v[106:109]
	v_mfma_f32_16x16x32_bf16 v[98:101], v[164:167], v[244:247], v[98:101]
	v_mfma_f32_16x16x32_bf16 v[94:97], v[168:171], v[194:197], v[94:97]
	v_mfma_f32_16x16x32_bf16 v[86:89], v[168:171], v[210:213], v[86:89]
	v_mfma_f32_16x16x32_bf16 v[78:81], v[168:171], v[218:221], v[78:81]
	v_mfma_f32_16x16x32_bf16 v[70:73], v[168:171], v[240:243], v[70:73]
	v_mfma_f32_16x16x32_bf16 v[90:93], v[176:179], v[194:197], v[90:93]
	v_mfma_f32_16x16x32_bf16 v[82:85], v[176:179], v[210:213], v[82:85]
	v_mfma_f32_16x16x32_bf16 v[74:77], v[176:179], v[218:221], v[74:77]
	v_mfma_f32_16x16x32_bf16 v[66:69], v[176:179], v[240:243], v[66:69]
	v_mfma_f32_16x16x32_bf16 v[94:97], v[172:175], v[206:209], v[94:97]
	v_mfma_f32_16x16x32_bf16 v[86:89], v[172:175], v[214:217], v[86:89]
	v_mfma_f32_16x16x32_bf16 v[78:81], v[172:175], v[236:239], v[78:81]
	v_mfma_f32_16x16x32_bf16 v[70:73], v[172:175], v[244:247], v[70:73]
	v_mfma_f32_16x16x32_bf16 v[90:93], v[180:183], v[206:209], v[90:93]
	v_mfma_f32_16x16x32_bf16 v[82:85], v[180:183], v[214:217], v[82:85]
	v_mfma_f32_16x16x32_bf16 v[74:77], v[180:183], v[236:239], v[74:77]
	v_mfma_f32_16x16x32_bf16 v[66:69], v[180:183], v[244:247], v[66:69]
	s_barrier
; #define PG8_STAGE(bufoff, gbase, voff) do { _Pragma("unroll") for (int _i = 0; _i < 2; ++_i) \
;         __builtin_amdgcn_global_load_lds((const unsigned*)((const char*)(gbase) + (voff)[_i]), (PG8_LAS unsigned*)(lds + (bufoff) + ldsw + _i * 8192), 16, 0, 0); } while (0)
; #define PG8_LDA(dst, b, h) do { _Pragma("unroll") for (int m = 0; m < 4; ++m) _Pragma("unroll") for (int k = 0; k < 2; ++k) dst[m][k] = *(const PG8_LAS bf16x8*)(lds + PG8_SA(b, h) + aoff + m * 2048 + k * 1024); } while (0)
; #define PG8_LDB(dst, b, h) do { _Pragma("unroll") for (int n = 0; n < 2; ++n) _Pragma("unroll") for (int k = 0; k < 2; ++k) dst[n][k] = *(const PG8_LAS bf16x8*)(lds + PG8_SB(b, h) + boff + n * 2048 + k * 1024); } while (0)
; #define PG8_MMA(ai, bj, At, Bt) do { __builtin_amdgcn_s_setprio(1); _Pragma("unroll") for (int m = 0; m < 4; ++m) _Pragma("unroll") for (int n = 0; n < 2; ++n) _Pragma("unroll") for (int k = 0; k < 2; ++k) \
;         acc[ai][bj][m][n] = __builtin_amdgcn_mfma_f32_16x16x32_bf16(Bt[n][k], At[m][k], acc[ai][bj][m][n], 0, 0, 0); __builtin_amdgcn_s_setprio(0); } while (0)
; #define PG8_WAIT_V(n) asm volatile("s_waitcnt vmcnt(" #n ")" ::: "memory")
; #define PG8_BAR __builtin_amdgcn_s_barrier()
; template <class Epi, class Sched, bool ALIGN_EPI = false, bool SP2 = false>
; __device__ __forceinline__ void gemm_phase(PG8_LAS unsigned char* lds, const Gemm g, const Sched& S, const Epi& E) {
;     ...
;         for (int t = 0; t < nt; t += 2) {
;             const bool last = (t == nt - 2);
;             const char* a1 = cA + (size_t)(t + 1) * kstep;
;             const char* a2 = last ? nA : cA + (size_t)(t + 2) * kstep; const char* b2 = last ? nB : cB + (size_t)(t + 2) * kstep;
;             const char* a3 = a2 + kstep; const char* b3 = b2 + kstep;
;             if (last && has_next) S.a_ready(nxt);
;             if constexpr (SP2) {
;             PG8_LDB(B0, 0, 0); PG8_LDB(B1, 0, 1); PG8_SCHED; PG8_LDA(At, 0, 0); PG8_STAGE(PG8_SA(1, 1), a1 + hstep, voffA);
;             PG8_WAIT_V(8); PG8_WAIT_L(0); PG8_BAR; PG8_MMA(0, 0, At, B0); PG8_MMA(0, 1, At, B1); PG8_BAR; PG8_SCHED;
;     ...
;             PG8_LDA(At, 1, 1); PG8_STAGE(PG8_SB(1, 0), b3, voffB); PG8_STAGE(PG8_SB(1, 1), b3 + hstepB, voffB); PG8_STAGE(PG8_SA(1, 0), a3, voffA);
;             PG8_WAIT_V(8); PG8_WAIT_L(0); PG8_BAR; PG8_MMA(1, 0, At, B0); PG8_MMA(1, 1, At, B1); PG8_BAR; PG8_SCHED;
	s_add_i32 s9, s9, s42
	s_mov_b32 m0, s9
	ds_read_b128 v[194:197], v151 offset:49152
	ds_read_b128 v[206:209], v151 offset:50176
	ds_read_b128 v[210:213], v151 offset:51200
	ds_read_b128 v[214:217], v151 offset:52224
	ds_read_b128 v[218:221], v151 offset:53248
	ds_read_b128 v[236:239], v151 offset:54272
	ds_read_b128 v[240:243], v151 offset:55296
	ds_read_b128 v[244:247], v151 offset:56320
	s_add_u32 s100, s84, s60
	s_addc_u32 s101, s85, s61
	global_load_lds_dwordx4 v130, s[100:101]
	s_add_i32 m0, s9, 0x2000
	s_add_u32 s10, s84, 0x20080
	s_addc_u32 s11, s85, 0
	s_add_i32 s9, s12, s42
	global_load_lds_dwordx4 v134, s[100:101]
	s_mov_b32 m0, s9
	s_nop 0
	global_load_lds_dwordx4 v130, s[10:11]
	s_add_i32 m0, s9, 0x2000
	s_nop 0
	global_load_lds_dwordx4 v134, s[10:11]
	s_mov_b32 m0, s82
	s_add_u32 s100, s92, s60
	s_addc_u32 s101, s93, s61
	global_load_lds_dwordx4 v190, s[100:101]
	s_mov_b32 m0, s86
	s_nop 0
	global_load_lds_dwordx4 v132, s[100:101]
	s_waitcnt vmcnt(8)
	s_waitcnt lgkmcnt(0)
	s_barrier
	v_mfma_f32_16x16x32_bf16 v[62:65], v[152:155], v[194:197], v[62:65]
	v_mfma_f32_16x16x32_bf16 v[54:57], v[152:155], v[210:213], v[54:57]
	v_mfma_f32_16x16x32_bf16 v[46:49], v[152:155], v[218:221], v[46:49]
	v_mfma_f32_16x16x32_bf16 v[38:41], v[152:155], v[240:243], v[38:41]
	v_mfma_f32_16x16x32_bf16 v[58:61], v[160:163], v[194:197], v[58:61]
	v_mfma_f32_16x16x32_bf16 v[50:53], v[160:163], v[210:213], v[50:53]
	v_mfma_f32_16x16x32_bf16 v[42:45], v[160:163], v[218:221], v[42:45]
	v_mfma_f32_16x16x32_bf16 v[34:37], v[160:163], v[240:243], v[34:37]
	v_mfma_f32_16x16x32_bf16 v[62:65], v[156:159], v[206:209], v[62:65]
	v_mfma_f32_16x16x32_bf16 v[54:57], v[156:159], v[214:217], v[54:57]
	v_mfma_f32_16x16x32_bf16 v[46:49], v[156:159], v[236:239], v[46:49]
	v_mfma_f32_16x16x32_bf16 v[38:41], v[156:159], v[244:247], v[38:41]
	v_mfma_f32_16x16x32_bf16 v[58:61], v[164:167], v[206:209], v[58:61]
	v_mfma_f32_16x16x32_bf16 v[50:53], v[164:167], v[214:217], v[50:53]
	v_mfma_f32_16x16x32_bf16 v[42:45], v[164:167], v[236:239], v[42:45]
	v_mfma_f32_16x16x32_bf16 v[34:37], v[164:167], v[244:247], v[34:37]
	v_mfma_f32_16x16x32_bf16 v[30:33], v[168:171], v[194:197], v[30:33]
	v_mfma_f32_16x16x32_bf16 v[22:25], v[168:171], v[210:213], v[22:25]
	v_mfma_f32_16x16x32_bf16 v[14:17], v[168:171], v[218:221], v[14:17]
	v_mfma_f32_16x16x32_bf16 v[6:9], v[168:171], v[240:243], v[6:9]
	v_mfma_f32_16x16x32_bf16 v[26:29], v[176:179], v[194:197], v[26:29]
	v_mfma_f32_16x16x32_bf16 v[18:21], v[176:179], v[210:213], v[18:21]
	v_mfma_f32_16x16x32_bf16 v[10:13], v[176:179], v[218:221], v[10:13]
	v_mfma_f32_16x16x32_bf16 v[2:5], v[176:179], v[240:243], v[2:5]
	v_mfma_f32_16x16x32_bf16 v[30:33], v[172:175], v[206:209], v[30:33]
	v_mfma_f32_16x16x32_bf16 v[22:25], v[172:175], v[214:217], v[22:25]
	v_mfma_f32_16x16x32_bf16 v[14:17], v[172:175], v[236:239], v[14:17]
	v_mfma_f32_16x16x32_bf16 v[6:9], v[172:175], v[244:247], v[6:9]
	v_mfma_f32_16x16x32_bf16 v[26:29], v[180:183], v[206:209], v[26:29]
	v_mfma_f32_16x16x32_bf16 v[18:21], v[180:183], v[214:217], v[18:21]
	v_mfma_f32_16x16x32_bf16 v[10:13], v[180:183], v[236:239], v[10:13]
	v_mfma_f32_16x16x32_bf16 v[2:5], v[180:183], v[244:247], v[2:5]
	s_barrier
	s_add_i32 s8, s8, 2
	s_add_u32 s80, s80, 0x100
	s_addc_u32 s81, s81, 0
	s_cmp_gt_u32 s8, 29
.LBB0_1233:
	s_add_u32 s9, s68, s80
	s_addc_u32 s10, s69, s81
	s_add_u32 s9, s9, 0x100
	s_addc_u32 s10, s10, 0
	s_add_u32 s100, s9, 0x7ff80
	s_addc_u32 s101, s10, 0
	s_add_u32 s11, s36, s80
	s_addc_u32 s12, s37, s81
	s_add_i32 s13, 0, 0x10000
	s_cmpk_eq_i32 s80, 0xf00
	s_cselect_b32 s93, s4, s10
	s_cselect_b32 s92, s5, s9
	s_cselect_b32 s85, s6, s12
	s_cselect_b32 s84, s7, s11
	s_add_i32 s9, 0, 0x14000
	ds_read_b128 v[152:155], v186
	ds_read_b128 v[156:159], v186 offset:1024
	ds_read_b128 v[160:163], v186 offset:2048
	ds_read_b128 v[164:167], v186 offset:3072
	ds_read_b128 v[168:171], v187
	ds_read_b128 v[172:175], v187 offset:1024
	ds_read_b128 v[176:179], v187 offset:2048
	ds_read_b128 v[180:183], v187 offset:3072
	s_add_i32 m0, s51, 0xc000
	ds_read_b128 v[206:209], v151
	ds_read_b128 v[210:213], v151 offset:1024
	ds_read_b128 v[214:217], v151 offset:2048
	ds_read_b128 v[218:221], v151 offset:3072
	ds_read_b128 v[236:239], v151 offset:4096
	ds_read_b128 v[240:243], v151 offset:5120
	ds_read_b128 v[244:247], v151 offset:6144
	ds_read_b128 v[194:197], v151 offset:7168
	global_load_lds_dwordx4 v136, s[100:101]
	s_add_i32 m0, s51, 0xe000
	s_nop 0
	global_load_lds_dwordx4 v138, s[100:101]
	s_waitcnt vmcnt(8)
	s_waitcnt lgkmcnt(0)
	s_barrier
; #define PG8_STAGE(bufoff, gbase, voff) do { _Pragma("unroll") for (int _i = 0; _i < 2; ++_i) \
;         __builtin_amdgcn_global_load_lds((const unsigned*)((const char*)(gbase) + (voff)[_i]), (PG8_LAS unsigned*)(lds + (bufoff) + ldsw + _i * 8192), 16, 0, 0); } while (0)
; #define PG8_LDA(dst, b, h) do { _Pragma("unroll") for (int m = 0; m < 4; ++m) _Pragma("unroll") for (int k = 0; k < 2; ++k) dst[m][k] = *(const PG8_LAS bf16x8*)(lds + PG8_SA(b, h) + aoff + m * 2048 + k * 1024); } while (0)
; #define PG8_LDB(dst, b, h) do { _Pragma("unroll") for (int n = 0; n < 2; ++n) _Pragma("unroll") for (int k = 0; k < 2; ++k) dst[n][k] = *(const PG8_LAS bf16x8*)(lds + PG8_SB(b, h) + boff + n * 2048 + k * 1024); } while (0)
; #define PG8_MMA(ai, bj, At, Bt) do { __builtin_amdgcn_s_setprio(1); _Pragma("unroll") for (int m = 0; m < 4; ++m) _Pragma("unroll") for (int n = 0; n < 2; ++n) _Pragma("unroll") for (int k = 0; k < 2; ++k) \
;         acc[ai][bj][m][n] = __builtin_amdgcn_mfma_f32_16x16x32_bf16(Bt[n][k], At[m][k], acc[ai][bj][m][n], 0, 0, 0); __builtin_amdgcn_s_setprio(0); } while (0)
; #define PG8_WAIT_V(n) asm volatile("s_waitcnt vmcnt(" #n ")" ::: "memory")
; #define PG8_WAIT_L(n) asm volatile("s_waitcnt lgkmcnt(" #n ")" ::: "memory")
; #define PG8_BAR __builtin_amdgcn_s_barrier()
; #define PG8_SCHED __builtin_amdgcn_sched_barrier(0)
; template <class Epi, class Sched, bool ALIGN_EPI = false, bool SP2 = false>
; __device__ __forceinline__ void gemm_phase(PG8_LAS unsigned char* lds, const Gemm g, const Sched& S, const Epi& E) {
;     ...
;             PG8_LDB(B0, 0, 0); PG8_LDB(B1, 0, 1); PG8_SCHED; PG8_LDA(At, 0, 0); PG8_STAGE(PG8_SA(1, 1), a1 + hstep, voffA);
;             PG8_WAIT_V(8); PG8_WAIT_L(0); PG8_BAR; PG8_MMA(0, 0, At, B0); PG8_MMA(0, 1, At, B1); PG8_BAR; PG8_SCHED;
;             PG8_LDA(At, 0, 1); PG8_STAGE(PG8_SB(0, 0), b2, voffB); PG8_STAGE(PG8_SB(0, 1), b2 + hstepB, voffB); PG8_STAGE(PG8_SA(0, 0), a2, voffA);
;             PG8_WAIT_V(8); PG8_WAIT_L(0); PG8_BAR; PG8_MMA(1, 0, At, B0); PG8_MMA(1, 1, At, B1); PG8_BAR; PG8_SCHED;
	v_mfma_f32_16x16x32_bf16 v[126:129], v[152:155], v[206:209], v[126:129]
	v_mfma_f32_16x16x32_bf16 v[118:121], v[152:155], v[214:217], v[118:121]
	v_mfma_f32_16x16x32_bf16 v[110:113], v[152:155], v[236:239], v[110:113]
	v_mfma_f32_16x16x32_bf16 v[102:105], v[152:155], v[244:247], v[102:105]
	v_mfma_f32_16x16x32_bf16 v[122:125], v[160:163], v[206:209], v[122:125]
	v_mfma_f32_16x16x32_bf16 v[114:117], v[160:163], v[214:217], v[114:117]
	v_mfma_f32_16x16x32_bf16 v[106:109], v[160:163], v[236:239], v[106:109]
	v_mfma_f32_16x16x32_bf16 v[98:101], v[160:163], v[244:247], v[98:101]
	v_mfma_f32_16x16x32_bf16 v[126:129], v[156:159], v[210:213], v[126:129]
	v_mfma_f32_16x16x32_bf16 v[118:121], v[156:159], v[218:221], v[118:121]
	v_mfma_f32_16x16x32_bf16 v[110:113], v[156:159], v[240:243], v[110:113]
	v_mfma_f32_16x16x32_bf16 v[102:105], v[156:159], v[194:197], v[102:105]
	v_mfma_f32_16x16x32_bf16 v[122:125], v[164:167], v[210:213], v[122:125]
	v_mfma_f32_16x16x32_bf16 v[114:117], v[164:167], v[218:221], v[114:117]
	v_mfma_f32_16x16x32_bf16 v[106:109], v[164:167], v[240:243], v[106:109]
	v_mfma_f32_16x16x32_bf16 v[98:101], v[164:167], v[194:197], v[98:101]
	v_mfma_f32_16x16x32_bf16 v[94:97], v[168:171], v[206:209], v[94:97]
	v_mfma_f32_16x16x32_bf16 v[86:89], v[168:171], v[214:217], v[86:89]
	v_mfma_f32_16x16x32_bf16 v[78:81], v[168:171], v[236:239], v[78:81]
	v_mfma_f32_16x16x32_bf16 v[70:73], v[168:171], v[244:247], v[70:73]
	v_mfma_f32_16x16x32_bf16 v[90:93], v[176:179], v[206:209], v[90:93]
	v_mfma_f32_16x16x32_bf16 v[82:85], v[176:179], v[214:217], v[82:85]
	v_mfma_f32_16x16x32_bf16 v[74:77], v[176:179], v[236:239], v[74:77]
	v_mfma_f32_16x16x32_bf16 v[66:69], v[176:179], v[244:247], v[66:69]
	v_mfma_f32_16x16x32_bf16 v[94:97], v[172:175], v[210:213], v[94:97]
	v_mfma_f32_16x16x32_bf16 v[86:89], v[172:175], v[218:221], v[86:89]
	v_mfma_f32_16x16x32_bf16 v[78:81], v[172:175], v[240:243], v[78:81]
	v_mfma_f32_16x16x32_bf16 v[70:73], v[172:175], v[194:197], v[70:73]
	v_mfma_f32_16x16x32_bf16 v[90:93], v[180:183], v[210:213], v[90:93]
	v_mfma_f32_16x16x32_bf16 v[82:85], v[180:183], v[218:221], v[82:85]
	v_mfma_f32_16x16x32_bf16 v[74:77], v[180:183], v[240:243], v[74:77]
	v_mfma_f32_16x16x32_bf16 v[66:69], v[180:183], v[194:197], v[66:69]
	s_barrier
	s_add_i32 s10, s13, s42
	s_mov_b32 m0, s10
	ds_read_b128 v[194:197], v151 offset:16384
	ds_read_b128 v[206:209], v151 offset:17408
	ds_read_b128 v[210:213], v151 offset:18432
	ds_read_b128 v[214:217], v151 offset:19456
	ds_read_b128 v[218:221], v151 offset:20480
	ds_read_b128 v[236:239], v151 offset:21504
	ds_read_b128 v[240:243], v151 offset:22528
	ds_read_b128 v[244:247], v151 offset:23552
	global_load_lds_dwordx4 v130, s[84:85]
	s_add_i32 m0, s10, 0x2000
	s_add_u32 s10, s84, 0x20000
	s_addc_u32 s11, s85, 0
	s_add_i32 s9, s9, s42
	global_load_lds_dwordx4 v134, s[84:85]
	s_mov_b32 m0, s9
	s_nop 0
	global_load_lds_dwordx4 v130, s[10:11]
	s_add_i32 m0, s9, 0x2000
	s_nop 0
	global_load_lds_dwordx4 v134, s[10:11]
	s_mov_b32 m0, s51
	s_nop 0
	global_load_lds_dwordx4 v190, s[92:93]
	s_mov_b32 m0, s67
	s_nop 0
	global_load_lds_dwordx4 v132, s[92:93]
	s_waitcnt vmcnt(8)
	s_waitcnt lgkmcnt(0)
	s_barrier
	v_mfma_f32_16x16x32_bf16 v[62:65], v[152:155], v[194:197], v[62:65]
	v_mfma_f32_16x16x32_bf16 v[54:57], v[152:155], v[210:213], v[54:57]
	v_mfma_f32_16x16x32_bf16 v[46:49], v[152:155], v[218:221], v[46:49]
	v_mfma_f32_16x16x32_bf16 v[38:41], v[152:155], v[240:243], v[38:41]
	v_mfma_f32_16x16x32_bf16 v[58:61], v[160:163], v[194:197], v[58:61]
	v_mfma_f32_16x16x32_bf16 v[50:53], v[160:163], v[210:213], v[50:53]
	v_mfma_f32_16x16x32_bf16 v[42:45], v[160:163], v[218:221], v[42:45]
	v_mfma_f32_16x16x32_bf16 v[34:37], v[160:163], v[240:243], v[34:37]
	v_mfma_f32_16x16x32_bf16 v[62:65], v[156:159], v[206:209], v[62:65]
	v_mfma_f32_16x16x32_bf16 v[54:57], v[156:159], v[214:217], v[54:57]
	v_mfma_f32_16x16x32_bf16 v[46:49], v[156:159], v[236:239], v[46:49]
	v_mfma_f32_16x16x32_bf16 v[38:41], v[156:159], v[244:247], v[38:41]
	v_mfma_f32_16x16x32_bf16 v[58:61], v[164:167], v[206:209], v[58:61]
	v_mfma_f32_16x16x32_bf16 v[50:53], v[164:167], v[214:217], v[50:53]
	v_mfma_f32_16x16x32_bf16 v[42:45], v[164:167], v[236:239], v[42:45]
	v_mfma_f32_16x16x32_bf16 v[34:37], v[164:167], v[244:247], v[34:37]
	v_mfma_f32_16x16x32_bf16 v[30:33], v[168:171], v[194:197], v[30:33]
	v_mfma_f32_16x16x32_bf16 v[22:25], v[168:171], v[210:213], v[22:25]
	v_mfma_f32_16x16x32_bf16 v[14:17], v[168:171], v[218:221], v[14:17]
	v_mfma_f32_16x16x32_bf16 v[6:9], v[168:171], v[240:243], v[6:9]
	v_mfma_f32_16x16x32_bf16 v[26:29], v[176:179], v[194:197], v[26:29]
	v_mfma_f32_16x16x32_bf16 v[18:21], v[176:179], v[210:213], v[18:21]
	v_mfma_f32_16x16x32_bf16 v[10:13], v[176:179], v[218:221], v[10:13]
	v_mfma_f32_16x16x32_bf16 v[2:5], v[176:179], v[240:243], v[2:5]
	v_mfma_f32_16x16x32_bf16 v[30:33], v[172:175], v[206:209], v[30:33]
	v_mfma_f32_16x16x32_bf16 v[22:25], v[172:175], v[214:217], v[22:25]
	v_mfma_f32_16x16x32_bf16 v[14:17], v[172:175], v[236:239], v[14:17]
	v_mfma_f32_16x16x32_bf16 v[6:9], v[172:175], v[244:247], v[6:9]
	v_mfma_f32_16x16x32_bf16 v[26:29], v[180:183], v[206:209], v[26:29]
	v_mfma_f32_16x16x32_bf16 v[18:21], v[180:183], v[214:217], v[18:21]
	v_mfma_f32_16x16x32_bf16 v[10:13], v[180:183], v[236:239], v[10:13]
	v_mfma_f32_16x16x32_bf16 v[2:5], v[180:183], v[244:247], v[2:5]
	s_barrier
; #define PG8_STAGE(bufoff, gbase, voff) do { _Pragma("unroll") for (int _i = 0; _i < 2; ++_i) \
;         __builtin_amdgcn_global_load_lds((const unsigned*)((const char*)(gbase) + (voff)[_i]), (PG8_LAS unsigned*)(lds + (bufoff) + ldsw + _i * 8192), 16, 0, 0); } while (0)
; #define PG8_LDA(dst, b, h) do { _Pragma("unroll") for (int m = 0; m < 4; ++m) _Pragma("unroll") for (int k = 0; k < 2; ++k) dst[m][k] = *(const PG8_LAS bf16x8*)(lds + PG8_SA(b, h) + aoff + m * 2048 + k * 1024); } while (0)
; #define PG8_LDB(dst, b, h) do { _Pragma("unroll") for (int n = 0; n < 2; ++n) _Pragma("unroll") for (int k = 0; k < 2; ++k) dst[n][k] = *(const PG8_LAS bf16x8*)(lds + PG8_SB(b, h) + boff + n * 2048 + k * 1024); } while (0)
; #define PG8_MMA(ai, bj, At, Bt) do { __builtin_amdgcn_s_setprio(1); _Pragma("unroll") for (int m = 0; m < 4; ++m) _Pragma("unroll") for (int n = 0; n < 2; ++n) _Pragma("unroll") for (int k = 0; k < 2; ++k) \
;         acc[ai][bj][m][n] = __builtin_amdgcn_mfma_f32_16x16x32_bf16(Bt[n][k], At[m][k], acc[ai][bj][m][n], 0, 0, 0); __builtin_amdgcn_s_setprio(0); } while (0)
; #define PG8_WAIT_V(n) asm volatile("s_waitcnt vmcnt(" #n ")" ::: "memory")
; #define PG8_WAIT_L(n) asm volatile("s_waitcnt lgkmcnt(" #n ")" ::: "memory")
; #define PG8_BAR __builtin_amdgcn_s_barrier()
; #define PG8_SCHED __builtin_amdgcn_sched_barrier(0)
; template <class Epi, class Sched, bool ALIGN_EPI = false, bool SP2 = false>
; __device__ __forceinline__ void gemm_phase(PG8_LAS unsigned char* lds, const Gemm g, const Sched& S, const Epi& E) {
;     ...
;             PG8_LDB(B0, 1, 0); PG8_LDB(B1, 1, 1); PG8_SCHED; PG8_LDA(At, 1, 0); PG8_STAGE(PG8_SA(0, 1), a2 + hstep, voffA);
;             PG8_WAIT_V(8); PG8_WAIT_L(0); PG8_BAR; PG8_MMA(0, 0, At, B0); PG8_MMA(0, 1, At, B1); PG8_BAR; PG8_SCHED;
;             PG8_LDA(At, 1, 1); PG8_STAGE(PG8_SB(1, 0), b3, voffB); PG8_STAGE(PG8_SB(1, 1), b3 + hstepB, voffB); PG8_STAGE(PG8_SA(1, 0), a3, voffA);
;             PG8_WAIT_V(8); PG8_WAIT_L(0); PG8_BAR; PG8_MMA(1, 0, At, B0); PG8_MMA(1, 1, At, B1); PG8_BAR; PG8_SCHED;
;     ...
;         if constexpr (ALIGN_EPI) { if (wr == 0) PG8_BAR; }
;         if constexpr (!Epi::AFTER_DRAIN) { E(acc, cur, wr, wc, fr, fq, ui); S.done(cur); }
;         if (!has_next) break;
	s_add_i32 s9, 0, 0x18000
	s_add_i32 s12, 0, 0x1c000
	ds_read_b128 v[152:155], v198
	ds_read_b128 v[156:159], v198 offset:1024
	ds_read_b128 v[160:163], v198 offset:2048
	ds_read_b128 v[164:167], v198 offset:3072
	ds_read_b128 v[168:171], v199
	ds_read_b128 v[172:175], v199 offset:1024
	ds_read_b128 v[176:179], v199 offset:2048
	ds_read_b128 v[180:183], v199 offset:3072
	s_add_u32 s10, s92, 0x80000
	s_addc_u32 s11, s93, 0
	s_mov_b32 m0, s74
	ds_read_b128 v[194:197], v151 offset:32768
	ds_read_b128 v[206:209], v151 offset:33792
	ds_read_b128 v[210:213], v151 offset:34816
	ds_read_b128 v[214:217], v151 offset:35840
	ds_read_b128 v[218:221], v151 offset:36864
	ds_read_b128 v[236:239], v151 offset:37888
	ds_read_b128 v[240:243], v151 offset:38912
	ds_read_b128 v[244:247], v151 offset:39936
	global_load_lds_dwordx4 v190, s[10:11]
	s_mov_b32 m0, s75
	s_nop 0
	global_load_lds_dwordx4 v132, s[10:11]
	s_waitcnt vmcnt(8)
	s_waitcnt lgkmcnt(0)
	s_barrier
	v_mfma_f32_16x16x32_bf16 v[126:129], v[152:155], v[194:197], v[126:129]
	v_mfma_f32_16x16x32_bf16 v[118:121], v[152:155], v[210:213], v[118:121]
	v_mfma_f32_16x16x32_bf16 v[110:113], v[152:155], v[218:221], v[110:113]
	v_mfma_f32_16x16x32_bf16 v[102:105], v[152:155], v[240:243], v[102:105]
	v_mfma_f32_16x16x32_bf16 v[122:125], v[160:163], v[194:197], v[122:125]
	v_mfma_f32_16x16x32_bf16 v[114:117], v[160:163], v[210:213], v[114:117]
	v_mfma_f32_16x16x32_bf16 v[106:109], v[160:163], v[218:221], v[106:109]
	v_mfma_f32_16x16x32_bf16 v[98:101], v[160:163], v[240:243], v[98:101]
	v_mfma_f32_16x16x32_bf16 v[126:129], v[156:159], v[206:209], v[126:129]
	v_mfma_f32_16x16x32_bf16 v[118:121], v[156:159], v[214:217], v[118:121]
	v_mfma_f32_16x16x32_bf16 v[110:113], v[156:159], v[236:239], v[110:113]
	v_mfma_f32_16x16x32_bf16 v[102:105], v[156:159], v[244:247], v[102:105]
	v_mfma_f32_16x16x32_bf16 v[122:125], v[164:167], v[206:209], v[122:125]
	v_mfma_f32_16x16x32_bf16 v[114:117], v[164:167], v[214:217], v[114:117]
	v_mfma_f32_16x16x32_bf16 v[106:109], v[164:167], v[236:239], v[106:109]
	v_mfma_f32_16x16x32_bf16 v[98:101], v[164:167], v[244:247], v[98:101]
	v_mfma_f32_16x16x32_bf16 v[94:97], v[168:171], v[194:197], v[94:97]
	v_mfma_f32_16x16x32_bf16 v[86:89], v[168:171], v[210:213], v[86:89]
	v_mfma_f32_16x16x32_bf16 v[78:81], v[168:171], v[218:221], v[78:81]
	v_mfma_f32_16x16x32_bf16 v[70:73], v[168:171], v[240:243], v[70:73]
	v_mfma_f32_16x16x32_bf16 v[90:93], v[176:179], v[194:197], v[90:93]
	v_mfma_f32_16x16x32_bf16 v[82:85], v[176:179], v[210:213], v[82:85]
	v_mfma_f32_16x16x32_bf16 v[74:77], v[176:179], v[218:221], v[74:77]
	v_mfma_f32_16x16x32_bf16 v[66:69], v[176:179], v[240:243], v[66:69]
	v_mfma_f32_16x16x32_bf16 v[94:97], v[172:175], v[206:209], v[94:97]
	v_mfma_f32_16x16x32_bf16 v[86:89], v[172:175], v[214:217], v[86:89]
	v_mfma_f32_16x16x32_bf16 v[78:81], v[172:175], v[236:239], v[78:81]
	v_mfma_f32_16x16x32_bf16 v[70:73], v[172:175], v[244:247], v[70:73]
	v_mfma_f32_16x16x32_bf16 v[90:93], v[180:183], v[206:209], v[90:93]
	v_mfma_f32_16x16x32_bf16 v[82:85], v[180:183], v[214:217], v[82:85]
	v_mfma_f32_16x16x32_bf16 v[74:77], v[180:183], v[236:239], v[74:77]
	v_mfma_f32_16x16x32_bf16 v[66:69], v[180:183], v[244:247], v[66:69]
	s_barrier
	s_add_i32 s9, s9, s42
	s_mov_b32 m0, s9
	ds_read_b128 v[194:197], v151 offset:49152
	ds_read_b128 v[206:209], v151 offset:50176
	ds_read_b128 v[210:213], v151 offset:51200
	ds_read_b128 v[214:217], v151 offset:52224
	ds_read_b128 v[218:221], v151 offset:53248
	ds_read_b128 v[236:239], v151 offset:54272
	ds_read_b128 v[240:243], v151 offset:55296
	ds_read_b128 v[244:247], v151 offset:56320
	s_add_u32 s100, s84, s60
	s_addc_u32 s101, s85, s61
	global_load_lds_dwordx4 v130, s[100:101]
	s_add_i32 m0, s9, 0x2000
	s_add_u32 s10, s84, 0x20080
	s_addc_u32 s11, s85, 0
	s_add_i32 s9, s12, s42
	global_load_lds_dwordx4 v134, s[100:101]
	s_mov_b32 m0, s9
	s_nop 0
	global_load_lds_dwordx4 v130, s[10:11]
	s_add_i32 m0, s9, 0x2000
	s_nop 0
	global_load_lds_dwordx4 v134, s[10:11]
	s_mov_b32 m0, s82
	s_add_u32 s100, s92, s60
	s_addc_u32 s101, s93, s61
	global_load_lds_dwordx4 v190, s[100:101]
	s_mov_b32 m0, s86
	s_nop 0
	global_load_lds_dwordx4 v132, s[100:101]
	s_waitcnt vmcnt(8)
	s_waitcnt lgkmcnt(0)
	s_barrier
	v_mfma_f32_16x16x32_bf16 v[62:65], v[152:155], v[194:197], v[62:65]
	v_mfma_f32_16x16x32_bf16 v[54:57], v[152:155], v[210:213], v[54:57]
	v_mfma_f32_16x16x32_bf16 v[46:49], v[152:155], v[218:221], v[46:49]
	v_mfma_f32_16x16x32_bf16 v[38:41], v[152:155], v[240:243], v[38:41]
	v_mfma_f32_16x16x32_bf16 v[58:61], v[160:163], v[194:197], v[58:61]
	v_mfma_f32_16x16x32_bf16 v[50:53], v[160:163], v[210:213], v[50:53]
	v_mfma_f32_16x16x32_bf16 v[42:45], v[160:163], v[218:221], v[42:45]
	v_mfma_f32_16x16x32_bf16 v[34:37], v[160:163], v[240:243], v[34:37]
	v_mfma_f32_16x16x32_bf16 v[62:65], v[156:159], v[206:209], v[62:65]
	v_mfma_f32_16x16x32_bf16 v[54:57], v[156:159], v[214:217], v[54:57]
	v_mfma_f32_16x16x32_bf16 v[46:49], v[156:159], v[236:239], v[46:49]
	v_mfma_f32_16x16x32_bf16 v[38:41], v[156:159], v[244:247], v[38:41]
	v_mfma_f32_16x16x32_bf16 v[58:61], v[164:167], v[206:209], v[58:61]
	v_mfma_f32_16x16x32_bf16 v[50:53], v[164:167], v[214:217], v[50:53]
	v_mfma_f32_16x16x32_bf16 v[42:45], v[164:167], v[236:239], v[42:45]
	v_mfma_f32_16x16x32_bf16 v[34:37], v[164:167], v[244:247], v[34:37]
	v_mfma_f32_16x16x32_bf16 v[30:33], v[168:171], v[194:197], v[30:33]
	v_mfma_f32_16x16x32_bf16 v[22:25], v[168:171], v[210:213], v[22:25]
	v_mfma_f32_16x16x32_bf16 v[14:17], v[168:171], v[218:221], v[14:17]
	v_mfma_f32_16x16x32_bf16 v[6:9], v[168:171], v[240:243], v[6:9]
	v_mfma_f32_16x16x32_bf16 v[26:29], v[176:179], v[194:197], v[26:29]
	v_mfma_f32_16x16x32_bf16 v[18:21], v[176:179], v[210:213], v[18:21]
	v_mfma_f32_16x16x32_bf16 v[10:13], v[176:179], v[218:221], v[10:13]
	v_mfma_f32_16x16x32_bf16 v[2:5], v[176:179], v[240:243], v[2:5]
	v_mfma_f32_16x16x32_bf16 v[30:33], v[172:175], v[206:209], v[30:33]
	v_mfma_f32_16x16x32_bf16 v[22:25], v[172:175], v[214:217], v[22:25]
	v_mfma_f32_16x16x32_bf16 v[14:17], v[172:175], v[236:239], v[14:17]
	v_mfma_f32_16x16x32_bf16 v[6:9], v[172:175], v[244:247], v[6:9]
	v_mfma_f32_16x16x32_bf16 v[26:29], v[180:183], v[206:209], v[26:29]
	v_mfma_f32_16x16x32_bf16 v[18:21], v[180:183], v[214:217], v[18:21]
	v_mfma_f32_16x16x32_bf16 v[10:13], v[180:183], v[236:239], v[10:13]
	v_mfma_f32_16x16x32_bf16 v[2:5], v[180:183], v[244:247], v[2:5]
	s_barrier
	s_add_i32 s8, s8, 2
	s_add_u32 s80, s80, 0x100
	s_addc_u32 s81, s81, 0
	s_cmp_gt_u32 s8, 29
	s_cbranch_scc0 .LBB0_1233
	s_and_b64 vcc, exec, s[62:63]
	s_cbranch_vccz .LBB0_1236
	s_barrier
